# v26 + GEMM k-loops: duplicate lgkmcnt(0) before each MFMA segment dropped; scalar/address instructions between the last MFMA and the closing barrier moved into the neighbouring load segment
# baseline (speedup 1.0000x reference)
.LBB0_211:
	s_add_i32 s60, s60, 1
	s_mov_b64 s[36:37], s[18:19]
	s_mul_i32 s18, s60, s26
	s_add_i32 s38, s18, s2
	s_cmpk_gt_i32 s38, 0x1ff
	s_cselect_b64 s[44:45], -1, 0
	s_lshl_b32 s18, s38, 3
	s_and_b32 s18, s18, 56
	s_bfe_u32 s19, s38, 0x30003
	s_mov_b32 s27, s61
	s_or_b32 s61, s18, s19
	s_mov_b32 s3, s42
	s_ashr_i32 s42, s38, 6
	s_lshl_b32 s18, s61, 19
	s_mov_b64 s[4:5], s[20:21]
	s_add_u32 s20, s14, s18
	s_addc_u32 s21, s15, 0
	s_ashr_i32 s43, s42, 31
	s_lshl_b64 s[18:19], s[42:43], 19
	s_add_u32 s18, s16, s18
	s_addc_u32 s19, s17, s19
	s_cmpk_lt_i32 s38, 0x200
	s_cselect_b32 s38, s21, s5
	s_cselect_b32 s43, s20, s4
	s_cselect_b32 s62, s19, s37
	s_cselect_b32 s63, s18, s36
	s_add_u32 s64, s36, 0x100
	s_addc_u32 s65, s37, 0
	s_mov_b32 s66, -2
	s_waitcnt lgkmcnt(0)
	s_add_u32 s36, s4, 0x100
	s_addc_u32 s37, s5, 0
	s_add_i32 s67, 0, 0x10000
	v_add_u32_e32 v1, s67, v191
	ds_read_b128 v[34:37], v1
	ds_read_b128 v[38:41], v1 offset:1024
	ds_read_b128 v[42:45], v1 offset:2048
	ds_read_b128 v[46:49], v1 offset:3072
	s_cmp_eq_u32 s66, 12
	s_cselect_b32 s49, s38, s37
	s_cselect_b32 s48, s43, s36
	s_cselect_b32 s47, s62, s65
	s_cselect_b32 s46, s63, s64
	v_lshl_add_u64 v[186:187], s[4:5], 0, v[168:169]
	s_add_i32 m0, s53, 0xc000
	ds_read_b128 v[50:53], v206
	ds_read_b128 v[58:61], v206 offset:1024
	ds_read_b128 v[62:65], v206 offset:2048
	ds_read_b128 v[66:69], v206 offset:3072
	ds_read_b128 v[170:173], v206 offset:4096
	ds_read_b128 v[174:177], v206 offset:5120
	ds_read_b128 v[178:181], v206 offset:6144
	ds_read_b128 v[182:185], v206 offset:7168
	global_load_lds_dwordx4 v[186:187], off
	v_lshl_add_u64 v[186:187], s[4:5], 0, v[166:167]
	s_add_i32 m0, s53, 0xe000
	s_nop 0
	global_load_lds_dwordx4 v[186:187], off
	s_waitcnt lgkmcnt(8)
	s_barrier
	s_waitcnt lgkmcnt(0)
	v_mfma_f32_16x16x32_bf16 v[158:161], v[34:37], v[50:53], 0
	v_mfma_f32_16x16x32_bf16 v[154:157], v[42:45], v[50:53], 0
	v_mfma_f32_16x16x32_bf16 v[142:145], v[34:37], v[62:65], 0
	v_mfma_f32_16x16x32_bf16 v[138:141], v[42:45], v[62:65], 0
	v_mfma_f32_16x16x32_bf16 v[126:129], v[34:37], v[170:173], 0
	v_mfma_f32_16x16x32_bf16 v[122:125], v[42:45], v[170:173], 0
	v_mfma_f32_16x16x32_bf16 v[110:113], v[34:37], v[178:181], 0
	v_mfma_f32_16x16x32_bf16 v[106:109], v[42:45], v[178:181], 0
	v_mfma_f32_16x16x32_bf16 v[158:161], v[38:41], v[58:61], v[158:161]
	v_mfma_f32_16x16x32_bf16 v[154:157], v[46:49], v[58:61], v[154:157]
	v_mfma_f32_16x16x32_bf16 v[142:145], v[38:41], v[66:69], v[142:145]
	v_mfma_f32_16x16x32_bf16 v[138:141], v[46:49], v[66:69], v[138:141]
	v_mfma_f32_16x16x32_bf16 v[126:129], v[38:41], v[174:177], v[126:129]
	v_mfma_f32_16x16x32_bf16 v[122:125], v[46:49], v[174:177], v[122:125]
	v_mfma_f32_16x16x32_bf16 v[110:113], v[38:41], v[182:185], v[110:113]
	v_mfma_f32_16x16x32_bf16 v[106:109], v[46:49], v[182:185], v[106:109]
	s_barrier
	v_mbcnt_lo_u32_b32 v250, -1, 0
	v_mbcnt_hi_u32_b32 v250, -1, v250
	v_lshlrev_b32_e32 v250, 4, v250
	s_lshl_b32 s32, s3, 10
	s_add_u32 s90, s8, s32
	s_addc_u32 s91, s9, 0
	s_add_u32 s92, s10, s32
	s_addc_u32 s93, s11, 0
	s_mov_b32 m0, 0x20840
	s_nop 0
	global_load_lds_dwordx4 v250, s[90:91]
	s_mov_b32 m0, 0x20c40
	s_nop 0
	global_load_lds_dwordx4 v250, s[92:93]
	s_add_i32 s68, 0, 0x14000
	s_add_i32 s4, s67, s52
	v_add_u32_e32 v1, s68, v191
	v_lshl_add_u64 v[214:215], s[46:47], 0, v[164:165]
	s_mov_b32 m0, s4
	ds_read_b128 v[186:189], v1
	ds_read_b128 v[208:211], v1 offset:1024
	ds_read_b128 v[222:225], v1 offset:2048
	ds_read_b128 v[226:229], v1 offset:3072
	global_load_lds_dwordx4 v[214:215], off
	v_lshl_add_u64 v[238:239], s[46:47], 0, v[162:163]
	s_add_i32 m0, s4, 0x2000
	s_nop 0
	global_load_lds_dwordx4 v[238:239], off
	s_barrier
	s_waitcnt lgkmcnt(0)
	v_mfma_f32_16x16x32_bf16 v[150:153], v[186:189], v[50:53], 0
	v_mfma_f32_16x16x32_bf16 v[50:53], v[222:225], v[50:53], 0
	v_mfma_f32_16x16x32_bf16 v[150:153], v[208:211], v[58:61], v[150:153]
	v_mfma_f32_16x16x32_bf16 v[50:53], v[226:229], v[58:61], v[50:53]
	v_mfma_f32_16x16x32_bf16 v[58:61], v[186:189], v[62:65], 0
	v_mfma_f32_16x16x32_bf16 v[62:65], v[222:225], v[62:65], 0
	v_mfma_f32_16x16x32_bf16 v[114:117], v[222:225], v[170:173], 0
	v_mfma_f32_16x16x32_bf16 v[102:105], v[186:189], v[178:181], 0
	v_mfma_f32_16x16x32_bf16 v[98:101], v[222:225], v[178:181], 0
	v_mfma_f32_16x16x32_bf16 v[58:61], v[208:211], v[66:69], v[58:61]
	v_mfma_f32_16x16x32_bf16 v[62:65], v[226:229], v[66:69], v[62:65]
	v_mfma_f32_16x16x32_bf16 v[66:69], v[186:189], v[170:173], 0
	v_mfma_f32_16x16x32_bf16 v[114:117], v[226:229], v[174:177], v[114:117]
	v_mfma_f32_16x16x32_bf16 v[102:105], v[208:211], v[182:185], v[102:105]
	v_mfma_f32_16x16x32_bf16 v[98:101], v[226:229], v[182:185], v[98:101]
	v_mfma_f32_16x16x32_bf16 v[66:69], v[208:211], v[174:177], v[66:69]
	s_barrier
	s_mov_b32 m0, s53
	v_lshl_add_u64 v[240:241], s[48:49], 0, v[164:165]
	ds_read_b128 v[118:121], v206 offset:16384
	ds_read_b128 v[130:133], v206 offset:17408
	ds_read_b128 v[134:137], v206 offset:18432
	ds_read_b128 v[146:149], v206 offset:19456
	ds_read_b128 v[170:173], v206 offset:20480
	ds_read_b128 v[174:177], v206 offset:21504
	ds_read_b128 v[178:181], v206 offset:22528
	ds_read_b128 v[182:185], v206 offset:23552
	global_load_lds_dwordx4 v[240:241], off
	v_lshl_add_u64 v[242:243], s[48:49], 0, v[162:163]
	s_mov_b32 m0, s54
	s_nop 0
	global_load_lds_dwordx4 v[242:243], off
	s_barrier
	s_waitcnt lgkmcnt(0)
	v_mfma_f32_16x16x32_bf16 v[94:97], v[34:37], v[118:121], 0
	v_mfma_f32_16x16x32_bf16 v[90:93], v[42:45], v[118:121], 0
	v_mfma_f32_16x16x32_bf16 v[78:81], v[34:37], v[134:137], 0
	v_mfma_f32_16x16x32_bf16 v[74:77], v[42:45], v[134:137], 0
	v_mfma_f32_16x16x32_bf16 v[30:33], v[34:37], v[170:173], 0
	v_mfma_f32_16x16x32_bf16 v[26:29], v[42:45], v[170:173], 0
	v_mfma_f32_16x16x32_bf16 v[14:17], v[34:37], v[178:181], 0
	v_mfma_f32_16x16x32_bf16 v[10:13], v[42:45], v[178:181], 0
	v_mfma_f32_16x16x32_bf16 v[94:97], v[38:41], v[130:133], v[94:97]
	v_mfma_f32_16x16x32_bf16 v[90:93], v[46:49], v[130:133], v[90:93]
	v_mfma_f32_16x16x32_bf16 v[78:81], v[38:41], v[146:149], v[78:81]
	v_mfma_f32_16x16x32_bf16 v[74:77], v[46:49], v[146:149], v[74:77]
	v_mfma_f32_16x16x32_bf16 v[30:33], v[38:41], v[174:177], v[30:33]
	v_mfma_f32_16x16x32_bf16 v[26:29], v[46:49], v[174:177], v[26:29]
	v_mfma_f32_16x16x32_bf16 v[14:17], v[38:41], v[182:185], v[14:17]
	v_mfma_f32_16x16x32_bf16 v[10:13], v[46:49], v[182:185], v[10:13]
	s_barrier
	s_add_u32 s4, s46, 0x40000
	s_addc_u32 s5, s47, 0
	s_add_i32 s67, s68, s52
	v_lshl_add_u64 v[34:35], s[4:5], 0, v[164:165]
	s_mov_b32 m0, s67
	s_nop 0
	global_load_lds_dwordx4 v[34:35], off
	v_lshl_add_u64 v[34:35], s[4:5], 0, v[162:163]
	s_add_i32 m0, s67, 0x2000
	s_nop 0
	global_load_lds_dwordx4 v[34:35], off
	s_waitcnt vmcnt(6)
	s_barrier
	v_mfma_f32_16x16x32_bf16 v[22:25], v[186:189], v[170:173], 0
	v_mfma_f32_16x16x32_bf16 v[18:21], v[222:225], v[170:173], 0
	v_mfma_f32_16x16x32_bf16 v[6:9], v[186:189], v[178:181], 0
	v_mfma_f32_16x16x32_bf16 v[2:5], v[222:225], v[178:181], 0
	v_mfma_f32_16x16x32_bf16 v[34:37], v[186:189], v[118:121], 0
	v_mfma_f32_16x16x32_bf16 v[38:41], v[222:225], v[118:121], 0
	v_mfma_f32_16x16x32_bf16 v[42:45], v[186:189], v[134:137], 0
	v_mfma_f32_16x16x32_bf16 v[46:49], v[222:225], v[134:137], 0
	v_mfma_f32_16x16x32_bf16 v[22:25], v[208:211], v[174:177], v[22:25]
	v_mfma_f32_16x16x32_bf16 v[18:21], v[226:229], v[174:177], v[18:21]
	v_mfma_f32_16x16x32_bf16 v[6:9], v[208:211], v[182:185], v[6:9]
	v_mfma_f32_16x16x32_bf16 v[2:5], v[226:229], v[182:185], v[2:5]
	v_mfma_f32_16x16x32_bf16 v[34:37], v[208:211], v[130:133], v[34:37]
	v_mfma_f32_16x16x32_bf16 v[38:41], v[226:229], v[130:133], v[38:41]
	v_mfma_f32_16x16x32_bf16 v[42:45], v[208:211], v[146:149], v[42:45]
	v_mfma_f32_16x16x32_bf16 v[46:49], v[226:229], v[146:149], v[46:49]
	s_barrier
	s_add_i32 s67, 0, 0x18000
	v_add_u32_e32 v1, s67, v191
	ds_read_b128 v[54:57], v1
	ds_read_b128 v[70:73], v1 offset:1024
	ds_read_b128 v[82:85], v1 offset:2048
	ds_read_b128 v[86:89], v1 offset:3072
	s_add_u32 s4, s48, 0x40000
	s_addc_u32 s5, s49, 0
	s_mov_b32 m0, s55
	v_lshl_add_u64 v[134:135], s[4:5], 0, v[164:165]
	ds_read_b128 v[118:121], v206 offset:32768
	ds_read_b128 v[130:133], v206 offset:33792
	ds_read_b128 v[170:173], v206 offset:34816
	ds_read_b128 v[174:177], v206 offset:35840
	ds_read_b128 v[178:181], v206 offset:36864
	ds_read_b128 v[182:185], v206 offset:37888
	ds_read_b128 v[186:189], v206 offset:38912
	ds_read_b128 v[208:211], v206 offset:39936
	global_load_lds_dwordx4 v[134:135], off
	v_lshl_add_u64 v[134:135], s[4:5], 0, v[162:163]
	s_mov_b32 m0, s56
	s_nop 0
	global_load_lds_dwordx4 v[134:135], off
	s_waitcnt lgkmcnt(8)
	s_barrier
	s_waitcnt lgkmcnt(0)
	v_mfma_f32_16x16x32_bf16 v[134:137], v[54:57], v[118:121], v[158:161]
	v_mfma_f32_16x16x32_bf16 v[158:161], v[70:73], v[130:133], v[134:137]
	v_mfma_f32_16x16x32_bf16 v[134:137], v[82:85], v[118:121], v[154:157]
	v_mfma_f32_16x16x32_bf16 v[154:157], v[86:89], v[130:133], v[134:137]
	v_mfma_f32_16x16x32_bf16 v[134:137], v[54:57], v[170:173], v[142:145]
	v_mfma_f32_16x16x32_bf16 v[142:145], v[70:73], v[174:177], v[134:137]
	v_mfma_f32_16x16x32_bf16 v[134:137], v[82:85], v[170:173], v[138:141]
	v_mfma_f32_16x16x32_bf16 v[126:129], v[54:57], v[178:181], v[126:129]
	v_mfma_f32_16x16x32_bf16 v[122:125], v[82:85], v[178:181], v[122:125]
	v_mfma_f32_16x16x32_bf16 v[110:113], v[54:57], v[186:189], v[110:113]
	v_mfma_f32_16x16x32_bf16 v[106:109], v[82:85], v[186:189], v[106:109]
	v_mfma_f32_16x16x32_bf16 v[138:141], v[86:89], v[174:177], v[134:137]
	v_mfma_f32_16x16x32_bf16 v[126:129], v[70:73], v[182:185], v[126:129]
	v_mfma_f32_16x16x32_bf16 v[122:125], v[86:89], v[182:185], v[122:125]
	v_mfma_f32_16x16x32_bf16 v[110:113], v[70:73], v[208:211], v[110:113]
	v_mfma_f32_16x16x32_bf16 v[106:109], v[86:89], v[208:211], v[106:109]
	s_barrier
	s_add_i32 s48, 0, 0x1c000
	s_add_i32 s4, s67, s52
	v_add_u32_e32 v1, s48, v191
	v_lshl_add_u64 v[134:135], v[214:215], 0, s[22:23]
	s_mov_b32 m0, s4
	ds_read_b128 v[222:225], v1
	ds_read_b128 v[226:229], v1 offset:1024
	ds_read_b128 v[230:233], v1 offset:2048
	ds_read_b128 v[234:237], v1 offset:3072
	global_load_lds_dwordx4 v[134:135], off
	v_lshl_add_u64 v[134:135], v[238:239], 0, s[22:23]
	s_add_i32 m0, s4, 0x2000
	s_nop 0
	global_load_lds_dwordx4 v[134:135], off
	s_barrier
	s_waitcnt lgkmcnt(0)
	v_mfma_f32_16x16x32_bf16 v[50:53], v[230:233], v[118:121], v[50:53]
	v_mfma_f32_16x16x32_bf16 v[134:137], v[222:225], v[118:121], v[150:153]
	v_mfma_f32_16x16x32_bf16 v[146:149], v[234:237], v[130:133], v[50:53]
	v_mfma_f32_16x16x32_bf16 v[50:53], v[222:225], v[170:173], v[58:61]
	v_mfma_f32_16x16x32_bf16 v[150:153], v[226:229], v[130:133], v[134:137]
	v_mfma_f32_16x16x32_bf16 v[134:137], v[226:229], v[174:177], v[50:53]
	v_mfma_f32_16x16x32_bf16 v[50:53], v[230:233], v[170:173], v[62:65]
	v_mfma_f32_16x16x32_bf16 v[130:133], v[234:237], v[174:177], v[50:53]
	v_mfma_f32_16x16x32_bf16 v[50:53], v[222:225], v[178:181], v[66:69]
	v_mfma_f32_16x16x32_bf16 v[118:121], v[226:229], v[182:185], v[50:53]
	v_mfma_f32_16x16x32_bf16 v[50:53], v[230:233], v[178:181], v[114:117]
	v_mfma_f32_16x16x32_bf16 v[114:117], v[234:237], v[182:185], v[50:53]
	v_mfma_f32_16x16x32_bf16 v[50:53], v[222:225], v[186:189], v[102:105]
	v_mfma_f32_16x16x32_bf16 v[102:105], v[226:229], v[208:211], v[50:53]
	v_mfma_f32_16x16x32_bf16 v[50:53], v[230:233], v[186:189], v[98:101]
	v_mfma_f32_16x16x32_bf16 v[98:101], v[234:237], v[208:211], v[50:53]
	s_barrier
	s_mov_b32 m0, s58
	v_lshl_add_u64 v[186:187], v[240:241], 0, s[22:23]
	s_nop 2
	ds_read_b128 v[50:53], v206 offset:49152
	ds_read_b128 v[58:61], v206 offset:50176
	ds_read_b128 v[62:65], v206 offset:51200
	ds_read_b128 v[66:69], v206 offset:52224
	ds_read_b128 v[170:173], v206 offset:53248
	ds_read_b128 v[174:177], v206 offset:54272
	ds_read_b128 v[178:181], v206 offset:55296
	ds_read_b128 v[182:185], v206 offset:56320
	global_load_lds_dwordx4 v[186:187], off
	v_lshl_add_u64 v[186:187], v[242:243], 0, s[22:23]
	s_mov_b32 m0, s59
	s_nop 0
	global_load_lds_dwordx4 v[186:187], off
	s_barrier
	s_waitcnt lgkmcnt(0)
	v_mfma_f32_16x16x32_bf16 v[94:97], v[54:57], v[50:53], v[94:97]
	v_mfma_f32_16x16x32_bf16 v[90:93], v[82:85], v[50:53], v[90:93]
	v_mfma_f32_16x16x32_bf16 v[78:81], v[54:57], v[62:65], v[78:81]
	v_mfma_f32_16x16x32_bf16 v[74:77], v[82:85], v[62:65], v[74:77]
	v_mfma_f32_16x16x32_bf16 v[30:33], v[54:57], v[170:173], v[30:33]
	v_mfma_f32_16x16x32_bf16 v[26:29], v[82:85], v[170:173], v[26:29]
	v_mfma_f32_16x16x32_bf16 v[14:17], v[54:57], v[178:181], v[14:17]
	v_mfma_f32_16x16x32_bf16 v[10:13], v[82:85], v[178:181], v[10:13]
	v_mfma_f32_16x16x32_bf16 v[94:97], v[70:73], v[58:61], v[94:97]
	v_mfma_f32_16x16x32_bf16 v[90:93], v[86:89], v[58:61], v[90:93]
	v_mfma_f32_16x16x32_bf16 v[78:81], v[70:73], v[66:69], v[78:81]
	v_mfma_f32_16x16x32_bf16 v[74:77], v[86:89], v[66:69], v[74:77]
	v_mfma_f32_16x16x32_bf16 v[30:33], v[70:73], v[174:177], v[30:33]
	v_mfma_f32_16x16x32_bf16 v[26:29], v[86:89], v[174:177], v[26:29]
	v_mfma_f32_16x16x32_bf16 v[14:17], v[70:73], v[182:185], v[14:17]
	v_mfma_f32_16x16x32_bf16 v[10:13], v[86:89], v[182:185], v[10:13]
	s_barrier
	s_add_u32 s4, s46, 0x40080
	s_addc_u32 s5, s47, 0
	s_add_i32 s46, s48, s52
	v_lshl_add_u64 v[54:55], s[4:5], 0, v[164:165]
	s_mov_b32 m0, s46
	s_nop 0
	global_load_lds_dwordx4 v[54:55], off
	v_lshl_add_u64 v[54:55], s[4:5], 0, v[162:163]
	s_add_i32 m0, s46, 0x2000
	s_nop 0
	global_load_lds_dwordx4 v[54:55], off
	s_add_i32 s66, s66, 2
	s_add_u32 s64, s64, 0x100
	s_addc_u32 s65, s65, 0
	s_cmp_gt_u32 s66, 13
	s_mov_b64 s[4:5], s[36:37]
	s_waitcnt vmcnt(6)
	s_barrier
	v_mfma_f32_16x16x32_bf16 v[34:37], v[222:225], v[50:53], v[34:37]
	v_mfma_f32_16x16x32_bf16 v[86:89], v[226:229], v[58:61], v[34:37]
	v_mfma_f32_16x16x32_bf16 v[34:37], v[230:233], v[50:53], v[38:41]
	v_mfma_f32_16x16x32_bf16 v[82:85], v[234:237], v[58:61], v[34:37]
	v_mfma_f32_16x16x32_bf16 v[34:37], v[222:225], v[62:65], v[42:45]
	v_mfma_f32_16x16x32_bf16 v[70:73], v[226:229], v[66:69], v[34:37]
	v_mfma_f32_16x16x32_bf16 v[34:37], v[230:233], v[62:65], v[46:49]
	v_mfma_f32_16x16x32_bf16 v[22:25], v[222:225], v[170:173], v[22:25]
	v_mfma_f32_16x16x32_bf16 v[18:21], v[230:233], v[170:173], v[18:21]
	v_mfma_f32_16x16x32_bf16 v[6:9], v[222:225], v[178:181], v[6:9]
	v_mfma_f32_16x16x32_bf16 v[2:5], v[230:233], v[178:181], v[2:5]
	v_mfma_f32_16x16x32_bf16 v[54:57], v[234:237], v[66:69], v[34:37]
	v_mfma_f32_16x16x32_bf16 v[22:25], v[226:229], v[174:177], v[22:25]
	v_mfma_f32_16x16x32_bf16 v[18:21], v[234:237], v[174:177], v[18:21]
	v_mfma_f32_16x16x32_bf16 v[6:9], v[226:229], v[182:185], v[6:9]
	v_mfma_f32_16x16x32_bf16 v[2:5], v[234:237], v[182:185], v[2:5]
	s_barrier
.LBB0_212:
	s_add_u32 s36, s4, 0x100
	s_addc_u32 s37, s5, 0
	s_add_i32 s67, 0, 0x10000
	v_add_u32_e32 v1, s67, v191
	ds_read_b128 v[34:37], v1
	ds_read_b128 v[38:41], v1 offset:1024
	ds_read_b128 v[42:45], v1 offset:2048
	ds_read_b128 v[46:49], v1 offset:3072
	s_cmp_eq_u32 s66, 12
	s_cselect_b32 s49, s38, s37
	s_cselect_b32 s48, s43, s36
	s_cselect_b32 s47, s62, s65
	s_cselect_b32 s46, s63, s64
	v_lshl_add_u64 v[186:187], s[4:5], 0, v[168:169]
	s_add_i32 m0, s53, 0xc000
	ds_read_b128 v[50:53], v206
	ds_read_b128 v[58:61], v206 offset:1024
	ds_read_b128 v[62:65], v206 offset:2048
	ds_read_b128 v[66:69], v206 offset:3072
	ds_read_b128 v[170:173], v206 offset:4096
	ds_read_b128 v[174:177], v206 offset:5120
	ds_read_b128 v[178:181], v206 offset:6144
	ds_read_b128 v[182:185], v206 offset:7168
	global_load_lds_dwordx4 v[186:187], off
	v_lshl_add_u64 v[186:187], s[4:5], 0, v[166:167]
	s_add_i32 m0, s53, 0xe000
	s_nop 0
	global_load_lds_dwordx4 v[186:187], off
	s_waitcnt lgkmcnt(8)
	s_barrier
	s_waitcnt lgkmcnt(0)
	v_mfma_f32_16x16x32_bf16 v[158:161], v[34:37], v[50:53], v[158:161]
	v_mfma_f32_16x16x32_bf16 v[154:157], v[42:45], v[50:53], v[154:157]
	v_mfma_f32_16x16x32_bf16 v[142:145], v[34:37], v[62:65], v[142:145]
	v_mfma_f32_16x16x32_bf16 v[138:141], v[42:45], v[62:65], v[138:141]
	v_mfma_f32_16x16x32_bf16 v[126:129], v[34:37], v[170:173], v[126:129]
	v_mfma_f32_16x16x32_bf16 v[122:125], v[42:45], v[170:173], v[122:125]
	v_mfma_f32_16x16x32_bf16 v[110:113], v[34:37], v[178:181], v[110:113]
	v_mfma_f32_16x16x32_bf16 v[106:109], v[42:45], v[178:181], v[106:109]
	v_mfma_f32_16x16x32_bf16 v[158:161], v[38:41], v[58:61], v[158:161]
	v_mfma_f32_16x16x32_bf16 v[154:157], v[46:49], v[58:61], v[154:157]
	v_mfma_f32_16x16x32_bf16 v[142:145], v[38:41], v[66:69], v[142:145]
	v_mfma_f32_16x16x32_bf16 v[138:141], v[46:49], v[66:69], v[138:141]
	v_mfma_f32_16x16x32_bf16 v[126:129], v[38:41], v[174:177], v[126:129]
	v_mfma_f32_16x16x32_bf16 v[122:125], v[46:49], v[174:177], v[122:125]
	v_mfma_f32_16x16x32_bf16 v[110:113], v[38:41], v[182:185], v[110:113]
	v_mfma_f32_16x16x32_bf16 v[106:109], v[46:49], v[182:185], v[106:109]
	s_barrier
	s_add_i32 s68, 0, 0x14000
	s_add_i32 s4, s67, s52
	v_add_u32_e32 v1, s68, v191
	v_lshl_add_u64 v[214:215], s[46:47], 0, v[164:165]
	s_mov_b32 m0, s4
	ds_read_b128 v[186:189], v1
	ds_read_b128 v[208:211], v1 offset:1024
	ds_read_b128 v[222:225], v1 offset:2048
	ds_read_b128 v[226:229], v1 offset:3072
	global_load_lds_dwordx4 v[214:215], off
	v_lshl_add_u64 v[238:239], s[46:47], 0, v[162:163]
	s_add_i32 m0, s4, 0x2000
	s_nop 0
	global_load_lds_dwordx4 v[238:239], off
	s_barrier
	s_waitcnt lgkmcnt(0)
	v_mfma_f32_16x16x32_bf16 v[150:153], v[186:189], v[50:53], v[150:153]
	v_mfma_f32_16x16x32_bf16 v[50:53], v[222:225], v[50:53], v[146:149]
	v_mfma_f32_16x16x32_bf16 v[150:153], v[208:211], v[58:61], v[150:153]
	v_mfma_f32_16x16x32_bf16 v[50:53], v[226:229], v[58:61], v[50:53]
	v_mfma_f32_16x16x32_bf16 v[58:61], v[186:189], v[62:65], v[134:137]
	v_mfma_f32_16x16x32_bf16 v[62:65], v[222:225], v[62:65], v[130:133]
	v_mfma_f32_16x16x32_bf16 v[114:117], v[222:225], v[170:173], v[114:117]
	v_mfma_f32_16x16x32_bf16 v[102:105], v[186:189], v[178:181], v[102:105]
	v_mfma_f32_16x16x32_bf16 v[98:101], v[222:225], v[178:181], v[98:101]
	v_mfma_f32_16x16x32_bf16 v[58:61], v[208:211], v[66:69], v[58:61]
	v_mfma_f32_16x16x32_bf16 v[62:65], v[226:229], v[66:69], v[62:65]
	v_mfma_f32_16x16x32_bf16 v[66:69], v[186:189], v[170:173], v[118:121]
	v_mfma_f32_16x16x32_bf16 v[114:117], v[226:229], v[174:177], v[114:117]
	v_mfma_f32_16x16x32_bf16 v[102:105], v[208:211], v[182:185], v[102:105]
	v_mfma_f32_16x16x32_bf16 v[98:101], v[226:229], v[182:185], v[98:101]
	v_mfma_f32_16x16x32_bf16 v[66:69], v[208:211], v[174:177], v[66:69]
	s_barrier
	s_mov_b32 m0, s53
	v_lshl_add_u64 v[240:241], s[48:49], 0, v[164:165]
	ds_read_b128 v[118:121], v206 offset:16384
	ds_read_b128 v[130:133], v206 offset:17408
	ds_read_b128 v[134:137], v206 offset:18432
	ds_read_b128 v[146:149], v206 offset:19456
	ds_read_b128 v[170:173], v206 offset:20480
	ds_read_b128 v[174:177], v206 offset:21504
	ds_read_b128 v[178:181], v206 offset:22528
	ds_read_b128 v[182:185], v206 offset:23552
	global_load_lds_dwordx4 v[240:241], off
	v_lshl_add_u64 v[242:243], s[48:49], 0, v[162:163]
	s_mov_b32 m0, s54
	s_nop 0
	global_load_lds_dwordx4 v[242:243], off
	s_barrier
	s_waitcnt lgkmcnt(0)
	v_mfma_f32_16x16x32_bf16 v[94:97], v[34:37], v[118:121], v[94:97]
	v_mfma_f32_16x16x32_bf16 v[90:93], v[42:45], v[118:121], v[90:93]
	v_mfma_f32_16x16x32_bf16 v[78:81], v[34:37], v[134:137], v[78:81]
	v_mfma_f32_16x16x32_bf16 v[74:77], v[42:45], v[134:137], v[74:77]
	v_mfma_f32_16x16x32_bf16 v[30:33], v[34:37], v[170:173], v[30:33]
	v_mfma_f32_16x16x32_bf16 v[26:29], v[42:45], v[170:173], v[26:29]
	v_mfma_f32_16x16x32_bf16 v[14:17], v[34:37], v[178:181], v[14:17]
	v_mfma_f32_16x16x32_bf16 v[10:13], v[42:45], v[178:181], v[10:13]
	v_mfma_f32_16x16x32_bf16 v[94:97], v[38:41], v[130:133], v[94:97]
	v_mfma_f32_16x16x32_bf16 v[90:93], v[46:49], v[130:133], v[90:93]
	v_mfma_f32_16x16x32_bf16 v[78:81], v[38:41], v[146:149], v[78:81]
	v_mfma_f32_16x16x32_bf16 v[74:77], v[46:49], v[146:149], v[74:77]
	v_mfma_f32_16x16x32_bf16 v[30:33], v[38:41], v[174:177], v[30:33]
	v_mfma_f32_16x16x32_bf16 v[26:29], v[46:49], v[174:177], v[26:29]
	v_mfma_f32_16x16x32_bf16 v[14:17], v[38:41], v[182:185], v[14:17]
	v_mfma_f32_16x16x32_bf16 v[10:13], v[46:49], v[182:185], v[10:13]
	s_barrier
	s_add_u32 s4, s46, 0x40000
	s_addc_u32 s5, s47, 0
	s_add_i32 s67, s68, s52
	v_lshl_add_u64 v[34:35], s[4:5], 0, v[164:165]
	s_mov_b32 m0, s67
	s_nop 0
	global_load_lds_dwordx4 v[34:35], off
	v_lshl_add_u64 v[34:35], s[4:5], 0, v[162:163]
	s_add_i32 m0, s67, 0x2000
	s_nop 0
	global_load_lds_dwordx4 v[34:35], off
	s_waitcnt vmcnt(6)
	s_barrier
	v_mfma_f32_16x16x32_bf16 v[22:25], v[186:189], v[170:173], v[22:25]
	v_mfma_f32_16x16x32_bf16 v[18:21], v[222:225], v[170:173], v[18:21]
	v_mfma_f32_16x16x32_bf16 v[6:9], v[186:189], v[178:181], v[6:9]
	v_mfma_f32_16x16x32_bf16 v[2:5], v[222:225], v[178:181], v[2:5]
	v_mfma_f32_16x16x32_bf16 v[34:37], v[186:189], v[118:121], v[86:89]
	v_mfma_f32_16x16x32_bf16 v[38:41], v[222:225], v[118:121], v[82:85]
	v_mfma_f32_16x16x32_bf16 v[42:45], v[186:189], v[134:137], v[70:73]
	v_mfma_f32_16x16x32_bf16 v[46:49], v[222:225], v[134:137], v[54:57]
	v_mfma_f32_16x16x32_bf16 v[22:25], v[208:211], v[174:177], v[22:25]
	v_mfma_f32_16x16x32_bf16 v[18:21], v[226:229], v[174:177], v[18:21]
	v_mfma_f32_16x16x32_bf16 v[6:9], v[208:211], v[182:185], v[6:9]
	v_mfma_f32_16x16x32_bf16 v[2:5], v[226:229], v[182:185], v[2:5]
	v_mfma_f32_16x16x32_bf16 v[34:37], v[208:211], v[130:133], v[34:37]
	v_mfma_f32_16x16x32_bf16 v[38:41], v[226:229], v[130:133], v[38:41]
	v_mfma_f32_16x16x32_bf16 v[42:45], v[208:211], v[146:149], v[42:45]
	v_mfma_f32_16x16x32_bf16 v[46:49], v[226:229], v[146:149], v[46:49]
	s_barrier
	s_add_i32 s67, 0, 0x18000
	v_add_u32_e32 v1, s67, v191
	ds_read_b128 v[54:57], v1
	ds_read_b128 v[70:73], v1 offset:1024
	ds_read_b128 v[82:85], v1 offset:2048
	ds_read_b128 v[86:89], v1 offset:3072
	s_add_u32 s4, s48, 0x40000
	s_addc_u32 s5, s49, 0
	s_mov_b32 m0, s55
	v_lshl_add_u64 v[134:135], s[4:5], 0, v[164:165]
	ds_read_b128 v[118:121], v206 offset:32768
	ds_read_b128 v[130:133], v206 offset:33792
	ds_read_b128 v[170:173], v206 offset:34816
	ds_read_b128 v[174:177], v206 offset:35840
	ds_read_b128 v[178:181], v206 offset:36864
	ds_read_b128 v[182:185], v206 offset:37888
	ds_read_b128 v[186:189], v206 offset:38912
	ds_read_b128 v[208:211], v206 offset:39936
	global_load_lds_dwordx4 v[134:135], off
	v_lshl_add_u64 v[134:135], s[4:5], 0, v[162:163]
	s_mov_b32 m0, s56
	s_nop 0
	global_load_lds_dwordx4 v[134:135], off
	s_waitcnt lgkmcnt(8)
	s_barrier
	s_waitcnt lgkmcnt(0)
	v_mfma_f32_16x16x32_bf16 v[134:137], v[54:57], v[118:121], v[158:161]
	v_mfma_f32_16x16x32_bf16 v[158:161], v[70:73], v[130:133], v[134:137]
	v_mfma_f32_16x16x32_bf16 v[134:137], v[82:85], v[118:121], v[154:157]
	v_mfma_f32_16x16x32_bf16 v[154:157], v[86:89], v[130:133], v[134:137]
	v_mfma_f32_16x16x32_bf16 v[134:137], v[54:57], v[170:173], v[142:145]
	v_mfma_f32_16x16x32_bf16 v[142:145], v[70:73], v[174:177], v[134:137]
	v_mfma_f32_16x16x32_bf16 v[134:137], v[82:85], v[170:173], v[138:141]
	v_mfma_f32_16x16x32_bf16 v[126:129], v[54:57], v[178:181], v[126:129]
	v_mfma_f32_16x16x32_bf16 v[122:125], v[82:85], v[178:181], v[122:125]
	v_mfma_f32_16x16x32_bf16 v[110:113], v[54:57], v[186:189], v[110:113]
	v_mfma_f32_16x16x32_bf16 v[106:109], v[82:85], v[186:189], v[106:109]
	v_mfma_f32_16x16x32_bf16 v[138:141], v[86:89], v[174:177], v[134:137]
	v_mfma_f32_16x16x32_bf16 v[126:129], v[70:73], v[182:185], v[126:129]
	v_mfma_f32_16x16x32_bf16 v[122:125], v[86:89], v[182:185], v[122:125]
	v_mfma_f32_16x16x32_bf16 v[110:113], v[70:73], v[208:211], v[110:113]
	v_mfma_f32_16x16x32_bf16 v[106:109], v[86:89], v[208:211], v[106:109]
	s_barrier
	s_add_i32 s48, 0, 0x1c000
	s_add_i32 s4, s67, s52
	v_add_u32_e32 v1, s48, v191
	v_lshl_add_u64 v[134:135], v[214:215], 0, s[22:23]
	s_mov_b32 m0, s4
	ds_read_b128 v[222:225], v1
	ds_read_b128 v[226:229], v1 offset:1024
	ds_read_b128 v[230:233], v1 offset:2048
	ds_read_b128 v[234:237], v1 offset:3072
	global_load_lds_dwordx4 v[134:135], off
	v_lshl_add_u64 v[134:135], v[238:239], 0, s[22:23]
	s_add_i32 m0, s4, 0x2000
	s_nop 0
	global_load_lds_dwordx4 v[134:135], off
	s_barrier
	s_waitcnt lgkmcnt(0)
	v_mfma_f32_16x16x32_bf16 v[50:53], v[230:233], v[118:121], v[50:53]
	v_mfma_f32_16x16x32_bf16 v[134:137], v[222:225], v[118:121], v[150:153]
	v_mfma_f32_16x16x32_bf16 v[146:149], v[234:237], v[130:133], v[50:53]
	v_mfma_f32_16x16x32_bf16 v[50:53], v[222:225], v[170:173], v[58:61]
	v_mfma_f32_16x16x32_bf16 v[150:153], v[226:229], v[130:133], v[134:137]
	v_mfma_f32_16x16x32_bf16 v[134:137], v[226:229], v[174:177], v[50:53]
	v_mfma_f32_16x16x32_bf16 v[50:53], v[230:233], v[170:173], v[62:65]
	v_mfma_f32_16x16x32_bf16 v[130:133], v[234:237], v[174:177], v[50:53]
	v_mfma_f32_16x16x32_bf16 v[50:53], v[222:225], v[178:181], v[66:69]
	v_mfma_f32_16x16x32_bf16 v[118:121], v[226:229], v[182:185], v[50:53]
	v_mfma_f32_16x16x32_bf16 v[50:53], v[230:233], v[178:181], v[114:117]
	v_mfma_f32_16x16x32_bf16 v[114:117], v[234:237], v[182:185], v[50:53]
	v_mfma_f32_16x16x32_bf16 v[50:53], v[222:225], v[186:189], v[102:105]
	v_mfma_f32_16x16x32_bf16 v[102:105], v[226:229], v[208:211], v[50:53]
	v_mfma_f32_16x16x32_bf16 v[50:53], v[230:233], v[186:189], v[98:101]
	v_mfma_f32_16x16x32_bf16 v[98:101], v[234:237], v[208:211], v[50:53]
	s_barrier
	s_mov_b32 m0, s58
	v_lshl_add_u64 v[186:187], v[240:241], 0, s[22:23]
	s_nop 2
	ds_read_b128 v[50:53], v206 offset:49152
	ds_read_b128 v[58:61], v206 offset:50176
	ds_read_b128 v[62:65], v206 offset:51200
	ds_read_b128 v[66:69], v206 offset:52224
	ds_read_b128 v[170:173], v206 offset:53248
	ds_read_b128 v[174:177], v206 offset:54272
	ds_read_b128 v[178:181], v206 offset:55296
	ds_read_b128 v[182:185], v206 offset:56320
	global_load_lds_dwordx4 v[186:187], off
	v_lshl_add_u64 v[186:187], v[242:243], 0, s[22:23]
	s_mov_b32 m0, s59
	s_nop 0
	global_load_lds_dwordx4 v[186:187], off
	s_barrier
	s_waitcnt lgkmcnt(0)
	v_mfma_f32_16x16x32_bf16 v[94:97], v[54:57], v[50:53], v[94:97]
	v_mfma_f32_16x16x32_bf16 v[90:93], v[82:85], v[50:53], v[90:93]
	v_mfma_f32_16x16x32_bf16 v[78:81], v[54:57], v[62:65], v[78:81]
	v_mfma_f32_16x16x32_bf16 v[74:77], v[82:85], v[62:65], v[74:77]
	v_mfma_f32_16x16x32_bf16 v[30:33], v[54:57], v[170:173], v[30:33]
	v_mfma_f32_16x16x32_bf16 v[26:29], v[82:85], v[170:173], v[26:29]
	v_mfma_f32_16x16x32_bf16 v[14:17], v[54:57], v[178:181], v[14:17]
	v_mfma_f32_16x16x32_bf16 v[10:13], v[82:85], v[178:181], v[10:13]
	v_mfma_f32_16x16x32_bf16 v[94:97], v[70:73], v[58:61], v[94:97]
	v_mfma_f32_16x16x32_bf16 v[90:93], v[86:89], v[58:61], v[90:93]
	v_mfma_f32_16x16x32_bf16 v[78:81], v[70:73], v[66:69], v[78:81]
	v_mfma_f32_16x16x32_bf16 v[74:77], v[86:89], v[66:69], v[74:77]
	v_mfma_f32_16x16x32_bf16 v[30:33], v[70:73], v[174:177], v[30:33]
	v_mfma_f32_16x16x32_bf16 v[26:29], v[86:89], v[174:177], v[26:29]
	v_mfma_f32_16x16x32_bf16 v[14:17], v[70:73], v[182:185], v[14:17]
	v_mfma_f32_16x16x32_bf16 v[10:13], v[86:89], v[182:185], v[10:13]
	s_barrier
	s_add_u32 s4, s46, 0x40080
	s_addc_u32 s5, s47, 0
	s_add_i32 s46, s48, s52
	v_lshl_add_u64 v[54:55], s[4:5], 0, v[164:165]
	s_mov_b32 m0, s46
	s_nop 0
	global_load_lds_dwordx4 v[54:55], off
	v_lshl_add_u64 v[54:55], s[4:5], 0, v[162:163]
	s_add_i32 m0, s46, 0x2000
	s_nop 0
	global_load_lds_dwordx4 v[54:55], off
	s_add_i32 s66, s66, 2
	s_add_u32 s64, s64, 0x100
	s_addc_u32 s65, s65, 0
	s_cmp_gt_u32 s66, 13
	s_mov_b64 s[4:5], s[36:37]
	s_waitcnt vmcnt(6)
	s_barrier
	v_mfma_f32_16x16x32_bf16 v[34:37], v[222:225], v[50:53], v[34:37]
	v_mfma_f32_16x16x32_bf16 v[86:89], v[226:229], v[58:61], v[34:37]
	v_mfma_f32_16x16x32_bf16 v[34:37], v[230:233], v[50:53], v[38:41]
	v_mfma_f32_16x16x32_bf16 v[82:85], v[234:237], v[58:61], v[34:37]
	v_mfma_f32_16x16x32_bf16 v[34:37], v[222:225], v[62:65], v[42:45]
	v_mfma_f32_16x16x32_bf16 v[70:73], v[226:229], v[66:69], v[34:37]
	v_mfma_f32_16x16x32_bf16 v[34:37], v[230:233], v[62:65], v[46:49]
	v_mfma_f32_16x16x32_bf16 v[22:25], v[222:225], v[170:173], v[22:25]
	v_mfma_f32_16x16x32_bf16 v[18:21], v[230:233], v[170:173], v[18:21]
	v_mfma_f32_16x16x32_bf16 v[6:9], v[222:225], v[178:181], v[6:9]
	v_mfma_f32_16x16x32_bf16 v[2:5], v[230:233], v[178:181], v[2:5]
	v_mfma_f32_16x16x32_bf16 v[54:57], v[234:237], v[66:69], v[34:37]
	v_mfma_f32_16x16x32_bf16 v[22:25], v[226:229], v[174:177], v[22:25]
	v_mfma_f32_16x16x32_bf16 v[18:21], v[234:237], v[174:177], v[18:21]
	v_mfma_f32_16x16x32_bf16 v[6:9], v[226:229], v[182:185], v[6:9]
	v_mfma_f32_16x16x32_bf16 v[2:5], v[234:237], v[182:185], v[2:5]
	s_barrier
	s_cbranch_scc0 .LBB0_212
	s_setprio 0
	v_lshl_or_b32 v208, s3, 8, v192
	v_mov_b32_e32 v1, v190
	v_ashrrev_i32_e32 v209, 31, v208
	v_lshlrev_b64 v[34:35], 2, v[208:209]
	v_lshl_add_u64 v[36:37], s[8:9], 0, v[34:35]
	v_lshlrev_b32_e32 v250, 2, v192
	v_add_u32_e32 v250, 0x20840, v250
	ds_read_b128 v[62:65], v250
	ds_read_b128 v[50:53], v250 offset:16
	v_lshl_add_u64 v[34:35], s[10:11], 0, v[34:35]
	ds_read_b128 v[66:69], v250 offset:1024
	ds_read_b128 v[42:45], v250 offset:1040
	ds_read_b128 v[58:61], v250 offset:512
	ds_read_b128 v[38:41], v250 offset:528
	ds_read_b128 v[46:49], v250 offset:1536
	s_nop 0
	ds_read_b128 v[34:37], v250 offset:1552
	s_lshl_b32 s37, s27, 8
	v_lshl_add_u32 v170, v1, 3, 0
	v_add_u32_e32 v170, 0x20040, v170
	ds_read_b64 v[188:189], v170
	s_mov_b32 s4, 0xbf3a00e3
	s_cmp_gt_i32 s3, 3
	v_mov_b64_e32 v[176:177], s[4:5]
	s_cselect_b64 s[4:5], -1, 0
	s_and_b64 s[46:47], s[40:41], s[4:5]
	s_mov_b32 s4, 0x3f07dc22
	s_mov_b32 s38, 0x3f35f0e3
	s_mov_b32 s48, 0xbe11a98e
	s_mov_b32 s62, 0x3e027906
	s_lshl_b32 s3, s3, 2
	s_and_b32 s36, s3, 12
	s_mov_b32 s3, 0x1020000
	v_add_u32_e32 v170, s37, v1
	v_lshlrev_b32_e32 v1, 10, v170
	s_waitcnt lgkmcnt(0)
	v_xor_b32_e32 v65, 0x80000000, v65
	v_xor_b32_e32 v64, 0x80000000, v64
	v_pk_fma_f32 v[158:159], v[62:63], v[188:189], v[158:159] op_sel_hi:[1,0,1] neg_lo:[1,0,0] neg_hi:[1,0,0]
	v_xor_b32_e32 v53, 0x80000000, v53
	v_xor_b32_e32 v52, 0x80000000, v52
	v_pk_fma_f32 v[154:155], v[50:51], v[188:189], v[154:155] op_sel_hi:[1,0,1] neg_lo:[1,0,0] neg_hi:[1,0,0]
	v_pk_fma_f32 v[160:161], v[64:65], v[188:189], v[160:161] op_sel_hi:[1,0,1]
	v_pk_fma_f32 v[158:159], v[188:189], v[158:159], v[66:67] op_sel:[1,0,0]
	v_pk_fma_f32 v[172:173], v[52:53], v[188:189], v[156:157] op_sel_hi:[1,0,1]
	v_pk_fma_f32 v[156:157], v[188:189], v[154:155], v[42:43] op_sel:[1,0,0]
	v_pk_fma_f32 v[154:155], v[188:189], v[160:161], v[68:69] op_sel:[1,0,0]
	v_fma_f32 v175, |v159|, s1, 1.0
	v_fma_f32 v171, |v158|, s1, 1.0
	v_pk_fma_f32 v[160:161], v[188:189], v[172:173], v[44:45] op_sel:[1,0,0]
	v_fma_f32 v172, |v156|, s1, 1.0
	v_rcp_f32_e32 v175, v175
	v_fma_f32 v187, |v155|, s1, 1.0
	v_mul_f32_e32 v174, v158, v158
	v_rcp_f32_e32 v182, v171
	v_rcp_f32_e32 v183, v172
	v_rcp_f32_e32 v215, v187
	v_mul_f32_e32 v173, v156, v156
	v_fma_f32 v179, |v157|, s1, 1.0
	v_mul_f32_e32 v180, v157, v157
	v_mul_f32_e32 v171, 0xbf38aa3b, v174
	v_mul_f32_e32 v186, v154, v154
	v_fma_f32 v181, |v154|, s1, 1.0
	v_mul_f32_e32 v172, 0xbf38aa3b, v173
	v_rcp_f32_e32 v185, v179
	v_mul_f32_e32 v173, 0xbf38aa3b, v180
	v_fma_f32 v179, |v160|, s1, 1.0
	v_mul_f32_e32 v209, v160, v160
	v_exp_f32_e32 v180, v171
	v_mul_f32_e32 v171, 0xbf38aa3b, v186
	v_fma_f32 v211, |v161|, s1, 1.0
	v_rcp_f32_e32 v184, v181
	v_exp_f32_e32 v181, v172
	v_rcp_f32_e32 v210, v179
	v_mul_f32_e32 v179, 0xbf38aa3b, v209
	v_exp_f32_e32 v172, v171
	v_fmamk_f32 v171, v175, 0x3f07dc22, v218
	v_rcp_f32_e32 v211, v211
	v_exp_f32_e32 v214, v179
	v_pk_fma_f32 v[186:187], v[182:183], s[4:5], v[176:177] op_sel_hi:[1,0,0]
	v_fmaak_f32 v171, v175, v171, 0x3f35f0e3
	v_fmamk_f32 v179, v215, 0x3f07dc22, v218
	v_pk_fma_f32 v[186:187], v[182:183], v[186:187], s[38:39] op_sel_hi:[1,1,0]
	v_fmaak_f32 v171, v175, v171, 0xbe11a98e
	v_fmaak_f32 v179, v215, v179, 0x3f35f0e3
	v_pk_fma_f32 v[186:187], v[182:183], v[186:187], s[48:49] op_sel_hi:[1,1,0]
	v_fmaak_f32 v171, v175, v171, 0x3e027906
	v_fmaak_f32 v179, v215, v179, 0xbe11a98e
	v_mul_f32_e32 v212, v161, v161
	v_pk_fma_f32 v[224:225], v[182:183], v[186:187], s[62:63] op_sel_hi:[1,1,0]
	v_mul_f32_e32 v186, v175, v171
	v_fmaak_f32 v171, v215, v179, 0x3e027906
	v_pk_fma_f32 v[222:223], v[184:185], s[4:5], v[176:177] op_sel_hi:[1,0,0]
	v_pk_mul_f32 v[224:225], v[182:183], v[224:225]
	v_mul_f32_e32 v182, v215, v171
	v_mul_f32_e32 v171, 0xbf38aa3b, v212
	v_pk_fma_f32 v[176:177], v[210:211], s[4:5], v[176:177] op_sel_hi:[1,0,0]
	v_exp_f32_e32 v215, v171
	v_pk_fma_f32 v[176:177], v[210:211], v[176:177], s[38:39] op_sel_hi:[1,1,0]
	v_cmp_gt_f32_e32 vcc, 0, v161
	v_pk_fma_f32 v[176:177], v[210:211], v[176:177], s[48:49] op_sel_hi:[1,1,0]
	v_pk_fma_f32 v[150:151], v[58:59], v[188:189], v[150:151] op_sel_hi:[1,0,1] neg_lo:[1,0,0] neg_hi:[1,0,0]
	v_pk_fma_f32 v[176:177], v[210:211], v[176:177], s[62:63] op_sel_hi:[1,1,0]
	v_pk_fma_f32 v[150:151], v[188:189], v[150:151], v[46:47] op_sel:[1,0,0]
	v_pk_mul_f32 v[176:177], v[210:211], v[176:177]
	v_fma_f32 v175, |v150|, s1, 1.0
	v_pk_mul_f32 v[176:177], v[214:215], v[176:177]
	v_rcp_f32_e32 v175, v175
	v_pk_mul_f32 v[210:211], v[160:161], v[176:177]
	v_pk_fma_f32 v[176:177], v[160:161], v[176:177], v[160:161] neg_lo:[1,0,0] neg_hi:[1,0,0]
	v_mul_f32_e32 v178, v159, v159
	v_cndmask_b32_e32 v177, v177, v211, vcc
	v_cmp_gt_f32_e32 vcc, 0, v160
	v_xor_b32_e32 v61, 0x80000000, v61
	v_xor_b32_e32 v60, 0x80000000, v60
	v_cndmask_b32_e32 v176, v176, v210, vcc
	v_mul_f32_e32 v160, v176, v176
	v_pk_fma_f32 v[160:161], v[176:177], v[176:177], v[160:161] op_sel_hi:[1,1,0]
	v_mul_f32_e32 v174, 0xbf38aa3b, v178
	v_lshrrev_b32_e32 v160, 10, v208
	v_mul_f32_e32 v207, v155, v155
	v_mul_lo_u32 v160, v160, s3
	s_movk_i32 s4, 0x3ff
	v_pk_fma_f32 v[152:153], v[60:61], v[188:189], v[152:153] op_sel_hi:[1,0,1]
	v_exp_f32_e32 v178, v174
	v_mul_f32_e32 v174, 0xbf38aa3b, v207
	v_and_or_b32 v207, v208, s4, v160
	v_add_u32_e32 v171, 0x80, v208
	v_pk_fma_f32 v[208:209], v[188:189], v[152:153], v[48:49] op_sel:[1,0,0]
	v_fmamk_f32 v152, v175, 0x3f07dc22, v218
	v_fmaak_f32 v152, v175, v152, 0x3f35f0e3
	v_mul_f32_e32 v153, v150, v150
	v_mul_f32_e32 v153, 0xbf38aa3b, v153
	v_fmaak_f32 v152, v175, v152, 0xbe11a98e
	v_exp_f32_e32 v153, v153
	v_fmaak_f32 v152, v175, v152, 0x3e027906
	v_mul_f32_e32 v152, v175, v152
	v_fma_f32 v175, |v151|, s1, 1.0
	v_rcp_f32_e32 v175, v175
	v_mul_f32_e32 v152, v153, v152
	v_mul_f32_e32 v153, v150, v152
	v_fma_f32 v152, -v150, v152, v150
	v_cmp_gt_f32_e32 vcc, 0, v150
	v_pk_fma_f32 v[146:147], v[38:39], v[188:189], v[146:147] op_sel_hi:[1,0,1] neg_lo:[1,0,0] neg_hi:[1,0,0]
	v_xor_b32_e32 v41, 0x80000000, v41
	v_cndmask_b32_e32 v150, v152, v153, vcc
	v_fmamk_f32 v152, v175, 0x3f07dc22, v218
	v_fmaak_f32 v152, v175, v152, 0x3f35f0e3
	v_mul_f32_e32 v153, v151, v151
	v_fmaak_f32 v152, v175, v152, 0xbe11a98e
	v_mul_f32_e32 v153, 0xbf38aa3b, v153
	v_fmaak_f32 v152, v175, v152, 0x3e027906
	v_exp_f32_e32 v153, v153
	v_mul_f32_e32 v152, v175, v152
	v_fma_f32 v175, |v208|, s1, 1.0
	v_rcp_f32_e32 v175, v175
	v_mul_f32_e32 v152, v153, v152
	v_mul_f32_e32 v153, v151, v152
	v_fma_f32 v152, -v151, v152, v151
	v_cmp_gt_f32_e32 vcc, 0, v151
	v_fmamk_f32 v151, v175, 0x3f07dc22, v218
	v_fmaak_f32 v151, v175, v151, 0x3f35f0e3
	v_cndmask_b32_e32 v152, v152, v153, vcc
	v_mul_f32_e32 v153, v208, v208
	v_mul_f32_e32 v153, 0xbf38aa3b, v153
	v_fmaak_f32 v151, v175, v151, 0xbe11a98e
	v_exp_f32_e32 v153, v153
	v_fmaak_f32 v151, v175, v151, 0x3e027906
	v_mul_f32_e32 v151, v175, v151
	v_fma_f32 v175, |v209|, s1, 1.0
	v_rcp_f32_e32 v175, v175
	v_mul_f32_e32 v151, v153, v151
	v_mul_f32_e32 v153, v208, v151
	v_fma_f32 v151, -v208, v151, v208
	v_cmp_gt_f32_e32 vcc, 0, v208
	v_pk_fma_f32 v[146:147], v[188:189], v[146:147], v[34:35] op_sel:[1,0,0]
	v_xor_b32_e32 v40, 0x80000000, v40
	v_cndmask_b32_e32 v208, v151, v153, vcc
	v_fmamk_f32 v151, v175, 0x3f07dc22, v218
	v_fmaak_f32 v151, v175, v151, 0x3f35f0e3
	v_fmaak_f32 v151, v175, v151, 0xbe11a98e
	v_fmaak_f32 v151, v175, v151, 0x3e027906
	v_mul_f32_e32 v151, v175, v151
	v_fma_f32 v175, |v146|, s1, 1.0
	v_rcp_f32_e32 v175, v175
	v_mul_f32_e32 v183, v146, v146
	v_mul_f32_e32 v153, v209, v209
	v_mul_f32_e32 v183, 0xbf38aa3b, v183
	v_fmamk_f32 v179, v175, 0x3f07dc22, v218
	v_mul_f32_e32 v153, 0xbf38aa3b, v153
	v_fmaak_f32 v179, v175, v179, 0x3f35f0e3
	v_exp_f32_e32 v183, v183
	v_exp_f32_e32 v153, v153
	v_fmaak_f32 v179, v175, v179, 0xbe11a98e
	v_fmaak_f32 v179, v175, v179, 0x3e027906
	v_mul_f32_e32 v175, v175, v179
	v_mul_f32_e32 v175, v183, v175
	v_fma_f32 v183, |v147|, s1, 1.0
	v_mul_f32_e32 v151, v153, v151
	v_rcp_f32_e32 v183, v183
	v_mul_f32_e32 v153, v209, v151
	v_fma_f32 v151, -v209, v151, v209
	v_cmp_gt_f32_e32 vcc, 0, v209
	v_mul_f32_e32 v179, v146, v175
	v_fma_f32 v175, -v146, v175, v146
	v_cndmask_b32_e32 v210, v151, v153, vcc
	v_cmp_gt_f32_e32 vcc, 0, v146
	v_pk_fma_f32 v[148:149], v[40:41], v[188:189], v[148:149] op_sel_hi:[1,0,1]
	v_fmamk_f32 v146, v183, 0x3f07dc22, v218
	v_cndmask_b32_e32 v214, v175, v179, vcc
	v_mul_f32_e32 v175, v147, v147
	v_mul_f32_e32 v175, 0xbf38aa3b, v175
	v_pk_fma_f32 v[148:149], v[188:189], v[148:149], v[36:37] op_sel:[1,0,0]
	v_fmaak_f32 v146, v183, v146, 0x3f35f0e3
	v_exp_f32_e32 v175, v175
	v_fmaak_f32 v146, v183, v146, 0xbe11a98e
	v_fma_f32 v179, |v148|, s1, 1.0
	v_fmaak_f32 v146, v183, v146, 0x3e027906
	v_rcp_f32_e32 v179, v179
	v_pk_fma_f32 v[222:223], v[184:185], v[222:223], s[38:39] op_sel_hi:[1,1,0]
	v_mul_f32_e32 v146, v183, v146
	v_pk_fma_f32 v[222:223], v[184:185], v[222:223], s[48:49] op_sel_hi:[1,1,0]
	v_mul_f32_e32 v146, v175, v146
	v_pk_fma_f32 v[222:223], v[184:185], v[222:223], s[62:63] op_sel_hi:[1,1,0]
	v_mul_f32_e32 v175, v147, v146
	v_fma_f32 v146, -v147, v146, v147
	v_cmp_gt_f32_e32 vcc, 0, v147
	v_mul_f32_e32 v147, v148, v148
	v_pk_mul_f32 v[184:185], v[184:185], v[222:223]
	v_cndmask_b32_e32 v222, v146, v175, vcc
	v_fmamk_f32 v146, v179, 0x3f07dc22, v218
	v_mul_f32_e32 v147, 0xbf38aa3b, v147
	v_fmaak_f32 v146, v179, v146, 0x3f35f0e3
	v_exp_f32_e32 v147, v147
	v_fmaak_f32 v146, v179, v146, 0xbe11a98e
	v_fmaak_f32 v146, v179, v146, 0x3e027906
	v_fma_f32 v175, |v149|, s1, 1.0
	v_mul_f32_e32 v146, v179, v146
	v_rcp_f32_e32 v175, v175
	v_mul_f32_e32 v146, v147, v146
	v_mul_f32_e32 v147, v148, v146
	v_fma_f32 v146, -v148, v146, v148
	v_cmp_gt_f32_e32 vcc, 0, v148
	v_exp_f32_e32 v173, v173
	v_exp_f32_e32 v174, v174
	v_cndmask_b32_e32 v226, v146, v147, vcc
	v_mul_f32_e32 v147, v149, v149
	v_fmamk_f32 v146, v175, 0x3f07dc22, v218
	v_mul_f32_e32 v147, 0xbf38aa3b, v147
	v_fmaak_f32 v146, v175, v146, 0x3f35f0e3
	v_exp_f32_e32 v147, v147
	v_fmaak_f32 v146, v175, v146, 0xbe11a98e
	v_fmaak_f32 v146, v175, v146, 0x3e027906
	v_mul_f32_e32 v146, v175, v146
	v_mul_f32_e32 v146, v147, v146
	v_mul_f32_e32 v147, v149, v146
	v_fma_f32 v146, -v149, v146, v149
	v_cmp_gt_f32_e32 vcc, 0, v149
	v_mov_b32_e32 v179, v181
	v_mov_b32_e32 v187, v225
	v_cndmask_b32_e32 v228, v146, v147, vcc
	v_lshrrev_b32_e32 v146, 10, v171
	v_mul_lo_u32 v146, v146, s3
	v_and_or_b32 v188, v171, s4, v146
	v_pk_mul_f32 v[146:147], v[180:181], v[224:225]
	v_pk_mul_f32 v[148:149], v[178:179], v[186:187]
	v_mov_b32_e32 v178, v158
	v_mov_b32_e32 v179, v156
	v_pk_mov_b32 v[186:187], v[158:159], v[156:157] op_sel:[1,0]
	v_pk_mul_f32 v[180:181], v[178:179], v[146:147]
	v_pk_mul_f32 v[224:225], v[186:187], v[148:149]
	v_pk_fma_f32 v[146:147], v[178:179], v[146:147], v[178:179] neg_lo:[1,0,0] neg_hi:[1,0,0]
	v_pk_fma_f32 v[148:149], v[186:187], v[148:149], v[186:187] neg_lo:[1,0,0] neg_hi:[1,0,0]
	v_cmp_gt_f32_e32 vcc, 0, v156
	v_cmp_gt_f32_e64 s[4:5], 0, v158
	v_mov_b32_e32 v175, v173
	v_cndmask_b32_e32 v179, v147, v181, vcc
	v_cndmask_b32_e32 v181, v149, v225, vcc
	v_cmp_gt_f32_e32 vcc, 0, v159
	v_mov_b32_e32 v183, v185
	v_cndmask_b32_e64 v178, v146, v180, s[4:5]
	v_cndmask_b32_e32 v180, v148, v224, vcc
	v_pk_mul_f32 v[148:149], v[172:173], v[184:185]
	v_pk_mul_f32 v[158:159], v[174:175], v[182:183]
	v_mov_b32_e32 v156, v154
	v_mov_b32_e32 v174, v155
	v_mov_b32_e32 v175, v157
	v_pk_mul_f32 v[172:173], v[156:157], v[148:149]
	v_pk_mul_f32 v[182:183], v[174:175], v[158:159]
	v_pk_fma_f32 v[148:149], v[156:157], v[148:149], v[156:157] neg_lo:[1,0,0] neg_hi:[1,0,0]
	v_pk_fma_f32 v[158:159], v[174:175], v[158:159], v[174:175] neg_lo:[1,0,0] neg_hi:[1,0,0]
	v_cmp_gt_f32_e32 vcc, 0, v157
	v_cmp_gt_f32_e64 s[4:5], 0, v154
	v_add_lshl_u32 v160, v1, v207, 1
	v_cndmask_b32_e32 v157, v149, v173, vcc
	v_cndmask_b32_e64 v156, v148, v172, s[4:5]
	v_cndmask_b32_e32 v159, v159, v183, vcc
	v_cmp_gt_f32_e32 vcc, 0, v155
	v_pk_mul_f32 v[174:175], v[156:157], v[156:157]
	v_mul_f32_e32 v151, v150, v150
	v_cndmask_b32_e32 v158, v158, v182, vcc
	v_mul_f32_e32 v153, v152, v152
	v_mul_f32_e32 v209, v208, v208
	v_mul_f32_e32 v211, v210, v210
	v_mul_f32_e32 v215, v214, v214
	v_mul_f32_e32 v223, v222, v222
	v_mul_f32_e32 v227, v226, v226
	v_mul_f32_e32 v229, v228, v228
	v_add_lshl_u32 v171, v1, v188, 1
	v_cvt_pk_bf16_f32 v146, v178, v180
	v_cvt_pk_bf16_f32 v147, v156, v158
	v_pk_mul_f32 v[154:155], v[178:179], v[178:179]
	v_pk_mul_f32 v[172:173], v[180:181], v[180:181]
	v_pk_mul_f32 v[182:183], v[158:159], v[158:159]
	v_pk_mov_b32 v[154:155], v[178:179], v[154:155] op_sel:[1,0]
	v_pk_mov_b32 v[172:173], v[156:157], v[172:173] op_sel:[1,0]
	v_cvt_pk_bf16_f32 v148, v179, v157
	v_mov_b32_e32 v1, v161
	v_pk_add_f32 v[154:155], v[154:155], v[172:173]
	v_mov_b32_e32 v172, v176
	v_mov_b32_e32 v173, v174
	v_pk_mov_b32 v[174:175], v[176:177], v[182:183] op_sel:[1,0]
	v_cvt_pk_bf16_f32 v149, v176, v177
	buffer_store_dwordx4 v[146:149], v160, s[28:31], 0 offen sc1
	v_pk_add_f32 v[172:173], v[172:173], v[174:175]
	v_pk_mul_f32 v[174:175], v[178:179], v[180:181]
	v_pk_add_f32 v[154:155], v[154:155], v[172:173]
	v_pk_add_f32 v[172:173], v[178:179], v[180:181]
	s_nop 0
	v_mov_b32_e32 v173, v175
	v_pk_add_f32 v[174:175], v[156:157], v[158:159]
	v_pk_mul_f32 v[156:157], v[156:157], v[158:159]
	s_nop 0
	v_mov_b32_e32 v175, v157
	v_pk_add_f32 v[156:157], v[172:173], v[174:175]
	s_nop 0
	v_pk_add_f32 v[156:157], v[156:157], v[0:1]
	s_nop 0
	v_pk_add_f32 v[154:155], v[154:155], v[156:157]
	v_cvt_pk_bf16_f32 v146, v150, v152
	v_pk_add_f32 v[148:149], v[150:151], v[152:153]
	v_pk_add_f32 v[150:151], v[208:209], v[210:211]
	v_cvt_pk_bf16_f32 v147, v208, v210
	s_nop 0
	v_pk_add_f32 v[148:149], v[148:149], v[150:151]
	s_nop 0
	v_pk_add_f32 v[150:151], v[148:149], v[154:155]
	v_pk_add_f32 v[152:153], v[214:215], v[222:223]
	v_pk_add_f32 v[154:155], v[226:227], v[228:229]
	v_cvt_pk_bf16_f32 v148, v214, v222
	v_cvt_pk_bf16_f32 v149, v226, v228
	buffer_store_dwordx4 v[146:149], v171, s[28:31], 0 offen sc1
	v_pk_add_f32 v[152:153], v[152:153], v[154:155]
	s_nop 0
	v_pk_add_f32 v[150:151], v[152:153], v[150:151]
	v_and_b32_e32 v146, 64, v216
	v_xor_b32_e32 v1, 16, v216
	v_add_u32_e32 v148, 64, v146
	v_cmp_lt_i32_e32 vcc, v1, v148
	s_nop 1
	v_cndmask_b32_e32 v1, v216, v1, vcc
	v_lshlrev_b32_e32 v174, 2, v1
	ds_bpermute_b32 v146, v174, v150
	ds_bpermute_b32 v147, v174, v151
	v_xor_b32_e32 v1, 32, v216
	v_cmp_lt_i32_e32 vcc, v1, v148
	s_waitcnt lgkmcnt(0)
	v_pk_add_f32 v[146:147], v[150:151], v[146:147]
	v_cndmask_b32_e32 v1, v216, v1, vcc
	v_lshlrev_b32_e32 v175, 2, v1
	ds_bpermute_b32 v148, v175, v146
	ds_bpermute_b32 v149, v175, v147
	s_and_saveexec_b64 s[4:5], s[46:47]
	s_cbranch_execz .LBB0_215
	v_ashrrev_i32_e32 v171, 31, v170
	v_lshlrev_b64 v[150:151], 7, v[170:171]
	v_lshl_add_u64 v[150:151], s[12:13], 0, v[150:151]
	s_lshl_b32 s38, s36, 3
	v_lshl_add_u64 v[150:151], v[150:151], 0, s[38:39]
	s_lshl_b32 s38, s57, 3
	v_lshl_add_u64 v[150:151], v[150:151], 0, s[38:39]
	s_waitcnt lgkmcnt(0)
	v_pk_add_f32 v[146:147], v[146:147], v[148:149]
	flat_store_dwordx2 v[150:151], v[146:147]

.LBB0_395:
	s_add_i32 s66, s66, 1
	s_mov_b64 s[36:37], s[20:21]
	s_mul_i32 s20, s66, s26
	s_add_i32 s42, s20, s2
	s_cmpk_gt_i32 s42, 0x3ff
	s_cselect_b64 s[52:53], -1, 0
	s_lshl_b32 s20, s42, 3
	s_and_b32 s20, s20, 56
	s_bfe_u32 s21, s42, 0x30003
	s_mov_b32 s3, s67
	s_or_b32 s67, s20, s21
	s_mov_b32 s27, s50
	s_ashr_i32 s50, s42, 6
	s_lshl_b32 s20, s67, 19
	s_mov_b64 s[4:5], s[48:49]
	s_add_u32 s48, s18, s20
	s_addc_u32 s49, s19, 0
	s_ashr_i32 s51, s50, 31
	s_lshl_b64 s[20:21], s[50:51], 19
	s_add_u32 s20, s16, s20
	s_addc_u32 s21, s17, s21
	s_cmpk_lt_i32 s42, 0x400
	s_cselect_b32 s46, s49, s5
	s_cselect_b32 s47, s48, s4
	s_cselect_b32 s51, s21, s37
	s_cselect_b32 s54, s20, s36
	s_add_u32 s55, s36, 0x100
	s_addc_u32 s56, s37, 0
	s_mov_b32 s57, -2
	s_add_u32 s36, s4, 0x100
	s_addc_u32 s37, s5, 0
	s_add_i32 s68, 0, 0x10000
	v_add_u32_e32 v30, s68, v204
	ds_read_b128 v[14:17], v30
	ds_read_b128 v[22:25], v30 offset:1024
	ds_read_b128 v[26:29], v30 offset:2048
	ds_read_b128 v[30:33], v30 offset:3072
	s_cmp_eq_u32 s57, 12
	s_cselect_b32 s45, s46, s37
	s_cselect_b32 s44, s47, s36
	s_cselect_b32 s43, s51, s56
	s_cselect_b32 s42, s54, s55
	v_lshl_add_u64 v[178:179], s[4:5], 0, v[188:189]
	s_add_i32 m0, s60, 0xc000
	ds_read_b128 v[38:41], v209
	ds_read_b128 v[42:45], v209 offset:1024
	ds_read_b128 v[46:49], v209 offset:2048
	ds_read_b128 v[54:57], v209 offset:3072
	ds_read_b128 v[58:61], v209 offset:4096
	ds_read_b128 v[62:65], v209 offset:5120
	ds_read_b128 v[66:69], v209 offset:6144
	ds_read_b128 v[70:73], v209 offset:7168
	global_load_lds_dwordx4 v[178:179], off
	v_lshl_add_u64 v[178:179], s[4:5], 0, v[186:187]
	s_add_i32 m0, s60, 0xe000
	s_nop 0
	global_load_lds_dwordx4 v[178:179], off
	s_waitcnt lgkmcnt(8)
	s_barrier
	s_waitcnt lgkmcnt(0)
	v_mfma_f32_16x16x32_bf16 v[174:177], v[14:17], v[38:41], 0
	v_mfma_f32_16x16x32_bf16 v[170:173], v[26:29], v[38:41], 0
	v_mfma_f32_16x16x32_bf16 v[158:161], v[14:17], v[46:49], 0
	v_mfma_f32_16x16x32_bf16 v[154:157], v[26:29], v[46:49], 0
	v_mfma_f32_16x16x32_bf16 v[142:145], v[14:17], v[58:61], 0
	v_mfma_f32_16x16x32_bf16 v[138:141], v[26:29], v[58:61], 0
	v_mfma_f32_16x16x32_bf16 v[126:129], v[14:17], v[66:69], 0
	v_mfma_f32_16x16x32_bf16 v[122:125], v[26:29], v[66:69], 0
	v_mfma_f32_16x16x32_bf16 v[174:177], v[22:25], v[42:45], v[174:177]
	v_mfma_f32_16x16x32_bf16 v[170:173], v[30:33], v[42:45], v[170:173]
	v_mfma_f32_16x16x32_bf16 v[158:161], v[22:25], v[54:57], v[158:161]
	v_mfma_f32_16x16x32_bf16 v[154:157], v[30:33], v[54:57], v[154:157]
	v_mfma_f32_16x16x32_bf16 v[142:145], v[22:25], v[62:65], v[142:145]
	v_mfma_f32_16x16x32_bf16 v[138:141], v[30:33], v[62:65], v[138:141]
	v_mfma_f32_16x16x32_bf16 v[126:129], v[22:25], v[70:73], v[126:129]
	v_mfma_f32_16x16x32_bf16 v[122:125], v[30:33], v[70:73], v[122:125]
	s_barrier
	v_mbcnt_lo_u32_b32 v250, -1, 0
	v_mbcnt_hi_u32_b32 v250, -1, v250
	v_lshlrev_b32_e32 v250, 4, v250
	s_lshl_b32 s32, s27, 10
	s_add_u32 s90, s10, s32
	s_addc_u32 s91, s11, 0
	s_add_u32 s92, s12, s32
	s_addc_u32 s93, s13, 0
	s_and_b32 s32, s27, 3
	s_lshl_b32 s32, s32, 10
	s_add_u32 s98, s14, s32
	s_addc_u32 s99, s15, 0
	s_mov_b32 m0, 0x20840
	s_nop 0
	global_load_lds_dwordx4 v250, s[90:91]
	s_mov_b32 m0, 0x20c40
	s_nop 0
	global_load_lds_dwordx4 v250, s[92:93]
	s_mov_b32 m0, 0x21040
	s_nop 0
	global_load_lds_dwordx4 v250, s[98:99]
	s_add_i32 s69, 0, 0x14000
	v_add_u32_e32 v210, s69, v204
	s_add_i32 s4, s68, s59
	ds_read_b128 v[178:181], v210
	ds_read_b128 v[190:193], v210 offset:1024
	ds_read_b128 v[200:203], v210 offset:2048
	ds_read_b128 v[222:225], v210 offset:3072
	v_lshl_add_u64 v[210:211], s[42:43], 0, v[184:185]
	s_mov_b32 m0, s4
	v_lshl_add_u64 v[214:215], s[42:43], 0, v[182:183]
	global_load_lds_dwordx4 v[210:211], off
	s_add_i32 m0, s4, 0x2000
	s_nop 0
	global_load_lds_dwordx4 v[214:215], off
	s_barrier
	s_waitcnt lgkmcnt(0)
	v_mfma_f32_16x16x32_bf16 v[166:169], v[178:181], v[38:41], 0
	v_mfma_f32_16x16x32_bf16 v[38:41], v[200:203], v[38:41], 0
	v_mfma_f32_16x16x32_bf16 v[166:169], v[190:193], v[42:45], v[166:169]
	v_mfma_f32_16x16x32_bf16 v[38:41], v[222:225], v[42:45], v[38:41]
	v_mfma_f32_16x16x32_bf16 v[42:45], v[178:181], v[46:49], 0
	v_mfma_f32_16x16x32_bf16 v[46:49], v[200:203], v[46:49], 0
	v_mfma_f32_16x16x32_bf16 v[42:45], v[190:193], v[54:57], v[42:45]
	v_mfma_f32_16x16x32_bf16 v[46:49], v[222:225], v[54:57], v[46:49]
	v_mfma_f32_16x16x32_bf16 v[54:57], v[178:181], v[58:61], 0
	v_mfma_f32_16x16x32_bf16 v[58:61], v[200:203], v[58:61], 0
	v_mfma_f32_16x16x32_bf16 v[54:57], v[190:193], v[62:65], v[54:57]
	v_mfma_f32_16x16x32_bf16 v[58:61], v[222:225], v[62:65], v[58:61]
	v_mfma_f32_16x16x32_bf16 v[62:65], v[178:181], v[66:69], 0
	v_mfma_f32_16x16x32_bf16 v[66:69], v[200:203], v[66:69], 0
	v_mfma_f32_16x16x32_bf16 v[62:65], v[190:193], v[70:73], v[62:65]
	v_mfma_f32_16x16x32_bf16 v[66:69], v[222:225], v[70:73], v[66:69]
	s_barrier
	s_mov_b32 m0, s60
	v_lshl_add_u64 v[242:243], s[44:45], 0, v[184:185]
	ds_read_b128 v[70:73], v209 offset:16384
	ds_read_b128 v[114:117], v209 offset:17408
	ds_read_b128 v[118:121], v209 offset:18432
	ds_read_b128 v[130:133], v209 offset:19456
	ds_read_b128 v[134:137], v209 offset:20480
	ds_read_b128 v[146:149], v209 offset:21504
	ds_read_b128 v[150:153], v209 offset:22528
	ds_read_b128 v[162:165], v209 offset:23552
	global_load_lds_dwordx4 v[242:243], off
	v_lshl_add_u64 v[244:245], s[44:45], 0, v[182:183]
	s_mov_b32 m0, s61
	s_nop 0
	global_load_lds_dwordx4 v[244:245], off
	s_barrier
	s_waitcnt lgkmcnt(0)
	v_mfma_f32_16x16x32_bf16 v[110:113], v[14:17], v[70:73], 0
	v_mfma_f32_16x16x32_bf16 v[106:109], v[26:29], v[70:73], 0
	v_mfma_f32_16x16x32_bf16 v[94:97], v[14:17], v[118:121], 0
	v_mfma_f32_16x16x32_bf16 v[90:93], v[26:29], v[118:121], 0
	v_mfma_f32_16x16x32_bf16 v[78:81], v[14:17], v[134:137], 0
	v_mfma_f32_16x16x32_bf16 v[74:77], v[26:29], v[134:137], 0
	v_mfma_f32_16x16x32_bf16 v[10:13], v[26:29], v[150:153], 0
	v_mfma_f32_16x16x32_bf16 v[110:113], v[22:25], v[114:117], v[110:113]
	v_mfma_f32_16x16x32_bf16 v[106:109], v[30:33], v[114:117], v[106:109]
	v_mfma_f32_16x16x32_bf16 v[94:97], v[22:25], v[130:133], v[94:97]
	v_mfma_f32_16x16x32_bf16 v[90:93], v[30:33], v[130:133], v[90:93]
	v_mfma_f32_16x16x32_bf16 v[78:81], v[22:25], v[146:149], v[78:81]
	v_mfma_f32_16x16x32_bf16 v[74:77], v[30:33], v[146:149], v[74:77]
	v_mfma_f32_16x16x32_bf16 v[14:17], v[14:17], v[150:153], 0
	v_mfma_f32_16x16x32_bf16 v[10:13], v[30:33], v[162:165], v[10:13]
	v_mfma_f32_16x16x32_bf16 v[14:17], v[22:25], v[162:165], v[14:17]
	s_barrier
	s_add_u32 s4, s42, 0x40000
	s_addc_u32 s5, s43, 0
	s_add_i32 s68, s69, s59
	v_lshl_add_u64 v[18:19], s[4:5], 0, v[184:185]
	s_mov_b32 m0, s68
	s_nop 0
	global_load_lds_dwordx4 v[18:19], off
	v_lshl_add_u64 v[18:19], s[4:5], 0, v[182:183]
	s_add_i32 m0, s68, 0x2000
	s_nop 0
	global_load_lds_dwordx4 v[18:19], off
	s_waitcnt vmcnt(6)
	s_barrier
	v_mfma_f32_16x16x32_bf16 v[18:21], v[178:181], v[70:73], 0
	v_mfma_f32_16x16x32_bf16 v[22:25], v[190:193], v[114:117], v[18:21]
	v_mfma_f32_16x16x32_bf16 v[18:21], v[200:203], v[70:73], 0
	v_mfma_f32_16x16x32_bf16 v[26:29], v[222:225], v[114:117], v[18:21]
	v_mfma_f32_16x16x32_bf16 v[18:21], v[178:181], v[118:121], 0
	v_mfma_f32_16x16x32_bf16 v[30:33], v[190:193], v[130:133], v[18:21]
	v_mfma_f32_16x16x32_bf16 v[18:21], v[200:203], v[118:121], 0
	v_mfma_f32_16x16x32_bf16 v[70:73], v[222:225], v[130:133], v[18:21]
	v_mfma_f32_16x16x32_bf16 v[18:21], v[178:181], v[134:137], 0
	v_mfma_f32_16x16x32_bf16 v[50:53], v[190:193], v[146:149], v[18:21]
	v_mfma_f32_16x16x32_bf16 v[18:21], v[200:203], v[134:137], 0
	v_mfma_f32_16x16x32_bf16 v[6:9], v[178:181], v[150:153], 0
	v_mfma_f32_16x16x32_bf16 v[2:5], v[200:203], v[150:153], 0
	v_mfma_f32_16x16x32_bf16 v[34:37], v[222:225], v[146:149], v[18:21]
	v_mfma_f32_16x16x32_bf16 v[6:9], v[190:193], v[162:165], v[6:9]
	v_mfma_f32_16x16x32_bf16 v[2:5], v[222:225], v[162:165], v[2:5]
	s_barrier
	s_add_i32 s68, 0, 0x18000
	v_add_u32_e32 v98, s68, v204
	ds_read_b128 v[18:21], v98
	ds_read_b128 v[82:85], v98 offset:1024
	ds_read_b128 v[86:89], v98 offset:2048
	ds_read_b128 v[98:101], v98 offset:3072
	s_add_u32 s4, s44, 0x40000
	s_addc_u32 s5, s45, 0
	s_mov_b32 m0, s62
	v_lshl_add_u64 v[134:135], s[4:5], 0, v[184:185]
	ds_read_b128 v[102:105], v209 offset:32768
	ds_read_b128 v[114:117], v209 offset:33792
	ds_read_b128 v[118:121], v209 offset:34816
	ds_read_b128 v[130:133], v209 offset:35840
	ds_read_b128 v[178:181], v209 offset:36864
	ds_read_b128 v[190:193], v209 offset:37888
	ds_read_b128 v[200:203], v209 offset:38912
	ds_read_b128 v[222:225], v209 offset:39936
	global_load_lds_dwordx4 v[134:135], off
	v_lshl_add_u64 v[134:135], s[4:5], 0, v[182:183]
	s_mov_b32 m0, s63
	s_nop 0
	global_load_lds_dwordx4 v[134:135], off
	s_waitcnt lgkmcnt(8)
	s_barrier
	s_waitcnt lgkmcnt(0)
	v_mfma_f32_16x16x32_bf16 v[134:137], v[18:21], v[102:105], v[174:177]
	v_mfma_f32_16x16x32_bf16 v[174:177], v[82:85], v[114:117], v[134:137]
	v_mfma_f32_16x16x32_bf16 v[134:137], v[86:89], v[102:105], v[170:173]
	v_mfma_f32_16x16x32_bf16 v[170:173], v[98:101], v[114:117], v[134:137]
	v_mfma_f32_16x16x32_bf16 v[134:137], v[18:21], v[118:121], v[158:161]
	v_mfma_f32_16x16x32_bf16 v[158:161], v[82:85], v[130:133], v[134:137]
	v_mfma_f32_16x16x32_bf16 v[134:137], v[86:89], v[118:121], v[154:157]
	v_mfma_f32_16x16x32_bf16 v[154:157], v[98:101], v[130:133], v[134:137]
	v_mfma_f32_16x16x32_bf16 v[134:137], v[18:21], v[178:181], v[142:145]
	v_mfma_f32_16x16x32_bf16 v[142:145], v[82:85], v[190:193], v[134:137]
	v_mfma_f32_16x16x32_bf16 v[134:137], v[86:89], v[178:181], v[138:141]
	v_mfma_f32_16x16x32_bf16 v[126:129], v[18:21], v[200:203], v[126:129]
	v_mfma_f32_16x16x32_bf16 v[122:125], v[86:89], v[200:203], v[122:125]
	v_mfma_f32_16x16x32_bf16 v[138:141], v[98:101], v[190:193], v[134:137]
	v_mfma_f32_16x16x32_bf16 v[126:129], v[82:85], v[222:225], v[126:129]
	v_mfma_f32_16x16x32_bf16 v[122:125], v[98:101], v[222:225], v[122:125]
	s_barrier
	s_add_i32 s44, 0, 0x1c000
	v_add_u32_e32 v134, s44, v204
	s_add_i32 s4, s68, s59
	ds_read_b128 v[226:229], v134
	ds_read_b128 v[230:233], v134 offset:1024
	ds_read_b128 v[234:237], v134 offset:2048
	ds_read_b128 v[238:241], v134 offset:3072
	v_lshl_add_u64 v[134:135], v[210:211], 0, s[22:23]
	s_mov_b32 m0, s4
	s_nop 0
	global_load_lds_dwordx4 v[134:135], off
	v_lshl_add_u64 v[134:135], v[214:215], 0, s[22:23]
	s_add_i32 m0, s4, 0x2000
	s_nop 0
	global_load_lds_dwordx4 v[134:135], off
	s_barrier
	s_waitcnt lgkmcnt(0)
	v_mfma_f32_16x16x32_bf16 v[38:41], v[234:237], v[102:105], v[38:41]
	v_mfma_f32_16x16x32_bf16 v[162:165], v[238:241], v[114:117], v[38:41]
	v_mfma_f32_16x16x32_bf16 v[38:41], v[226:229], v[118:121], v[42:45]
	v_mfma_f32_16x16x32_bf16 v[150:153], v[230:233], v[130:133], v[38:41]
	v_mfma_f32_16x16x32_bf16 v[38:41], v[234:237], v[118:121], v[46:49]
	v_mfma_f32_16x16x32_bf16 v[134:137], v[226:229], v[102:105], v[166:169]
	v_mfma_f32_16x16x32_bf16 v[146:149], v[238:241], v[130:133], v[38:41]
	v_mfma_f32_16x16x32_bf16 v[38:41], v[226:229], v[178:181], v[54:57]
	v_mfma_f32_16x16x32_bf16 v[166:169], v[230:233], v[114:117], v[134:137]
	v_mfma_f32_16x16x32_bf16 v[134:137], v[230:233], v[190:193], v[38:41]
	v_mfma_f32_16x16x32_bf16 v[38:41], v[234:237], v[178:181], v[58:61]
	v_mfma_f32_16x16x32_bf16 v[130:133], v[238:241], v[190:193], v[38:41]
	v_mfma_f32_16x16x32_bf16 v[38:41], v[226:229], v[200:203], v[62:65]
	v_mfma_f32_16x16x32_bf16 v[118:121], v[230:233], v[222:225], v[38:41]
	v_mfma_f32_16x16x32_bf16 v[38:41], v[234:237], v[200:203], v[66:69]
	v_mfma_f32_16x16x32_bf16 v[114:117], v[238:241], v[222:225], v[38:41]
	s_barrier
	s_mov_b32 m0, s64
	v_lshl_add_u64 v[102:103], v[242:243], 0, s[22:23]
	s_nop 2
	ds_read_b128 v[38:41], v209 offset:49152
	ds_read_b128 v[42:45], v209 offset:50176
	ds_read_b128 v[46:49], v209 offset:51200
	ds_read_b128 v[54:57], v209 offset:52224
	ds_read_b128 v[58:61], v209 offset:53248
	ds_read_b128 v[62:65], v209 offset:54272
	ds_read_b128 v[66:69], v209 offset:55296
	ds_read_b128 v[178:181], v209 offset:56320
	global_load_lds_dwordx4 v[102:103], off
	v_lshl_add_u64 v[102:103], v[244:245], 0, s[22:23]
	s_mov_b32 m0, s65
	s_nop 0
	global_load_lds_dwordx4 v[102:103], off
	s_barrier
	s_waitcnt lgkmcnt(0)
	v_mfma_f32_16x16x32_bf16 v[102:105], v[18:21], v[38:41], v[110:113]
	v_mfma_f32_16x16x32_bf16 v[110:113], v[82:85], v[42:45], v[102:105]
	v_mfma_f32_16x16x32_bf16 v[102:105], v[86:89], v[38:41], v[106:109]
	v_mfma_f32_16x16x32_bf16 v[94:97], v[18:21], v[46:49], v[94:97]
	v_mfma_f32_16x16x32_bf16 v[90:93], v[86:89], v[46:49], v[90:93]
	v_mfma_f32_16x16x32_bf16 v[78:81], v[18:21], v[58:61], v[78:81]
	v_mfma_f32_16x16x32_bf16 v[74:77], v[86:89], v[58:61], v[74:77]
	v_mfma_f32_16x16x32_bf16 v[14:17], v[18:21], v[66:69], v[14:17]
	v_mfma_f32_16x16x32_bf16 v[10:13], v[86:89], v[66:69], v[10:13]
	v_mfma_f32_16x16x32_bf16 v[106:109], v[98:101], v[42:45], v[102:105]
	v_mfma_f32_16x16x32_bf16 v[94:97], v[82:85], v[54:57], v[94:97]
	v_mfma_f32_16x16x32_bf16 v[90:93], v[98:101], v[54:57], v[90:93]
	v_mfma_f32_16x16x32_bf16 v[78:81], v[82:85], v[62:65], v[78:81]
	v_mfma_f32_16x16x32_bf16 v[74:77], v[98:101], v[62:65], v[74:77]
	v_mfma_f32_16x16x32_bf16 v[18:21], v[82:85], v[178:181], v[14:17]
	v_mfma_f32_16x16x32_bf16 v[10:13], v[98:101], v[178:181], v[10:13]
	s_barrier
	s_add_u32 s4, s42, 0x40080
	s_addc_u32 s5, s43, 0
	s_add_i32 s42, s44, s59
	v_lshl_add_u64 v[14:15], s[4:5], 0, v[184:185]
	s_mov_b32 m0, s42
	s_nop 0
	global_load_lds_dwordx4 v[14:15], off
	v_lshl_add_u64 v[14:15], s[4:5], 0, v[182:183]
	s_add_i32 m0, s42, 0x2000
	s_nop 0
	global_load_lds_dwordx4 v[14:15], off
	s_add_i32 s57, s57, 2
	s_add_u32 s55, s55, 0x100
	s_addc_u32 s56, s56, 0
	s_cmp_gt_u32 s57, 13
	s_mov_b64 s[4:5], s[36:37]
	s_waitcnt vmcnt(6)
	s_barrier
	v_mfma_f32_16x16x32_bf16 v[14:17], v[226:229], v[38:41], v[22:25]
	v_mfma_f32_16x16x32_bf16 v[102:105], v[230:233], v[42:45], v[14:17]
	v_mfma_f32_16x16x32_bf16 v[14:17], v[234:237], v[38:41], v[26:29]
	v_mfma_f32_16x16x32_bf16 v[98:101], v[238:241], v[42:45], v[14:17]
	v_mfma_f32_16x16x32_bf16 v[14:17], v[226:229], v[46:49], v[30:33]
	v_mfma_f32_16x16x32_bf16 v[86:89], v[230:233], v[54:57], v[14:17]
	v_mfma_f32_16x16x32_bf16 v[14:17], v[234:237], v[46:49], v[70:73]
	v_mfma_f32_16x16x32_bf16 v[82:85], v[238:241], v[54:57], v[14:17]
	v_mfma_f32_16x16x32_bf16 v[14:17], v[226:229], v[58:61], v[50:53]
	v_mfma_f32_16x16x32_bf16 v[50:53], v[230:233], v[62:65], v[14:17]
	v_mfma_f32_16x16x32_bf16 v[14:17], v[234:237], v[58:61], v[34:37]
	v_mfma_f32_16x16x32_bf16 v[6:9], v[226:229], v[66:69], v[6:9]
	v_mfma_f32_16x16x32_bf16 v[2:5], v[234:237], v[66:69], v[2:5]
	v_mfma_f32_16x16x32_bf16 v[34:37], v[238:241], v[62:65], v[14:17]
	v_mfma_f32_16x16x32_bf16 v[6:9], v[230:233], v[178:181], v[6:9]
	v_mfma_f32_16x16x32_bf16 v[2:5], v[238:241], v[178:181], v[2:5]
	s_barrier
.LBB0_396:
	s_add_u32 s36, s4, 0x100
	s_addc_u32 s37, s5, 0
	s_add_i32 s68, 0, 0x10000
	v_add_u32_e32 v30, s68, v204
	ds_read_b128 v[14:17], v30
	ds_read_b128 v[22:25], v30 offset:1024
	ds_read_b128 v[26:29], v30 offset:2048
	ds_read_b128 v[30:33], v30 offset:3072
	s_cmp_eq_u32 s57, 12
	s_cselect_b32 s45, s46, s37
	s_cselect_b32 s44, s47, s36
	s_cselect_b32 s43, s51, s56
	s_cselect_b32 s42, s54, s55
	v_lshl_add_u64 v[178:179], s[4:5], 0, v[188:189]
	s_add_i32 m0, s60, 0xc000
	ds_read_b128 v[38:41], v209
	ds_read_b128 v[42:45], v209 offset:1024
	ds_read_b128 v[46:49], v209 offset:2048
	ds_read_b128 v[54:57], v209 offset:3072
	ds_read_b128 v[58:61], v209 offset:4096
	ds_read_b128 v[62:65], v209 offset:5120
	ds_read_b128 v[66:69], v209 offset:6144
	ds_read_b128 v[70:73], v209 offset:7168
	global_load_lds_dwordx4 v[178:179], off
	v_lshl_add_u64 v[178:179], s[4:5], 0, v[186:187]
	s_add_i32 m0, s60, 0xe000
	s_nop 0
	global_load_lds_dwordx4 v[178:179], off
	s_waitcnt lgkmcnt(8)
	s_barrier
	s_waitcnt lgkmcnt(0)
	v_mfma_f32_16x16x32_bf16 v[174:177], v[14:17], v[38:41], v[174:177]
	v_mfma_f32_16x16x32_bf16 v[170:173], v[26:29], v[38:41], v[170:173]
	v_mfma_f32_16x16x32_bf16 v[158:161], v[14:17], v[46:49], v[158:161]
	v_mfma_f32_16x16x32_bf16 v[154:157], v[26:29], v[46:49], v[154:157]
	v_mfma_f32_16x16x32_bf16 v[142:145], v[14:17], v[58:61], v[142:145]
	v_mfma_f32_16x16x32_bf16 v[138:141], v[26:29], v[58:61], v[138:141]
	v_mfma_f32_16x16x32_bf16 v[126:129], v[14:17], v[66:69], v[126:129]
	v_mfma_f32_16x16x32_bf16 v[122:125], v[26:29], v[66:69], v[122:125]
	v_mfma_f32_16x16x32_bf16 v[174:177], v[22:25], v[42:45], v[174:177]
	v_mfma_f32_16x16x32_bf16 v[170:173], v[30:33], v[42:45], v[170:173]
	v_mfma_f32_16x16x32_bf16 v[158:161], v[22:25], v[54:57], v[158:161]
	v_mfma_f32_16x16x32_bf16 v[154:157], v[30:33], v[54:57], v[154:157]
	v_mfma_f32_16x16x32_bf16 v[142:145], v[22:25], v[62:65], v[142:145]
	v_mfma_f32_16x16x32_bf16 v[138:141], v[30:33], v[62:65], v[138:141]
	v_mfma_f32_16x16x32_bf16 v[126:129], v[22:25], v[70:73], v[126:129]
	v_mfma_f32_16x16x32_bf16 v[122:125], v[30:33], v[70:73], v[122:125]
	s_barrier
	s_add_i32 s69, 0, 0x14000
	v_add_u32_e32 v210, s69, v204
	s_add_i32 s4, s68, s59
	ds_read_b128 v[178:181], v210
	ds_read_b128 v[190:193], v210 offset:1024
	ds_read_b128 v[200:203], v210 offset:2048
	ds_read_b128 v[222:225], v210 offset:3072
	v_lshl_add_u64 v[210:211], s[42:43], 0, v[184:185]
	s_mov_b32 m0, s4
	v_lshl_add_u64 v[214:215], s[42:43], 0, v[182:183]
	global_load_lds_dwordx4 v[210:211], off
	s_add_i32 m0, s4, 0x2000
	s_nop 0
	global_load_lds_dwordx4 v[214:215], off
	s_barrier
	s_waitcnt lgkmcnt(0)
	v_mfma_f32_16x16x32_bf16 v[166:169], v[178:181], v[38:41], v[166:169]
	v_mfma_f32_16x16x32_bf16 v[38:41], v[200:203], v[38:41], v[162:165]
	v_mfma_f32_16x16x32_bf16 v[166:169], v[190:193], v[42:45], v[166:169]
	v_mfma_f32_16x16x32_bf16 v[38:41], v[222:225], v[42:45], v[38:41]
	v_mfma_f32_16x16x32_bf16 v[42:45], v[178:181], v[46:49], v[150:153]
	v_mfma_f32_16x16x32_bf16 v[46:49], v[200:203], v[46:49], v[146:149]
	v_mfma_f32_16x16x32_bf16 v[42:45], v[190:193], v[54:57], v[42:45]
	v_mfma_f32_16x16x32_bf16 v[46:49], v[222:225], v[54:57], v[46:49]
	v_mfma_f32_16x16x32_bf16 v[54:57], v[178:181], v[58:61], v[134:137]
	v_mfma_f32_16x16x32_bf16 v[58:61], v[200:203], v[58:61], v[130:133]
	v_mfma_f32_16x16x32_bf16 v[54:57], v[190:193], v[62:65], v[54:57]
	v_mfma_f32_16x16x32_bf16 v[58:61], v[222:225], v[62:65], v[58:61]
	v_mfma_f32_16x16x32_bf16 v[62:65], v[178:181], v[66:69], v[118:121]
	v_mfma_f32_16x16x32_bf16 v[66:69], v[200:203], v[66:69], v[114:117]
	v_mfma_f32_16x16x32_bf16 v[62:65], v[190:193], v[70:73], v[62:65]
	v_mfma_f32_16x16x32_bf16 v[66:69], v[222:225], v[70:73], v[66:69]
	s_barrier
	s_mov_b32 m0, s60
	v_lshl_add_u64 v[242:243], s[44:45], 0, v[184:185]
	ds_read_b128 v[70:73], v209 offset:16384
	ds_read_b128 v[114:117], v209 offset:17408
	ds_read_b128 v[118:121], v209 offset:18432
	ds_read_b128 v[130:133], v209 offset:19456
	ds_read_b128 v[134:137], v209 offset:20480
	ds_read_b128 v[146:149], v209 offset:21504
	ds_read_b128 v[150:153], v209 offset:22528
	ds_read_b128 v[162:165], v209 offset:23552
	global_load_lds_dwordx4 v[242:243], off
	v_lshl_add_u64 v[244:245], s[44:45], 0, v[182:183]
	s_mov_b32 m0, s61
	s_nop 0
	global_load_lds_dwordx4 v[244:245], off
	s_barrier
	s_waitcnt lgkmcnt(0)
	v_mfma_f32_16x16x32_bf16 v[110:113], v[14:17], v[70:73], v[110:113]
	v_mfma_f32_16x16x32_bf16 v[106:109], v[26:29], v[70:73], v[106:109]
	v_mfma_f32_16x16x32_bf16 v[94:97], v[14:17], v[118:121], v[94:97]
	v_mfma_f32_16x16x32_bf16 v[90:93], v[26:29], v[118:121], v[90:93]
	v_mfma_f32_16x16x32_bf16 v[78:81], v[14:17], v[134:137], v[78:81]
	v_mfma_f32_16x16x32_bf16 v[74:77], v[26:29], v[134:137], v[74:77]
	v_mfma_f32_16x16x32_bf16 v[10:13], v[26:29], v[150:153], v[10:13]
	v_mfma_f32_16x16x32_bf16 v[110:113], v[22:25], v[114:117], v[110:113]
	v_mfma_f32_16x16x32_bf16 v[106:109], v[30:33], v[114:117], v[106:109]
	v_mfma_f32_16x16x32_bf16 v[94:97], v[22:25], v[130:133], v[94:97]
	v_mfma_f32_16x16x32_bf16 v[90:93], v[30:33], v[130:133], v[90:93]
	v_mfma_f32_16x16x32_bf16 v[78:81], v[22:25], v[146:149], v[78:81]
	v_mfma_f32_16x16x32_bf16 v[74:77], v[30:33], v[146:149], v[74:77]
	v_mfma_f32_16x16x32_bf16 v[14:17], v[14:17], v[150:153], v[18:21]
	v_mfma_f32_16x16x32_bf16 v[10:13], v[30:33], v[162:165], v[10:13]
	v_mfma_f32_16x16x32_bf16 v[14:17], v[22:25], v[162:165], v[14:17]
	s_barrier
	s_add_u32 s4, s42, 0x40000
	s_addc_u32 s5, s43, 0
	s_add_i32 s68, s69, s59
	v_lshl_add_u64 v[18:19], s[4:5], 0, v[184:185]
	s_mov_b32 m0, s68
	s_nop 0
	global_load_lds_dwordx4 v[18:19], off
	v_lshl_add_u64 v[18:19], s[4:5], 0, v[182:183]
	s_add_i32 m0, s68, 0x2000
	s_nop 0
	global_load_lds_dwordx4 v[18:19], off
	s_waitcnt vmcnt(6)
	s_barrier
	v_mfma_f32_16x16x32_bf16 v[18:21], v[178:181], v[70:73], v[102:105]
	v_mfma_f32_16x16x32_bf16 v[22:25], v[190:193], v[114:117], v[18:21]
	v_mfma_f32_16x16x32_bf16 v[18:21], v[200:203], v[70:73], v[98:101]
	v_mfma_f32_16x16x32_bf16 v[26:29], v[222:225], v[114:117], v[18:21]
	v_mfma_f32_16x16x32_bf16 v[18:21], v[178:181], v[118:121], v[86:89]
	v_mfma_f32_16x16x32_bf16 v[30:33], v[190:193], v[130:133], v[18:21]
	v_mfma_f32_16x16x32_bf16 v[18:21], v[200:203], v[118:121], v[82:85]
	v_mfma_f32_16x16x32_bf16 v[70:73], v[222:225], v[130:133], v[18:21]
	v_mfma_f32_16x16x32_bf16 v[18:21], v[178:181], v[134:137], v[50:53]
	v_mfma_f32_16x16x32_bf16 v[50:53], v[190:193], v[146:149], v[18:21]
	v_mfma_f32_16x16x32_bf16 v[18:21], v[200:203], v[134:137], v[34:37]
	v_mfma_f32_16x16x32_bf16 v[6:9], v[178:181], v[150:153], v[6:9]
	v_mfma_f32_16x16x32_bf16 v[2:5], v[200:203], v[150:153], v[2:5]
	v_mfma_f32_16x16x32_bf16 v[34:37], v[222:225], v[146:149], v[18:21]
	v_mfma_f32_16x16x32_bf16 v[6:9], v[190:193], v[162:165], v[6:9]
	v_mfma_f32_16x16x32_bf16 v[2:5], v[222:225], v[162:165], v[2:5]
	s_barrier
	s_add_i32 s68, 0, 0x18000
	v_add_u32_e32 v98, s68, v204
	ds_read_b128 v[18:21], v98
	ds_read_b128 v[82:85], v98 offset:1024
	ds_read_b128 v[86:89], v98 offset:2048
	ds_read_b128 v[98:101], v98 offset:3072
	s_add_u32 s4, s44, 0x40000
	s_addc_u32 s5, s45, 0
	s_mov_b32 m0, s62
	v_lshl_add_u64 v[134:135], s[4:5], 0, v[184:185]
	ds_read_b128 v[102:105], v209 offset:32768
	ds_read_b128 v[114:117], v209 offset:33792
	ds_read_b128 v[118:121], v209 offset:34816
	ds_read_b128 v[130:133], v209 offset:35840
	ds_read_b128 v[178:181], v209 offset:36864
	ds_read_b128 v[190:193], v209 offset:37888
	ds_read_b128 v[200:203], v209 offset:38912
	ds_read_b128 v[222:225], v209 offset:39936
	global_load_lds_dwordx4 v[134:135], off
	v_lshl_add_u64 v[134:135], s[4:5], 0, v[182:183]
	s_mov_b32 m0, s63
	s_nop 0
	global_load_lds_dwordx4 v[134:135], off
	s_waitcnt lgkmcnt(8)
	s_barrier
	s_waitcnt lgkmcnt(0)
	v_mfma_f32_16x16x32_bf16 v[134:137], v[18:21], v[102:105], v[174:177]
	v_mfma_f32_16x16x32_bf16 v[174:177], v[82:85], v[114:117], v[134:137]
	v_mfma_f32_16x16x32_bf16 v[134:137], v[86:89], v[102:105], v[170:173]
	v_mfma_f32_16x16x32_bf16 v[170:173], v[98:101], v[114:117], v[134:137]
	v_mfma_f32_16x16x32_bf16 v[134:137], v[18:21], v[118:121], v[158:161]
	v_mfma_f32_16x16x32_bf16 v[158:161], v[82:85], v[130:133], v[134:137]
	v_mfma_f32_16x16x32_bf16 v[134:137], v[86:89], v[118:121], v[154:157]
	v_mfma_f32_16x16x32_bf16 v[154:157], v[98:101], v[130:133], v[134:137]
	v_mfma_f32_16x16x32_bf16 v[134:137], v[18:21], v[178:181], v[142:145]
	v_mfma_f32_16x16x32_bf16 v[142:145], v[82:85], v[190:193], v[134:137]
	v_mfma_f32_16x16x32_bf16 v[134:137], v[86:89], v[178:181], v[138:141]
	v_mfma_f32_16x16x32_bf16 v[126:129], v[18:21], v[200:203], v[126:129]
	v_mfma_f32_16x16x32_bf16 v[122:125], v[86:89], v[200:203], v[122:125]
	v_mfma_f32_16x16x32_bf16 v[138:141], v[98:101], v[190:193], v[134:137]
	v_mfma_f32_16x16x32_bf16 v[126:129], v[82:85], v[222:225], v[126:129]
	v_mfma_f32_16x16x32_bf16 v[122:125], v[98:101], v[222:225], v[122:125]
	s_barrier
	s_add_i32 s44, 0, 0x1c000
	v_add_u32_e32 v134, s44, v204
	s_add_i32 s4, s68, s59
	ds_read_b128 v[226:229], v134
	ds_read_b128 v[230:233], v134 offset:1024
	ds_read_b128 v[234:237], v134 offset:2048
	ds_read_b128 v[238:241], v134 offset:3072
	v_lshl_add_u64 v[134:135], v[210:211], 0, s[22:23]
	s_mov_b32 m0, s4
	s_nop 0
	global_load_lds_dwordx4 v[134:135], off
	v_lshl_add_u64 v[134:135], v[214:215], 0, s[22:23]
	s_add_i32 m0, s4, 0x2000
	s_nop 0
	global_load_lds_dwordx4 v[134:135], off
	s_barrier
	s_waitcnt lgkmcnt(0)
	v_mfma_f32_16x16x32_bf16 v[38:41], v[234:237], v[102:105], v[38:41]
	v_mfma_f32_16x16x32_bf16 v[162:165], v[238:241], v[114:117], v[38:41]
	v_mfma_f32_16x16x32_bf16 v[38:41], v[226:229], v[118:121], v[42:45]
	v_mfma_f32_16x16x32_bf16 v[150:153], v[230:233], v[130:133], v[38:41]
	v_mfma_f32_16x16x32_bf16 v[38:41], v[234:237], v[118:121], v[46:49]
	v_mfma_f32_16x16x32_bf16 v[134:137], v[226:229], v[102:105], v[166:169]
	v_mfma_f32_16x16x32_bf16 v[146:149], v[238:241], v[130:133], v[38:41]
	v_mfma_f32_16x16x32_bf16 v[38:41], v[226:229], v[178:181], v[54:57]
	v_mfma_f32_16x16x32_bf16 v[166:169], v[230:233], v[114:117], v[134:137]
	v_mfma_f32_16x16x32_bf16 v[134:137], v[230:233], v[190:193], v[38:41]
	v_mfma_f32_16x16x32_bf16 v[38:41], v[234:237], v[178:181], v[58:61]
	v_mfma_f32_16x16x32_bf16 v[130:133], v[238:241], v[190:193], v[38:41]
	v_mfma_f32_16x16x32_bf16 v[38:41], v[226:229], v[200:203], v[62:65]
	v_mfma_f32_16x16x32_bf16 v[118:121], v[230:233], v[222:225], v[38:41]
	v_mfma_f32_16x16x32_bf16 v[38:41], v[234:237], v[200:203], v[66:69]
	v_mfma_f32_16x16x32_bf16 v[114:117], v[238:241], v[222:225], v[38:41]
	s_barrier
	s_mov_b32 m0, s64
	v_lshl_add_u64 v[102:103], v[242:243], 0, s[22:23]
	s_nop 2
	ds_read_b128 v[38:41], v209 offset:49152
	ds_read_b128 v[42:45], v209 offset:50176
	ds_read_b128 v[46:49], v209 offset:51200
	ds_read_b128 v[54:57], v209 offset:52224
	ds_read_b128 v[58:61], v209 offset:53248
	ds_read_b128 v[62:65], v209 offset:54272
	ds_read_b128 v[66:69], v209 offset:55296
	ds_read_b128 v[178:181], v209 offset:56320
	global_load_lds_dwordx4 v[102:103], off
	v_lshl_add_u64 v[102:103], v[244:245], 0, s[22:23]
	s_mov_b32 m0, s65
	s_nop 0
	global_load_lds_dwordx4 v[102:103], off
	s_barrier
	s_waitcnt lgkmcnt(0)
	v_mfma_f32_16x16x32_bf16 v[102:105], v[18:21], v[38:41], v[110:113]
	v_mfma_f32_16x16x32_bf16 v[110:113], v[82:85], v[42:45], v[102:105]
	v_mfma_f32_16x16x32_bf16 v[102:105], v[86:89], v[38:41], v[106:109]
	v_mfma_f32_16x16x32_bf16 v[94:97], v[18:21], v[46:49], v[94:97]
	v_mfma_f32_16x16x32_bf16 v[90:93], v[86:89], v[46:49], v[90:93]
	v_mfma_f32_16x16x32_bf16 v[78:81], v[18:21], v[58:61], v[78:81]
	v_mfma_f32_16x16x32_bf16 v[74:77], v[86:89], v[58:61], v[74:77]
	v_mfma_f32_16x16x32_bf16 v[14:17], v[18:21], v[66:69], v[14:17]
	v_mfma_f32_16x16x32_bf16 v[10:13], v[86:89], v[66:69], v[10:13]
	v_mfma_f32_16x16x32_bf16 v[106:109], v[98:101], v[42:45], v[102:105]
	v_mfma_f32_16x16x32_bf16 v[94:97], v[82:85], v[54:57], v[94:97]
	v_mfma_f32_16x16x32_bf16 v[90:93], v[98:101], v[54:57], v[90:93]
	v_mfma_f32_16x16x32_bf16 v[78:81], v[82:85], v[62:65], v[78:81]
	v_mfma_f32_16x16x32_bf16 v[74:77], v[98:101], v[62:65], v[74:77]
	v_mfma_f32_16x16x32_bf16 v[18:21], v[82:85], v[178:181], v[14:17]
	v_mfma_f32_16x16x32_bf16 v[10:13], v[98:101], v[178:181], v[10:13]
	s_barrier
	s_add_u32 s4, s42, 0x40080
	s_addc_u32 s5, s43, 0
	s_add_i32 s42, s44, s59
	v_lshl_add_u64 v[14:15], s[4:5], 0, v[184:185]
	s_mov_b32 m0, s42
	s_nop 0
	global_load_lds_dwordx4 v[14:15], off
	v_lshl_add_u64 v[14:15], s[4:5], 0, v[182:183]
	s_add_i32 m0, s42, 0x2000
	s_nop 0
	global_load_lds_dwordx4 v[14:15], off
	s_add_i32 s57, s57, 2
	s_add_u32 s55, s55, 0x100
	s_addc_u32 s56, s56, 0
	s_cmp_gt_u32 s57, 13
	s_mov_b64 s[4:5], s[36:37]
	s_waitcnt vmcnt(6)
	s_barrier
	v_mfma_f32_16x16x32_bf16 v[14:17], v[226:229], v[38:41], v[22:25]
	v_mfma_f32_16x16x32_bf16 v[102:105], v[230:233], v[42:45], v[14:17]
	v_mfma_f32_16x16x32_bf16 v[14:17], v[234:237], v[38:41], v[26:29]
	v_mfma_f32_16x16x32_bf16 v[98:101], v[238:241], v[42:45], v[14:17]
	v_mfma_f32_16x16x32_bf16 v[14:17], v[226:229], v[46:49], v[30:33]
	v_mfma_f32_16x16x32_bf16 v[86:89], v[230:233], v[54:57], v[14:17]
	v_mfma_f32_16x16x32_bf16 v[14:17], v[234:237], v[46:49], v[70:73]
	v_mfma_f32_16x16x32_bf16 v[82:85], v[238:241], v[54:57], v[14:17]
	v_mfma_f32_16x16x32_bf16 v[14:17], v[226:229], v[58:61], v[50:53]
	v_mfma_f32_16x16x32_bf16 v[50:53], v[230:233], v[62:65], v[14:17]
	v_mfma_f32_16x16x32_bf16 v[14:17], v[234:237], v[58:61], v[34:37]
	v_mfma_f32_16x16x32_bf16 v[6:9], v[226:229], v[66:69], v[6:9]
	v_mfma_f32_16x16x32_bf16 v[2:5], v[234:237], v[66:69], v[2:5]
	v_mfma_f32_16x16x32_bf16 v[34:37], v[238:241], v[62:65], v[14:17]
	v_mfma_f32_16x16x32_bf16 v[6:9], v[230:233], v[178:181], v[6:9]
	v_mfma_f32_16x16x32_bf16 v[2:5], v[238:241], v[178:181], v[2:5]
	s_barrier
	s_cbranch_scc0 .LBB0_396
	s_setprio 0
	s_lshr_b32 s32, s27, 2
	s_cmp_eq_u32 s32, 0
	s_cbranch_scc1 .Lepi0_seg0
	s_cmp_eq_u32 s32, 1
	s_cbranch_scc1 .Lepi0_seg1
	s_cmp_eq_u32 s32, 2
	s_cbranch_scc1 .Lepi0_seg2
	s_branch .Lepi0_seg3

.LBB0_1098:
	s_add_i32 s76, s76, 1
	s_mov_b64 s[62:63], s[54:55]
	s_mul_i32 s54, s76, s26
	s_add_i32 s64, s54, s2
	s_cmpk_gt_i32 s64, 0x57f
	s_cselect_b64 s[60:61], -1, 0
	s_lshl_b32 s54, s64, 3
	s_and_b32 s54, s54, 56
	s_bfe_u32 s55, s64, 0x30003
	s_or_b32 s77, s54, s55
	s_ashr_i32 s58, s64, 6
	s_lshl_b32 s54, s77, 19
	s_mov_b64 s[36:37], s[56:57]
	s_add_u32 s56, s52, s54
	s_addc_u32 s57, s53, 0
	s_ashr_i32 s59, s58, 31
	s_lshl_b64 s[54:55], s[58:59], 19
	s_add_u32 s54, s4, s54
	s_addc_u32 s55, s5, s55
	s_cmpk_lt_i32 s64, 0x580
	s_cselect_b32 s59, s57, s37
	s_cselect_b32 s78, s56, s36
	s_cselect_b32 s79, s55, s63
	s_cselect_b32 s80, s54, s62
	s_add_u32 s81, s62, 0x100
	s_addc_u32 s82, s63, 0
	s_mov_b32 s83, -2
	s_add_u32 s62, s36, 0x100
	s_addc_u32 s63, s37, 0
	s_add_i32 s84, 0, 0x10000
	v_add_u32_e32 v70, s84, v170
	ds_read_b128 v[58:61], v70
	ds_read_b128 v[62:65], v70 offset:1024
	ds_read_b128 v[66:69], v70 offset:2048
	ds_read_b128 v[70:73], v70 offset:3072
	s_cmp_eq_u32 s83, 12
	s_cselect_b32 s67, s59, s63
	s_cselect_b32 s66, s78, s62
	s_cselect_b32 s65, s79, s82
	s_cselect_b32 s64, s80, s81
	v_lshl_add_u64 v[192:193], s[36:37], 0, v[168:169]
	s_add_i32 m0, s69, 0xc000
	ds_read_b128 v[78:81], v175
	ds_read_b128 v[86:89], v175 offset:1024
	ds_read_b128 v[90:93], v175 offset:2048
	ds_read_b128 v[94:97], v175 offset:3072
	ds_read_b128 v[176:179], v175 offset:4096
	ds_read_b128 v[180:183], v175 offset:5120
	ds_read_b128 v[184:187], v175 offset:6144
	ds_read_b128 v[188:191], v175 offset:7168
	global_load_lds_dwordx4 v[192:193], off
	v_lshl_add_u64 v[192:193], s[36:37], 0, v[166:167]
	s_add_i32 m0, s69, 0xe000
	s_nop 0
	global_load_lds_dwordx4 v[192:193], off
	s_waitcnt lgkmcnt(8)
	s_barrier
	s_waitcnt lgkmcnt(0)
	v_mfma_f32_16x16x32_bf16 v[158:161], v[58:61], v[78:81], 0
	v_mfma_f32_16x16x32_bf16 v[150:153], v[66:69], v[78:81], 0
	v_mfma_f32_16x16x32_bf16 v[142:145], v[58:61], v[90:93], 0
	v_mfma_f32_16x16x32_bf16 v[134:137], v[66:69], v[90:93], 0
	v_mfma_f32_16x16x32_bf16 v[126:129], v[58:61], v[176:179], 0
	v_mfma_f32_16x16x32_bf16 v[118:121], v[66:69], v[176:179], 0
	v_mfma_f32_16x16x32_bf16 v[110:113], v[58:61], v[184:187], 0
	v_mfma_f32_16x16x32_bf16 v[102:105], v[66:69], v[184:187], 0
	v_mfma_f32_16x16x32_bf16 v[158:161], v[62:65], v[86:89], v[158:161]
	v_mfma_f32_16x16x32_bf16 v[150:153], v[70:73], v[86:89], v[150:153]
	v_mfma_f32_16x16x32_bf16 v[142:145], v[62:65], v[94:97], v[142:145]
	v_mfma_f32_16x16x32_bf16 v[134:137], v[70:73], v[94:97], v[134:137]
	v_mfma_f32_16x16x32_bf16 v[126:129], v[62:65], v[180:183], v[126:129]
	v_mfma_f32_16x16x32_bf16 v[118:121], v[70:73], v[180:183], v[118:121]
	v_mfma_f32_16x16x32_bf16 v[110:113], v[62:65], v[188:191], v[110:113]
	v_mfma_f32_16x16x32_bf16 v[102:105], v[70:73], v[188:191], v[102:105]
	s_barrier
	v_mbcnt_lo_u32_b32 v250, -1, 0
	v_mbcnt_hi_u32_b32 v250, -1, v250
	v_lshlrev_b32_e32 v250, 4, v250
	s_lshl_b32 s32, s27, 10
	s_add_u32 s90, s46, s32
	s_addc_u32 s91, s47, 0
	s_add_u32 s92, s48, s32
	s_addc_u32 s93, s49, 0
	s_mov_b32 m0, 0x20840
	s_nop 0
	global_load_lds_dwordx4 v250, s[90:91]
	s_mov_b32 m0, 0x20c40
	s_nop 0
	global_load_lds_dwordx4 v250, s[92:93]
	s_add_i32 s85, 0, 0x14000
	v_add_u32_e32 v192, s85, v170
	s_add_i32 s36, s84, s68
	ds_read_b128 v[200:203], v192
	ds_read_b128 v[204:207], v192 offset:1024
	ds_read_b128 v[208:211], v192 offset:2048
	ds_read_b128 v[222:225], v192 offset:3072
	v_lshl_add_u64 v[192:193], s[64:65], 0, v[164:165]
	s_mov_b32 m0, s36
	v_lshl_add_u64 v[214:215], s[64:65], 0, v[162:163]
	global_load_lds_dwordx4 v[192:193], off
	s_add_i32 m0, s36, 0x2000
	s_nop 0
	global_load_lds_dwordx4 v[214:215], off
	s_barrier
	s_waitcnt lgkmcnt(0)
	v_mfma_f32_16x16x32_bf16 v[154:157], v[200:203], v[78:81], 0
	v_mfma_f32_16x16x32_bf16 v[78:81], v[208:211], v[78:81], 0
	v_mfma_f32_16x16x32_bf16 v[154:157], v[204:207], v[86:89], v[154:157]
	v_mfma_f32_16x16x32_bf16 v[78:81], v[222:225], v[86:89], v[78:81]
	v_mfma_f32_16x16x32_bf16 v[86:89], v[200:203], v[90:93], 0
	v_mfma_f32_16x16x32_bf16 v[90:93], v[208:211], v[90:93], 0
	v_mfma_f32_16x16x32_bf16 v[114:117], v[208:211], v[176:179], 0
	v_mfma_f32_16x16x32_bf16 v[106:109], v[200:203], v[184:187], 0
	v_mfma_f32_16x16x32_bf16 v[98:101], v[208:211], v[184:187], 0
	v_mfma_f32_16x16x32_bf16 v[86:89], v[204:207], v[94:97], v[86:89]
	v_mfma_f32_16x16x32_bf16 v[90:93], v[222:225], v[94:97], v[90:93]
	v_mfma_f32_16x16x32_bf16 v[94:97], v[200:203], v[176:179], 0
	v_mfma_f32_16x16x32_bf16 v[114:117], v[222:225], v[180:183], v[114:117]
	v_mfma_f32_16x16x32_bf16 v[106:109], v[204:207], v[188:191], v[106:109]
	v_mfma_f32_16x16x32_bf16 v[98:101], v[222:225], v[188:191], v[98:101]
	v_mfma_f32_16x16x32_bf16 v[94:97], v[204:207], v[180:183], v[94:97]
	s_barrier
	s_mov_b32 m0, s69
	v_lshl_add_u64 v[234:235], s[66:67], 0, v[164:165]
	ds_read_b128 v[122:125], v175 offset:16384
	ds_read_b128 v[130:133], v175 offset:17408
	ds_read_b128 v[138:141], v175 offset:18432
	ds_read_b128 v[146:149], v175 offset:19456
	ds_read_b128 v[176:179], v175 offset:20480
	ds_read_b128 v[180:183], v175 offset:21504
	ds_read_b128 v[184:187], v175 offset:22528
	ds_read_b128 v[188:191], v175 offset:23552
	global_load_lds_dwordx4 v[234:235], off
	v_lshl_add_u64 v[236:237], s[66:67], 0, v[162:163]
	s_mov_b32 m0, s70
	s_nop 0
	global_load_lds_dwordx4 v[236:237], off
	s_barrier
	s_waitcnt lgkmcnt(0)
	v_mfma_f32_16x16x32_bf16 v[82:85], v[58:61], v[122:125], 0
	v_mfma_f32_16x16x32_bf16 v[54:57], v[66:69], v[122:125], 0
	v_mfma_f32_16x16x32_bf16 v[46:49], v[58:61], v[138:141], 0
	v_mfma_f32_16x16x32_bf16 v[38:41], v[66:69], v[138:141], 0
	v_mfma_f32_16x16x32_bf16 v[30:33], v[58:61], v[176:179], 0
	v_mfma_f32_16x16x32_bf16 v[22:25], v[66:69], v[176:179], 0
	v_mfma_f32_16x16x32_bf16 v[14:17], v[58:61], v[184:187], 0
	v_mfma_f32_16x16x32_bf16 v[6:9], v[66:69], v[184:187], 0
	v_mfma_f32_16x16x32_bf16 v[82:85], v[62:65], v[130:133], v[82:85]
	v_mfma_f32_16x16x32_bf16 v[54:57], v[70:73], v[130:133], v[54:57]
	v_mfma_f32_16x16x32_bf16 v[46:49], v[62:65], v[146:149], v[46:49]
	v_mfma_f32_16x16x32_bf16 v[38:41], v[70:73], v[146:149], v[38:41]
	v_mfma_f32_16x16x32_bf16 v[30:33], v[62:65], v[180:183], v[30:33]
	v_mfma_f32_16x16x32_bf16 v[22:25], v[70:73], v[180:183], v[22:25]
	v_mfma_f32_16x16x32_bf16 v[14:17], v[62:65], v[188:191], v[14:17]
	v_mfma_f32_16x16x32_bf16 v[6:9], v[70:73], v[188:191], v[6:9]
	s_barrier
	s_add_u32 s36, s64, 0x40000
	s_addc_u32 s37, s65, 0
	s_add_i32 s84, s85, s68
	v_lshl_add_u64 v[58:59], s[36:37], 0, v[164:165]
	s_mov_b32 m0, s84
	s_nop 0
	global_load_lds_dwordx4 v[58:59], off
	v_lshl_add_u64 v[58:59], s[36:37], 0, v[162:163]
	s_add_i32 m0, s84, 0x2000
	s_nop 0
	global_load_lds_dwordx4 v[58:59], off
	s_waitcnt vmcnt(6)
	s_barrier
	v_mfma_f32_16x16x32_bf16 v[50:53], v[208:211], v[122:125], 0
	v_mfma_f32_16x16x32_bf16 v[42:45], v[200:203], v[138:141], 0
	v_mfma_f32_16x16x32_bf16 v[34:37], v[208:211], v[138:141], 0
	v_mfma_f32_16x16x32_bf16 v[26:29], v[200:203], v[176:179], 0
	v_mfma_f32_16x16x32_bf16 v[18:21], v[208:211], v[176:179], 0
	v_mfma_f32_16x16x32_bf16 v[10:13], v[200:203], v[184:187], 0
	v_mfma_f32_16x16x32_bf16 v[2:5], v[208:211], v[184:187], 0
	v_mfma_f32_16x16x32_bf16 v[58:61], v[200:203], v[122:125], 0
	v_mfma_f32_16x16x32_bf16 v[50:53], v[222:225], v[130:133], v[50:53]
	v_mfma_f32_16x16x32_bf16 v[42:45], v[204:207], v[146:149], v[42:45]
	v_mfma_f32_16x16x32_bf16 v[34:37], v[222:225], v[146:149], v[34:37]
	v_mfma_f32_16x16x32_bf16 v[26:29], v[204:207], v[180:183], v[26:29]
	v_mfma_f32_16x16x32_bf16 v[18:21], v[222:225], v[180:183], v[18:21]
	v_mfma_f32_16x16x32_bf16 v[10:13], v[204:207], v[188:191], v[10:13]
	v_mfma_f32_16x16x32_bf16 v[2:5], v[222:225], v[188:191], v[2:5]
	v_mfma_f32_16x16x32_bf16 v[58:61], v[204:207], v[130:133], v[58:61]
	s_barrier
	s_add_i32 s84, 0, 0x18000
	v_add_u32_e32 v74, s84, v170
	ds_read_b128 v[62:65], v74
	ds_read_b128 v[66:69], v74 offset:1024
	ds_read_b128 v[70:73], v74 offset:2048
	ds_read_b128 v[74:77], v74 offset:3072
	s_add_u32 s36, s66, 0x40000
	s_addc_u32 s37, s67, 0
	s_mov_b32 m0, s71
	v_lshl_add_u64 v[138:139], s[36:37], 0, v[164:165]
	ds_read_b128 v[122:125], v175 offset:32768
	ds_read_b128 v[130:133], v175 offset:33792
	ds_read_b128 v[176:179], v175 offset:34816
	ds_read_b128 v[180:183], v175 offset:35840
	ds_read_b128 v[184:187], v175 offset:36864
	ds_read_b128 v[188:191], v175 offset:37888
	ds_read_b128 v[200:203], v175 offset:38912
	ds_read_b128 v[204:207], v175 offset:39936
	global_load_lds_dwordx4 v[138:139], off
	v_lshl_add_u64 v[138:139], s[36:37], 0, v[162:163]
	s_mov_b32 m0, s72
	s_nop 0
	global_load_lds_dwordx4 v[138:139], off
	s_waitcnt lgkmcnt(8)
	s_barrier
	s_waitcnt lgkmcnt(0)
	v_mfma_f32_16x16x32_bf16 v[138:141], v[62:65], v[122:125], v[158:161]
	v_mfma_f32_16x16x32_bf16 v[158:161], v[66:69], v[130:133], v[138:141]
	v_mfma_f32_16x16x32_bf16 v[138:141], v[70:73], v[122:125], v[150:153]
	v_mfma_f32_16x16x32_bf16 v[150:153], v[74:77], v[130:133], v[138:141]
	v_mfma_f32_16x16x32_bf16 v[138:141], v[62:65], v[176:179], v[142:145]
	v_mfma_f32_16x16x32_bf16 v[134:137], v[70:73], v[176:179], v[134:137]
	v_mfma_f32_16x16x32_bf16 v[126:129], v[62:65], v[184:187], v[126:129]
	v_mfma_f32_16x16x32_bf16 v[118:121], v[70:73], v[184:187], v[118:121]
	v_mfma_f32_16x16x32_bf16 v[110:113], v[62:65], v[200:203], v[110:113]
	v_mfma_f32_16x16x32_bf16 v[102:105], v[70:73], v[200:203], v[102:105]
	v_mfma_f32_16x16x32_bf16 v[142:145], v[66:69], v[180:183], v[138:141]
	v_mfma_f32_16x16x32_bf16 v[134:137], v[74:77], v[180:183], v[134:137]
	v_mfma_f32_16x16x32_bf16 v[126:129], v[66:69], v[188:191], v[126:129]
	v_mfma_f32_16x16x32_bf16 v[118:121], v[74:77], v[188:191], v[118:121]
	v_mfma_f32_16x16x32_bf16 v[110:113], v[66:69], v[204:207], v[110:113]
	v_mfma_f32_16x16x32_bf16 v[102:105], v[74:77], v[204:207], v[102:105]
	s_barrier
	s_add_i32 s66, 0, 0x1c000
	v_add_u32_e32 v138, s66, v170
	s_add_i32 s36, s84, s68
	ds_read_b128 v[208:211], v138
	ds_read_b128 v[222:225], v138 offset:1024
	ds_read_b128 v[226:229], v138 offset:2048
	ds_read_b128 v[230:233], v138 offset:3072
	v_lshl_add_u64 v[138:139], v[192:193], 0, s[22:23]
	s_mov_b32 m0, s36
	s_nop 0
	global_load_lds_dwordx4 v[138:139], off
	v_lshl_add_u64 v[138:139], v[214:215], 0, s[22:23]
	s_add_i32 m0, s36, 0x2000
	s_nop 0
	global_load_lds_dwordx4 v[138:139], off
	s_barrier
	s_waitcnt lgkmcnt(0)
	v_mfma_f32_16x16x32_bf16 v[78:81], v[226:229], v[122:125], v[78:81]
	v_mfma_f32_16x16x32_bf16 v[138:141], v[208:211], v[122:125], v[154:157]
	v_mfma_f32_16x16x32_bf16 v[146:149], v[230:233], v[130:133], v[78:81]
	v_mfma_f32_16x16x32_bf16 v[78:81], v[208:211], v[176:179], v[86:89]
	v_mfma_f32_16x16x32_bf16 v[154:157], v[222:225], v[130:133], v[138:141]
	v_mfma_f32_16x16x32_bf16 v[138:141], v[222:225], v[180:183], v[78:81]
	v_mfma_f32_16x16x32_bf16 v[78:81], v[226:229], v[176:179], v[90:93]
	v_mfma_f32_16x16x32_bf16 v[130:133], v[230:233], v[180:183], v[78:81]
	v_mfma_f32_16x16x32_bf16 v[78:81], v[208:211], v[184:187], v[94:97]
	v_mfma_f32_16x16x32_bf16 v[122:125], v[222:225], v[188:191], v[78:81]
	v_mfma_f32_16x16x32_bf16 v[78:81], v[226:229], v[184:187], v[114:117]
	v_mfma_f32_16x16x32_bf16 v[114:117], v[230:233], v[188:191], v[78:81]
	v_mfma_f32_16x16x32_bf16 v[78:81], v[208:211], v[200:203], v[106:109]
	v_mfma_f32_16x16x32_bf16 v[106:109], v[222:225], v[204:207], v[78:81]
	v_mfma_f32_16x16x32_bf16 v[78:81], v[226:229], v[200:203], v[98:101]
	v_mfma_f32_16x16x32_bf16 v[98:101], v[230:233], v[204:207], v[78:81]
	s_barrier
	s_mov_b32 m0, s73
	v_lshl_add_u64 v[192:193], v[234:235], 0, s[22:23]
	s_nop 2
	ds_read_b128 v[78:81], v175 offset:49152
	ds_read_b128 v[86:89], v175 offset:50176
	ds_read_b128 v[90:93], v175 offset:51200
	ds_read_b128 v[94:97], v175 offset:52224
	ds_read_b128 v[176:179], v175 offset:53248
	ds_read_b128 v[180:183], v175 offset:54272
	ds_read_b128 v[184:187], v175 offset:55296
	ds_read_b128 v[188:191], v175 offset:56320
	global_load_lds_dwordx4 v[192:193], off
	v_lshl_add_u64 v[192:193], v[236:237], 0, s[22:23]
	s_mov_b32 m0, s75
	s_nop 0
	global_load_lds_dwordx4 v[192:193], off
	s_barrier
	s_waitcnt lgkmcnt(0)
	v_mfma_f32_16x16x32_bf16 v[82:85], v[62:65], v[78:81], v[82:85]
	v_mfma_f32_16x16x32_bf16 v[54:57], v[70:73], v[78:81], v[54:57]
	v_mfma_f32_16x16x32_bf16 v[46:49], v[62:65], v[90:93], v[46:49]
	v_mfma_f32_16x16x32_bf16 v[38:41], v[70:73], v[90:93], v[38:41]
	v_mfma_f32_16x16x32_bf16 v[30:33], v[62:65], v[176:179], v[30:33]
	v_mfma_f32_16x16x32_bf16 v[22:25], v[70:73], v[176:179], v[22:25]
	v_mfma_f32_16x16x32_bf16 v[14:17], v[62:65], v[184:187], v[14:17]
	v_mfma_f32_16x16x32_bf16 v[6:9], v[70:73], v[184:187], v[6:9]
	v_mfma_f32_16x16x32_bf16 v[82:85], v[66:69], v[86:89], v[82:85]
	v_mfma_f32_16x16x32_bf16 v[54:57], v[74:77], v[86:89], v[54:57]
	v_mfma_f32_16x16x32_bf16 v[46:49], v[66:69], v[94:97], v[46:49]
	v_mfma_f32_16x16x32_bf16 v[38:41], v[74:77], v[94:97], v[38:41]
	v_mfma_f32_16x16x32_bf16 v[30:33], v[66:69], v[180:183], v[30:33]
	v_mfma_f32_16x16x32_bf16 v[22:25], v[74:77], v[180:183], v[22:25]
	v_mfma_f32_16x16x32_bf16 v[14:17], v[66:69], v[188:191], v[14:17]
	v_mfma_f32_16x16x32_bf16 v[6:9], v[74:77], v[188:191], v[6:9]
	s_barrier
	s_add_u32 s36, s64, 0x40080
	s_addc_u32 s37, s65, 0
	s_add_i32 s64, s66, s68
	v_lshl_add_u64 v[62:63], s[36:37], 0, v[164:165]
	s_mov_b32 m0, s64
	s_nop 0
	global_load_lds_dwordx4 v[62:63], off
	v_lshl_add_u64 v[62:63], s[36:37], 0, v[162:163]
	s_add_i32 m0, s64, 0x2000
	s_nop 0
	global_load_lds_dwordx4 v[62:63], off
	s_add_i32 s83, s83, 2
	s_add_u32 s81, s81, 0x100
	s_addc_u32 s82, s82, 0
	s_cmp_gt_u32 s83, 13
	s_mov_b64 s[36:37], s[62:63]
	s_waitcnt vmcnt(6)
	s_barrier
	v_mfma_f32_16x16x32_bf16 v[58:61], v[208:211], v[78:81], v[58:61]
	v_mfma_f32_16x16x32_bf16 v[50:53], v[226:229], v[78:81], v[50:53]
	v_mfma_f32_16x16x32_bf16 v[42:45], v[208:211], v[90:93], v[42:45]
	v_mfma_f32_16x16x32_bf16 v[34:37], v[226:229], v[90:93], v[34:37]
	v_mfma_f32_16x16x32_bf16 v[26:29], v[208:211], v[176:179], v[26:29]
	v_mfma_f32_16x16x32_bf16 v[18:21], v[226:229], v[176:179], v[18:21]
	v_mfma_f32_16x16x32_bf16 v[10:13], v[208:211], v[184:187], v[10:13]
	v_mfma_f32_16x16x32_bf16 v[2:5], v[226:229], v[184:187], v[2:5]
	v_mfma_f32_16x16x32_bf16 v[74:77], v[222:225], v[86:89], v[58:61]
	v_mfma_f32_16x16x32_bf16 v[50:53], v[230:233], v[86:89], v[50:53]
	v_mfma_f32_16x16x32_bf16 v[42:45], v[222:225], v[94:97], v[42:45]
	v_mfma_f32_16x16x32_bf16 v[34:37], v[230:233], v[94:97], v[34:37]
	v_mfma_f32_16x16x32_bf16 v[26:29], v[222:225], v[180:183], v[26:29]
	v_mfma_f32_16x16x32_bf16 v[18:21], v[230:233], v[180:183], v[18:21]
	v_mfma_f32_16x16x32_bf16 v[10:13], v[222:225], v[188:191], v[10:13]
	v_mfma_f32_16x16x32_bf16 v[2:5], v[230:233], v[188:191], v[2:5]
	s_barrier
.LBB0_1099:
	s_add_u32 s62, s36, 0x100
	s_addc_u32 s63, s37, 0
	s_add_i32 s84, 0, 0x10000
	v_add_u32_e32 v70, s84, v170
	ds_read_b128 v[58:61], v70
	ds_read_b128 v[62:65], v70 offset:1024
	ds_read_b128 v[66:69], v70 offset:2048
	ds_read_b128 v[70:73], v70 offset:3072
	s_cmp_eq_u32 s83, 12
	s_cselect_b32 s67, s59, s63
	s_cselect_b32 s66, s78, s62
	s_cselect_b32 s65, s79, s82
	s_cselect_b32 s64, s80, s81
	v_lshl_add_u64 v[192:193], s[36:37], 0, v[168:169]
	s_add_i32 m0, s69, 0xc000
	ds_read_b128 v[78:81], v175
	ds_read_b128 v[86:89], v175 offset:1024
	ds_read_b128 v[90:93], v175 offset:2048
	ds_read_b128 v[94:97], v175 offset:3072
	ds_read_b128 v[176:179], v175 offset:4096
	ds_read_b128 v[180:183], v175 offset:5120
	ds_read_b128 v[184:187], v175 offset:6144
	ds_read_b128 v[188:191], v175 offset:7168
	global_load_lds_dwordx4 v[192:193], off
	v_lshl_add_u64 v[192:193], s[36:37], 0, v[166:167]
	s_add_i32 m0, s69, 0xe000
	s_nop 0
	global_load_lds_dwordx4 v[192:193], off
	s_waitcnt lgkmcnt(8)
	s_barrier
	s_waitcnt lgkmcnt(0)
	v_mfma_f32_16x16x32_bf16 v[158:161], v[58:61], v[78:81], v[158:161]
	v_mfma_f32_16x16x32_bf16 v[150:153], v[66:69], v[78:81], v[150:153]
	v_mfma_f32_16x16x32_bf16 v[142:145], v[58:61], v[90:93], v[142:145]
	v_mfma_f32_16x16x32_bf16 v[134:137], v[66:69], v[90:93], v[134:137]
	v_mfma_f32_16x16x32_bf16 v[126:129], v[58:61], v[176:179], v[126:129]
	v_mfma_f32_16x16x32_bf16 v[118:121], v[66:69], v[176:179], v[118:121]
	v_mfma_f32_16x16x32_bf16 v[110:113], v[58:61], v[184:187], v[110:113]
	v_mfma_f32_16x16x32_bf16 v[102:105], v[66:69], v[184:187], v[102:105]
	v_mfma_f32_16x16x32_bf16 v[158:161], v[62:65], v[86:89], v[158:161]
	v_mfma_f32_16x16x32_bf16 v[150:153], v[70:73], v[86:89], v[150:153]
	v_mfma_f32_16x16x32_bf16 v[142:145], v[62:65], v[94:97], v[142:145]
	v_mfma_f32_16x16x32_bf16 v[134:137], v[70:73], v[94:97], v[134:137]
	v_mfma_f32_16x16x32_bf16 v[126:129], v[62:65], v[180:183], v[126:129]
	v_mfma_f32_16x16x32_bf16 v[118:121], v[70:73], v[180:183], v[118:121]
	v_mfma_f32_16x16x32_bf16 v[110:113], v[62:65], v[188:191], v[110:113]
	v_mfma_f32_16x16x32_bf16 v[102:105], v[70:73], v[188:191], v[102:105]
	s_barrier
	s_add_i32 s85, 0, 0x14000
	v_add_u32_e32 v192, s85, v170
	s_add_i32 s36, s84, s68
	ds_read_b128 v[200:203], v192
	ds_read_b128 v[204:207], v192 offset:1024
	ds_read_b128 v[208:211], v192 offset:2048
	ds_read_b128 v[222:225], v192 offset:3072
	v_lshl_add_u64 v[192:193], s[64:65], 0, v[164:165]
	s_mov_b32 m0, s36
	v_lshl_add_u64 v[214:215], s[64:65], 0, v[162:163]
	global_load_lds_dwordx4 v[192:193], off
	s_add_i32 m0, s36, 0x2000
	s_nop 0
	global_load_lds_dwordx4 v[214:215], off
	s_barrier
	s_waitcnt lgkmcnt(0)
	v_mfma_f32_16x16x32_bf16 v[154:157], v[200:203], v[78:81], v[154:157]
	v_mfma_f32_16x16x32_bf16 v[78:81], v[208:211], v[78:81], v[146:149]
	v_mfma_f32_16x16x32_bf16 v[154:157], v[204:207], v[86:89], v[154:157]
	v_mfma_f32_16x16x32_bf16 v[78:81], v[222:225], v[86:89], v[78:81]
	v_mfma_f32_16x16x32_bf16 v[86:89], v[200:203], v[90:93], v[138:141]
	v_mfma_f32_16x16x32_bf16 v[90:93], v[208:211], v[90:93], v[130:133]
	v_mfma_f32_16x16x32_bf16 v[114:117], v[208:211], v[176:179], v[114:117]
	v_mfma_f32_16x16x32_bf16 v[106:109], v[200:203], v[184:187], v[106:109]
	v_mfma_f32_16x16x32_bf16 v[98:101], v[208:211], v[184:187], v[98:101]
	v_mfma_f32_16x16x32_bf16 v[86:89], v[204:207], v[94:97], v[86:89]
	v_mfma_f32_16x16x32_bf16 v[90:93], v[222:225], v[94:97], v[90:93]
	v_mfma_f32_16x16x32_bf16 v[94:97], v[200:203], v[176:179], v[122:125]
	v_mfma_f32_16x16x32_bf16 v[114:117], v[222:225], v[180:183], v[114:117]
	v_mfma_f32_16x16x32_bf16 v[106:109], v[204:207], v[188:191], v[106:109]
	v_mfma_f32_16x16x32_bf16 v[98:101], v[222:225], v[188:191], v[98:101]
	v_mfma_f32_16x16x32_bf16 v[94:97], v[204:207], v[180:183], v[94:97]
	s_barrier
	s_mov_b32 m0, s69
	v_lshl_add_u64 v[234:235], s[66:67], 0, v[164:165]
	ds_read_b128 v[122:125], v175 offset:16384
	ds_read_b128 v[130:133], v175 offset:17408
	ds_read_b128 v[138:141], v175 offset:18432
	ds_read_b128 v[146:149], v175 offset:19456
	ds_read_b128 v[176:179], v175 offset:20480
	ds_read_b128 v[180:183], v175 offset:21504
	ds_read_b128 v[184:187], v175 offset:22528
	ds_read_b128 v[188:191], v175 offset:23552
	global_load_lds_dwordx4 v[234:235], off
	v_lshl_add_u64 v[236:237], s[66:67], 0, v[162:163]
	s_mov_b32 m0, s70
	s_nop 0
	global_load_lds_dwordx4 v[236:237], off
	s_barrier
	s_waitcnt lgkmcnt(0)
	v_mfma_f32_16x16x32_bf16 v[82:85], v[58:61], v[122:125], v[82:85]
	v_mfma_f32_16x16x32_bf16 v[54:57], v[66:69], v[122:125], v[54:57]
	v_mfma_f32_16x16x32_bf16 v[46:49], v[58:61], v[138:141], v[46:49]
	v_mfma_f32_16x16x32_bf16 v[38:41], v[66:69], v[138:141], v[38:41]
	v_mfma_f32_16x16x32_bf16 v[30:33], v[58:61], v[176:179], v[30:33]
	v_mfma_f32_16x16x32_bf16 v[22:25], v[66:69], v[176:179], v[22:25]
	v_mfma_f32_16x16x32_bf16 v[14:17], v[58:61], v[184:187], v[14:17]
	v_mfma_f32_16x16x32_bf16 v[6:9], v[66:69], v[184:187], v[6:9]
	v_mfma_f32_16x16x32_bf16 v[82:85], v[62:65], v[130:133], v[82:85]
	v_mfma_f32_16x16x32_bf16 v[54:57], v[70:73], v[130:133], v[54:57]
	v_mfma_f32_16x16x32_bf16 v[46:49], v[62:65], v[146:149], v[46:49]
	v_mfma_f32_16x16x32_bf16 v[38:41], v[70:73], v[146:149], v[38:41]
	v_mfma_f32_16x16x32_bf16 v[30:33], v[62:65], v[180:183], v[30:33]
	v_mfma_f32_16x16x32_bf16 v[22:25], v[70:73], v[180:183], v[22:25]
	v_mfma_f32_16x16x32_bf16 v[14:17], v[62:65], v[188:191], v[14:17]
	v_mfma_f32_16x16x32_bf16 v[6:9], v[70:73], v[188:191], v[6:9]
	s_barrier
	s_add_u32 s36, s64, 0x40000
	s_addc_u32 s37, s65, 0
	s_add_i32 s84, s85, s68
	v_lshl_add_u64 v[58:59], s[36:37], 0, v[164:165]
	s_mov_b32 m0, s84
	s_nop 0
	global_load_lds_dwordx4 v[58:59], off
	v_lshl_add_u64 v[58:59], s[36:37], 0, v[162:163]
	s_add_i32 m0, s84, 0x2000
	s_nop 0
	global_load_lds_dwordx4 v[58:59], off
	s_waitcnt vmcnt(6)
	s_barrier
	v_mfma_f32_16x16x32_bf16 v[50:53], v[208:211], v[122:125], v[50:53]
	v_mfma_f32_16x16x32_bf16 v[42:45], v[200:203], v[138:141], v[42:45]
	v_mfma_f32_16x16x32_bf16 v[34:37], v[208:211], v[138:141], v[34:37]
	v_mfma_f32_16x16x32_bf16 v[26:29], v[200:203], v[176:179], v[26:29]
	v_mfma_f32_16x16x32_bf16 v[18:21], v[208:211], v[176:179], v[18:21]
	v_mfma_f32_16x16x32_bf16 v[10:13], v[200:203], v[184:187], v[10:13]
	v_mfma_f32_16x16x32_bf16 v[2:5], v[208:211], v[184:187], v[2:5]
	v_mfma_f32_16x16x32_bf16 v[58:61], v[200:203], v[122:125], v[74:77]
	v_mfma_f32_16x16x32_bf16 v[50:53], v[222:225], v[130:133], v[50:53]
	v_mfma_f32_16x16x32_bf16 v[42:45], v[204:207], v[146:149], v[42:45]
	v_mfma_f32_16x16x32_bf16 v[34:37], v[222:225], v[146:149], v[34:37]
	v_mfma_f32_16x16x32_bf16 v[26:29], v[204:207], v[180:183], v[26:29]
	v_mfma_f32_16x16x32_bf16 v[18:21], v[222:225], v[180:183], v[18:21]
	v_mfma_f32_16x16x32_bf16 v[10:13], v[204:207], v[188:191], v[10:13]
	v_mfma_f32_16x16x32_bf16 v[2:5], v[222:225], v[188:191], v[2:5]
	v_mfma_f32_16x16x32_bf16 v[58:61], v[204:207], v[130:133], v[58:61]
	s_barrier
	s_add_i32 s84, 0, 0x18000
	v_add_u32_e32 v74, s84, v170
	ds_read_b128 v[62:65], v74
	ds_read_b128 v[66:69], v74 offset:1024
	ds_read_b128 v[70:73], v74 offset:2048
	ds_read_b128 v[74:77], v74 offset:3072
	s_add_u32 s36, s66, 0x40000
	s_addc_u32 s37, s67, 0
	s_mov_b32 m0, s71
	v_lshl_add_u64 v[138:139], s[36:37], 0, v[164:165]
	ds_read_b128 v[122:125], v175 offset:32768
	ds_read_b128 v[130:133], v175 offset:33792
	ds_read_b128 v[176:179], v175 offset:34816
	ds_read_b128 v[180:183], v175 offset:35840
	ds_read_b128 v[184:187], v175 offset:36864
	ds_read_b128 v[188:191], v175 offset:37888
	ds_read_b128 v[200:203], v175 offset:38912
	ds_read_b128 v[204:207], v175 offset:39936
	global_load_lds_dwordx4 v[138:139], off
	v_lshl_add_u64 v[138:139], s[36:37], 0, v[162:163]
	s_mov_b32 m0, s72
	s_nop 0
	global_load_lds_dwordx4 v[138:139], off
	s_waitcnt lgkmcnt(8)
	s_barrier
	s_waitcnt lgkmcnt(0)
	v_mfma_f32_16x16x32_bf16 v[138:141], v[62:65], v[122:125], v[158:161]
	v_mfma_f32_16x16x32_bf16 v[158:161], v[66:69], v[130:133], v[138:141]
	v_mfma_f32_16x16x32_bf16 v[138:141], v[70:73], v[122:125], v[150:153]
	v_mfma_f32_16x16x32_bf16 v[150:153], v[74:77], v[130:133], v[138:141]
	v_mfma_f32_16x16x32_bf16 v[138:141], v[62:65], v[176:179], v[142:145]
	v_mfma_f32_16x16x32_bf16 v[134:137], v[70:73], v[176:179], v[134:137]
	v_mfma_f32_16x16x32_bf16 v[126:129], v[62:65], v[184:187], v[126:129]
	v_mfma_f32_16x16x32_bf16 v[118:121], v[70:73], v[184:187], v[118:121]
	v_mfma_f32_16x16x32_bf16 v[110:113], v[62:65], v[200:203], v[110:113]
	v_mfma_f32_16x16x32_bf16 v[102:105], v[70:73], v[200:203], v[102:105]
	v_mfma_f32_16x16x32_bf16 v[142:145], v[66:69], v[180:183], v[138:141]
	v_mfma_f32_16x16x32_bf16 v[134:137], v[74:77], v[180:183], v[134:137]
	v_mfma_f32_16x16x32_bf16 v[126:129], v[66:69], v[188:191], v[126:129]
	v_mfma_f32_16x16x32_bf16 v[118:121], v[74:77], v[188:191], v[118:121]
	v_mfma_f32_16x16x32_bf16 v[110:113], v[66:69], v[204:207], v[110:113]
	v_mfma_f32_16x16x32_bf16 v[102:105], v[74:77], v[204:207], v[102:105]
	s_barrier
	s_add_i32 s66, 0, 0x1c000
	v_add_u32_e32 v138, s66, v170
	s_add_i32 s36, s84, s68
	ds_read_b128 v[208:211], v138
	ds_read_b128 v[222:225], v138 offset:1024
	ds_read_b128 v[226:229], v138 offset:2048
	ds_read_b128 v[230:233], v138 offset:3072
	v_lshl_add_u64 v[138:139], v[192:193], 0, s[22:23]
	s_mov_b32 m0, s36
	s_nop 0
	global_load_lds_dwordx4 v[138:139], off
	v_lshl_add_u64 v[138:139], v[214:215], 0, s[22:23]
	s_add_i32 m0, s36, 0x2000
	s_nop 0
	global_load_lds_dwordx4 v[138:139], off
	s_barrier
	s_waitcnt lgkmcnt(0)
	v_mfma_f32_16x16x32_bf16 v[78:81], v[226:229], v[122:125], v[78:81]
	v_mfma_f32_16x16x32_bf16 v[138:141], v[208:211], v[122:125], v[154:157]
	v_mfma_f32_16x16x32_bf16 v[146:149], v[230:233], v[130:133], v[78:81]
	v_mfma_f32_16x16x32_bf16 v[78:81], v[208:211], v[176:179], v[86:89]
	v_mfma_f32_16x16x32_bf16 v[154:157], v[222:225], v[130:133], v[138:141]
	v_mfma_f32_16x16x32_bf16 v[138:141], v[222:225], v[180:183], v[78:81]
	v_mfma_f32_16x16x32_bf16 v[78:81], v[226:229], v[176:179], v[90:93]
	v_mfma_f32_16x16x32_bf16 v[130:133], v[230:233], v[180:183], v[78:81]
	v_mfma_f32_16x16x32_bf16 v[78:81], v[208:211], v[184:187], v[94:97]
	v_mfma_f32_16x16x32_bf16 v[122:125], v[222:225], v[188:191], v[78:81]
	v_mfma_f32_16x16x32_bf16 v[78:81], v[226:229], v[184:187], v[114:117]
	v_mfma_f32_16x16x32_bf16 v[114:117], v[230:233], v[188:191], v[78:81]
	v_mfma_f32_16x16x32_bf16 v[78:81], v[208:211], v[200:203], v[106:109]
	v_mfma_f32_16x16x32_bf16 v[106:109], v[222:225], v[204:207], v[78:81]
	v_mfma_f32_16x16x32_bf16 v[78:81], v[226:229], v[200:203], v[98:101]
	v_mfma_f32_16x16x32_bf16 v[98:101], v[230:233], v[204:207], v[78:81]
	s_barrier
	s_mov_b32 m0, s73
	v_lshl_add_u64 v[192:193], v[234:235], 0, s[22:23]
	s_nop 2
	ds_read_b128 v[78:81], v175 offset:49152
	ds_read_b128 v[86:89], v175 offset:50176
	ds_read_b128 v[90:93], v175 offset:51200
	ds_read_b128 v[94:97], v175 offset:52224
	ds_read_b128 v[176:179], v175 offset:53248
	ds_read_b128 v[180:183], v175 offset:54272
	ds_read_b128 v[184:187], v175 offset:55296
	ds_read_b128 v[188:191], v175 offset:56320
	global_load_lds_dwordx4 v[192:193], off
	v_lshl_add_u64 v[192:193], v[236:237], 0, s[22:23]
	s_mov_b32 m0, s75
	s_nop 0
	global_load_lds_dwordx4 v[192:193], off
	s_barrier
	s_waitcnt lgkmcnt(0)
	v_mfma_f32_16x16x32_bf16 v[82:85], v[62:65], v[78:81], v[82:85]
	v_mfma_f32_16x16x32_bf16 v[54:57], v[70:73], v[78:81], v[54:57]
	v_mfma_f32_16x16x32_bf16 v[46:49], v[62:65], v[90:93], v[46:49]
	v_mfma_f32_16x16x32_bf16 v[38:41], v[70:73], v[90:93], v[38:41]
	v_mfma_f32_16x16x32_bf16 v[30:33], v[62:65], v[176:179], v[30:33]
	v_mfma_f32_16x16x32_bf16 v[22:25], v[70:73], v[176:179], v[22:25]
	v_mfma_f32_16x16x32_bf16 v[14:17], v[62:65], v[184:187], v[14:17]
	v_mfma_f32_16x16x32_bf16 v[6:9], v[70:73], v[184:187], v[6:9]
	v_mfma_f32_16x16x32_bf16 v[82:85], v[66:69], v[86:89], v[82:85]
	v_mfma_f32_16x16x32_bf16 v[54:57], v[74:77], v[86:89], v[54:57]
	v_mfma_f32_16x16x32_bf16 v[46:49], v[66:69], v[94:97], v[46:49]
	v_mfma_f32_16x16x32_bf16 v[38:41], v[74:77], v[94:97], v[38:41]
	v_mfma_f32_16x16x32_bf16 v[30:33], v[66:69], v[180:183], v[30:33]
	v_mfma_f32_16x16x32_bf16 v[22:25], v[74:77], v[180:183], v[22:25]
	v_mfma_f32_16x16x32_bf16 v[14:17], v[66:69], v[188:191], v[14:17]
	v_mfma_f32_16x16x32_bf16 v[6:9], v[74:77], v[188:191], v[6:9]
	s_barrier
	s_add_u32 s36, s64, 0x40080
	s_addc_u32 s37, s65, 0
	s_add_i32 s64, s66, s68
	v_lshl_add_u64 v[62:63], s[36:37], 0, v[164:165]
	s_mov_b32 m0, s64
	s_nop 0
	global_load_lds_dwordx4 v[62:63], off
	v_lshl_add_u64 v[62:63], s[36:37], 0, v[162:163]
	s_add_i32 m0, s64, 0x2000
	s_nop 0
	global_load_lds_dwordx4 v[62:63], off
	s_add_i32 s83, s83, 2
	s_add_u32 s81, s81, 0x100
	s_addc_u32 s82, s82, 0
	s_cmp_gt_u32 s83, 13
	s_mov_b64 s[36:37], s[62:63]
	s_waitcnt vmcnt(6)
	s_barrier
	v_mfma_f32_16x16x32_bf16 v[58:61], v[208:211], v[78:81], v[58:61]
	v_mfma_f32_16x16x32_bf16 v[50:53], v[226:229], v[78:81], v[50:53]
	v_mfma_f32_16x16x32_bf16 v[42:45], v[208:211], v[90:93], v[42:45]
	v_mfma_f32_16x16x32_bf16 v[34:37], v[226:229], v[90:93], v[34:37]
	v_mfma_f32_16x16x32_bf16 v[26:29], v[208:211], v[176:179], v[26:29]
	v_mfma_f32_16x16x32_bf16 v[18:21], v[226:229], v[176:179], v[18:21]
	v_mfma_f32_16x16x32_bf16 v[10:13], v[208:211], v[184:187], v[10:13]
	v_mfma_f32_16x16x32_bf16 v[2:5], v[226:229], v[184:187], v[2:5]
	v_mfma_f32_16x16x32_bf16 v[74:77], v[222:225], v[86:89], v[58:61]
	v_mfma_f32_16x16x32_bf16 v[50:53], v[230:233], v[86:89], v[50:53]
	v_mfma_f32_16x16x32_bf16 v[42:45], v[222:225], v[94:97], v[42:45]
	v_mfma_f32_16x16x32_bf16 v[34:37], v[230:233], v[94:97], v[34:37]
	v_mfma_f32_16x16x32_bf16 v[26:29], v[222:225], v[180:183], v[26:29]
	v_mfma_f32_16x16x32_bf16 v[18:21], v[230:233], v[180:183], v[18:21]
	v_mfma_f32_16x16x32_bf16 v[10:13], v[222:225], v[188:191], v[10:13]
	v_mfma_f32_16x16x32_bf16 v[2:5], v[230:233], v[188:191], v[2:5]
	s_barrier
	s_cbranch_scc0 .LBB0_1099
	s_setprio 0
	v_lshl_or_b32 v58, s27, 8, v174
	v_mov_b32_e32 v177, v1
	v_ashrrev_i32_e32 v59, 31, v58
	v_lshlrev_b64 v[58:59], 2, v[58:59]
	v_lshl_add_u64 v[66:67], s[46:47], 0, v[58:59]
	v_lshl_add_u64 v[70:71], s[48:49], 0, v[58:59]
	v_lshlrev_b32_e32 v250, 2, v174
	v_add_u32_e32 v250, 0x20840, v250
	ds_read_b128 v[86:89], v250
	ds_read_b128 v[78:81], v250 offset:1024
	ds_read_b128 v[62:65], v250 offset:16
	ds_read_b128 v[58:61], v250 offset:1040
	ds_read_b128 v[94:97], v250 offset:512
	ds_read_b128 v[90:93], v250 offset:1536
	s_nop 0
	ds_read_b128 v[66:69], v250 offset:528
	s_nop 0
	ds_read_b128 v[70:73], v250 offset:1552
	s_lshl_b32 s3, s3, 8
	v_lshl_or_b32 v176, s27, 7, v174
	v_add_u32_e32 v184, s3, v177
	v_lshl_add_u32 v177, v177, 3, s33
	ds_read_b64 v[178:179], v177
	s_movk_i32 s27, 0xb00
	s_and_b64 vcc, exec, s[60:61]
	s_waitcnt lgkmcnt(0)
	v_xor_b32_e32 v89, 0x80000000, v89
	v_xor_b32_e32 v88, 0x80000000, v88
	v_pk_fma_f32 v[160:161], v[88:89], v[178:179], v[160:161] op_sel_hi:[1,0,1]
	v_pk_fma_f32 v[158:159], v[86:87], v[178:179], v[158:159] op_sel_hi:[1,0,1] neg_lo:[1,0,0] neg_hi:[1,0,0]
	v_pk_fma_f32 v[160:161], v[178:179], v[160:161], v[80:81] op_sel:[1,0,0]
	v_pk_fma_f32 v[158:159], v[178:179], v[158:159], v[78:79] op_sel:[1,0,0]
	v_pk_fma_f32 v[154:155], v[94:95], v[178:179], v[154:155] op_sel_hi:[1,0,1] neg_lo:[1,0,0] neg_hi:[1,0,0]
	v_mul_f32_e32 v182, 0xbfb8aa3b, v160
	v_pk_fma_f32 v[180:181], v[178:179], v[154:155], v[90:91] op_sel:[1,0,0]
	v_mul_f32_e32 v154, 0xbfb8aa3b, v158
	v_mul_f32_e32 v155, 0xbfb8aa3b, v159
	v_mul_f32_e32 v183, 0xbfb8aa3b, v161
	v_exp_f32_e32 v154, v154
	v_exp_f32_e32 v155, v155
	v_exp_f32_e32 v182, v182
	v_exp_f32_e32 v183, v183
	v_add_f32_e32 v154, 1.0, v154
	v_add_f32_e32 v155, 1.0, v155
	v_add_f32_e32 v182, 1.0, v182
	v_add_f32_e32 v183, 1.0, v183
	v_rcp_f32_e32 v154, v154
	v_rcp_f32_e32 v155, v155
	v_rcp_f32_e32 v182, v182
	v_rcp_f32_e32 v183, v183
	v_xor_b32_e32 v97, 0x80000000, v97
	v_xor_b32_e32 v96, 0x80000000, v96
	v_xor_b32_e32 v65, 0x80000000, v65
	v_xor_b32_e32 v64, 0x80000000, v64
	v_pk_fma_f32 v[156:157], v[96:97], v[178:179], v[156:157] op_sel_hi:[1,0,1]
	v_pk_fma_f32 v[152:153], v[64:65], v[178:179], v[152:153] op_sel_hi:[1,0,1]
	v_pk_fma_f32 v[150:151], v[62:63], v[178:179], v[150:151] op_sel_hi:[1,0,1] neg_lo:[1,0,0] neg_hi:[1,0,0]
	v_pk_fma_f32 v[156:157], v[178:179], v[156:157], v[92:93] op_sel:[1,0,0]
	v_pk_mul_f32 v[160:161], v[160:161], v[182:183]
	v_pk_mul_f32 v[158:159], v[158:159], v[154:155]
	v_pk_fma_f32 v[152:153], v[178:179], v[152:153], v[60:61] op_sel:[1,0,0]
	v_pk_fma_f32 v[150:151], v[178:179], v[150:151], v[58:59] op_sel:[1,0,0]
	v_pk_mul_f32 v[154:155], v[156:157], v[160:161]
	v_pk_mul_f32 v[156:157], v[180:181], v[158:159]
	v_mul_f32_e32 v158, 0xbfb8aa3b, v150
	v_mul_f32_e32 v159, 0xbfb8aa3b, v151
	v_mul_f32_e32 v160, 0xbfb8aa3b, v152
	v_mul_f32_e32 v161, 0xbfb8aa3b, v153
	v_exp_f32_e32 v158, v158
	v_exp_f32_e32 v159, v159
	v_exp_f32_e32 v160, v160
	v_exp_f32_e32 v161, v161
	v_add_f32_e32 v158, 1.0, v158
	v_add_f32_e32 v159, 1.0, v159
	v_add_f32_e32 v160, 1.0, v160
	v_add_f32_e32 v161, 1.0, v161
	v_rcp_f32_e32 v158, v158
	v_rcp_f32_e32 v159, v159
	v_rcp_f32_e32 v160, v160
	v_rcp_f32_e32 v161, v161
	v_xor_b32_e32 v69, 0x80000000, v69
	v_xor_b32_e32 v68, 0x80000000, v68
	v_pk_fma_f32 v[148:149], v[68:69], v[178:179], v[148:149] op_sel_hi:[1,0,1]
	v_pk_fma_f32 v[146:147], v[66:67], v[178:179], v[146:147] op_sel_hi:[1,0,1] neg_lo:[1,0,0] neg_hi:[1,0,0]
	v_pk_fma_f32 v[148:149], v[178:179], v[148:149], v[72:73] op_sel:[1,0,0]
	v_pk_fma_f32 v[146:147], v[178:179], v[146:147], v[70:71] op_sel:[1,0,0]
	v_pk_mul_f32 v[152:153], v[152:153], v[160:161]
	v_pk_mul_f32 v[150:151], v[150:151], v[158:159]
	v_mul_lo_u32 v158, v184, s27
	v_pk_mul_f32 v[152:153], v[148:149], v[152:153]
	v_pk_mul_f32 v[148:149], v[146:147], v[150:151]
	v_add_lshl_u32 v150, v158, v176, 1
	v_cvt_pk_bf16_f32 v146, v156, v157
	v_cvt_pk_bf16_f32 v147, v154, v155
	v_cvt_pk_bf16_f32 v148, v148, v149
	v_cvt_pk_bf16_f32 v149, v152, v153
	buffer_store_dwordx4 v[146:149], v150, s[28:31], 0 offen sc1
	ds_read_b64 v[146:147], v177 offset:128
	s_waitcnt lgkmcnt(0)
	v_pk_fma_f32 v[142:143], v[86:87], v[146:147], v[142:143] op_sel_hi:[1,0,1] neg_lo:[1,0,0] neg_hi:[1,0,0]
	s_nop 0
	v_pk_fma_f32 v[142:143], v[146:147], v[142:143], v[78:79] op_sel:[1,0,0]
	v_pk_fma_f32 v[144:145], v[88:89], v[146:147], v[144:145] op_sel_hi:[1,0,1]
	v_mul_f32_e32 v148, 0xbfb8aa3b, v142
	v_mul_f32_e32 v149, 0xbfb8aa3b, v143
	v_pk_fma_f32 v[144:145], v[146:147], v[144:145], v[80:81] op_sel:[1,0,0]
	v_exp_f32_e32 v148, v148
	v_exp_f32_e32 v149, v149
	v_mul_f32_e32 v150, 0xbfb8aa3b, v144
	v_mul_f32_e32 v151, 0xbfb8aa3b, v145
	v_exp_f32_e32 v150, v150
	v_exp_f32_e32 v151, v151
	v_add_f32_e32 v148, 1.0, v148
	v_add_f32_e32 v149, 1.0, v149
	v_rcp_f32_e32 v148, v148
	v_rcp_f32_e32 v149, v149
	v_add_f32_e32 v150, 1.0, v150
	v_add_f32_e32 v151, 1.0, v151
	v_rcp_f32_e32 v150, v150
	v_rcp_f32_e32 v151, v151
	v_pk_fma_f32 v[138:139], v[94:95], v[146:147], v[138:139] op_sel_hi:[1,0,1] neg_lo:[1,0,0] neg_hi:[1,0,0]
	v_pk_fma_f32 v[134:135], v[62:63], v[146:147], v[134:135] op_sel_hi:[1,0,1] neg_lo:[1,0,0] neg_hi:[1,0,0]
	v_pk_fma_f32 v[138:139], v[146:147], v[138:139], v[90:91] op_sel:[1,0,0]
	v_pk_mul_f32 v[142:143], v[142:143], v[148:149]
	v_pk_fma_f32 v[134:135], v[146:147], v[134:135], v[58:59] op_sel:[1,0,0]
	v_pk_fma_f32 v[140:141], v[96:97], v[146:147], v[140:141] op_sel_hi:[1,0,1]
	v_pk_mul_f32 v[138:139], v[138:139], v[142:143]
	v_pk_fma_f32 v[136:137], v[64:65], v[146:147], v[136:137] op_sel_hi:[1,0,1]
	v_mul_f32_e32 v142, 0xbfb8aa3b, v134
	v_mul_f32_e32 v143, 0xbfb8aa3b, v135
	v_pk_fma_f32 v[140:141], v[146:147], v[140:141], v[92:93] op_sel:[1,0,0]
	v_pk_mul_f32 v[144:145], v[144:145], v[150:151]
	v_pk_fma_f32 v[136:137], v[146:147], v[136:137], v[60:61] op_sel:[1,0,0]
	v_exp_f32_e32 v142, v142
	v_exp_f32_e32 v143, v143
	v_pk_mul_f32 v[140:141], v[140:141], v[144:145]
	v_mul_f32_e32 v144, 0xbfb8aa3b, v136
	v_mul_f32_e32 v145, 0xbfb8aa3b, v137
	v_exp_f32_e32 v144, v144
	v_exp_f32_e32 v145, v145
	v_add_f32_e32 v142, 1.0, v142
	v_add_f32_e32 v143, 1.0, v143
	v_rcp_f32_e32 v142, v142
	v_rcp_f32_e32 v143, v143
	v_add_f32_e32 v144, 1.0, v144
	v_add_f32_e32 v145, 1.0, v145
	v_rcp_f32_e32 v144, v144
	v_rcp_f32_e32 v145, v145
	v_pk_fma_f32 v[130:131], v[66:67], v[146:147], v[130:131] op_sel_hi:[1,0,1] neg_lo:[1,0,0] neg_hi:[1,0,0]
	v_pk_mul_f32 v[134:135], v[134:135], v[142:143]
	v_pk_fma_f32 v[130:131], v[146:147], v[130:131], v[70:71] op_sel:[1,0,0]
	v_pk_fma_f32 v[132:133], v[68:69], v[146:147], v[132:133] op_sel_hi:[1,0,1]
	v_pk_mul_f32 v[134:135], v[130:131], v[134:135]
	v_add_u32_e32 v130, 0xb000, v176
	v_pk_fma_f32 v[132:133], v[146:147], v[132:133], v[72:73] op_sel:[1,0,0]
	v_pk_mul_f32 v[136:137], v[136:137], v[144:145]
	v_add_lshl_u32 v131, v158, v130, 1
	v_pk_mul_f32 v[136:137], v[132:133], v[136:137]
	v_cvt_pk_bf16_f32 v132, v138, v139
	v_cvt_pk_bf16_f32 v133, v140, v141
	v_cvt_pk_bf16_f32 v134, v134, v135
	s_nop 0
	v_cvt_pk_bf16_f32 v135, v136, v137
	buffer_store_dwordx4 v[132:135], v131, s[28:31], 0 offen sc1
	v_mov_b32_e32 v131, v171
	s_nop 0
	v_add_u32_e32 v138, s3, v131
	v_lshl_add_u32 v131, v131, 3, s33
	ds_read_b64 v[132:133], v131
	s_waitcnt lgkmcnt(0)
	v_pk_fma_f32 v[128:129], v[88:89], v[132:133], v[128:129] op_sel_hi:[1,0,1]
	v_pk_fma_f32 v[126:127], v[86:87], v[132:133], v[126:127] op_sel_hi:[1,0,1] neg_lo:[1,0,0] neg_hi:[1,0,0]
	v_pk_fma_f32 v[128:129], v[132:133], v[128:129], v[80:81] op_sel:[1,0,0]
	v_pk_fma_f32 v[126:127], v[132:133], v[126:127], v[78:79] op_sel:[1,0,0]
	v_mul_f32_e32 v136, 0xbfb8aa3b, v128
	v_mul_f32_e32 v134, 0xbfb8aa3b, v126
	v_mul_f32_e32 v135, 0xbfb8aa3b, v127
	v_mul_f32_e32 v137, 0xbfb8aa3b, v129
	v_exp_f32_e32 v134, v134
	v_exp_f32_e32 v135, v135
	v_exp_f32_e32 v136, v136
	v_exp_f32_e32 v137, v137
	v_add_f32_e32 v134, 1.0, v134
	v_add_f32_e32 v135, 1.0, v135
	v_add_f32_e32 v136, 1.0, v136
	v_add_f32_e32 v137, 1.0, v137
	v_rcp_f32_e32 v134, v134
	v_rcp_f32_e32 v135, v135
	v_rcp_f32_e32 v136, v136
	v_rcp_f32_e32 v137, v137
	v_pk_fma_f32 v[124:125], v[96:97], v[132:133], v[124:125] op_sel_hi:[1,0,1]
	v_pk_fma_f32 v[122:123], v[94:95], v[132:133], v[122:123] op_sel_hi:[1,0,1] neg_lo:[1,0,0] neg_hi:[1,0,0]
	v_pk_fma_f32 v[120:121], v[64:65], v[132:133], v[120:121] op_sel_hi:[1,0,1]
	v_pk_fma_f32 v[118:119], v[62:63], v[132:133], v[118:119] op_sel_hi:[1,0,1] neg_lo:[1,0,0] neg_hi:[1,0,0]
	v_pk_fma_f32 v[124:125], v[132:133], v[124:125], v[92:93] op_sel:[1,0,0]
	v_pk_fma_f32 v[122:123], v[132:133], v[122:123], v[90:91] op_sel:[1,0,0]
	v_pk_mul_f32 v[128:129], v[128:129], v[136:137]
	v_pk_mul_f32 v[126:127], v[126:127], v[134:135]
	v_pk_fma_f32 v[120:121], v[132:133], v[120:121], v[60:61] op_sel:[1,0,0]
	v_pk_fma_f32 v[118:119], v[132:133], v[118:119], v[58:59] op_sel:[1,0,0]
	v_pk_mul_f32 v[124:125], v[124:125], v[128:129]
	v_pk_mul_f32 v[122:123], v[122:123], v[126:127]
	v_mul_f32_e32 v126, 0xbfb8aa3b, v118
	v_mul_f32_e32 v127, 0xbfb8aa3b, v119
	v_mul_f32_e32 v128, 0xbfb8aa3b, v120
	v_mul_f32_e32 v129, 0xbfb8aa3b, v121
	v_exp_f32_e32 v126, v126
	v_exp_f32_e32 v127, v127
	v_exp_f32_e32 v128, v128
	v_exp_f32_e32 v129, v129
	v_add_f32_e32 v126, 1.0, v126
	v_add_f32_e32 v127, 1.0, v127
	v_add_f32_e32 v128, 1.0, v128
	v_add_f32_e32 v129, 1.0, v129
	v_rcp_f32_e32 v126, v126
	v_rcp_f32_e32 v127, v127
	v_rcp_f32_e32 v128, v128
	v_rcp_f32_e32 v129, v129
	v_pk_fma_f32 v[116:117], v[68:69], v[132:133], v[116:117] op_sel_hi:[1,0,1]
	v_pk_fma_f32 v[114:115], v[66:67], v[132:133], v[114:115] op_sel_hi:[1,0,1] neg_lo:[1,0,0] neg_hi:[1,0,0]
	v_pk_fma_f32 v[116:117], v[132:133], v[116:117], v[72:73] op_sel:[1,0,0]
	v_pk_fma_f32 v[114:115], v[132:133], v[114:115], v[70:71] op_sel:[1,0,0]
	v_pk_mul_f32 v[120:121], v[120:121], v[128:129]
	v_pk_mul_f32 v[118:119], v[118:119], v[126:127]
	v_mul_lo_u32 v126, v138, s27
	v_pk_mul_f32 v[120:121], v[116:117], v[120:121]
	v_pk_mul_f32 v[116:117], v[114:115], v[118:119]
	v_add_lshl_u32 v118, v126, v176, 1
	v_cvt_pk_bf16_f32 v114, v122, v123
	v_cvt_pk_bf16_f32 v115, v124, v125
	v_cvt_pk_bf16_f32 v116, v116, v117
	v_cvt_pk_bf16_f32 v117, v120, v121
	buffer_store_dwordx4 v[114:117], v118, s[28:31], 0 offen sc1
	ds_read_b64 v[114:115], v131 offset:128
	s_waitcnt lgkmcnt(0)
	v_pk_fma_f32 v[112:113], v[88:89], v[114:115], v[112:113] op_sel_hi:[1,0,1]
	v_pk_fma_f32 v[110:111], v[86:87], v[114:115], v[110:111] op_sel_hi:[1,0,1] neg_lo:[1,0,0] neg_hi:[1,0,0]
	v_pk_fma_f32 v[112:113], v[114:115], v[112:113], v[80:81] op_sel:[1,0,0]
	v_pk_fma_f32 v[110:111], v[114:115], v[110:111], v[78:79] op_sel:[1,0,0]
	v_mul_f32_e32 v118, 0xbfb8aa3b, v112
	v_mul_f32_e32 v116, 0xbfb8aa3b, v110
	v_mul_f32_e32 v117, 0xbfb8aa3b, v111
	v_mul_f32_e32 v119, 0xbfb8aa3b, v113
	v_exp_f32_e32 v116, v116
	v_exp_f32_e32 v117, v117
	v_exp_f32_e32 v118, v118
	v_exp_f32_e32 v119, v119
	v_add_f32_e32 v116, 1.0, v116
	v_add_f32_e32 v117, 1.0, v117
	v_add_f32_e32 v118, 1.0, v118
	v_add_f32_e32 v119, 1.0, v119
	v_rcp_f32_e32 v116, v116
	v_rcp_f32_e32 v117, v117
	v_rcp_f32_e32 v118, v118
	v_rcp_f32_e32 v119, v119
	v_pk_fma_f32 v[108:109], v[96:97], v[114:115], v[108:109] op_sel_hi:[1,0,1]
	v_pk_fma_f32 v[106:107], v[94:95], v[114:115], v[106:107] op_sel_hi:[1,0,1] neg_lo:[1,0,0] neg_hi:[1,0,0]
	v_pk_fma_f32 v[104:105], v[64:65], v[114:115], v[104:105] op_sel_hi:[1,0,1]
	v_pk_fma_f32 v[102:103], v[62:63], v[114:115], v[102:103] op_sel_hi:[1,0,1] neg_lo:[1,0,0] neg_hi:[1,0,0]
	v_pk_fma_f32 v[108:109], v[114:115], v[108:109], v[92:93] op_sel:[1,0,0]
	v_pk_fma_f32 v[106:107], v[114:115], v[106:107], v[90:91] op_sel:[1,0,0]
	v_pk_mul_f32 v[112:113], v[112:113], v[118:119]
	v_pk_mul_f32 v[110:111], v[110:111], v[116:117]
	v_pk_fma_f32 v[104:105], v[114:115], v[104:105], v[60:61] op_sel:[1,0,0]
	v_pk_fma_f32 v[102:103], v[114:115], v[102:103], v[58:59] op_sel:[1,0,0]
	v_pk_mul_f32 v[108:109], v[108:109], v[112:113]
	v_pk_mul_f32 v[106:107], v[106:107], v[110:111]
	v_mul_f32_e32 v110, 0xbfb8aa3b, v102
	v_mul_f32_e32 v111, 0xbfb8aa3b, v103
	v_mul_f32_e32 v112, 0xbfb8aa3b, v104
	v_mul_f32_e32 v113, 0xbfb8aa3b, v105
	v_exp_f32_e32 v110, v110
	v_exp_f32_e32 v111, v111
	v_exp_f32_e32 v112, v112
	v_exp_f32_e32 v113, v113
	v_add_f32_e32 v110, 1.0, v110
	v_add_f32_e32 v111, 1.0, v111
	v_add_f32_e32 v112, 1.0, v112
	v_add_f32_e32 v113, 1.0, v113
	v_rcp_f32_e32 v110, v110
	v_rcp_f32_e32 v111, v111
	v_rcp_f32_e32 v112, v112
	v_rcp_f32_e32 v113, v113
	v_pk_fma_f32 v[100:101], v[68:69], v[114:115], v[100:101] op_sel_hi:[1,0,1]
	v_pk_fma_f32 v[98:99], v[66:67], v[114:115], v[98:99] op_sel_hi:[1,0,1] neg_lo:[1,0,0] neg_hi:[1,0,0]
	v_pk_fma_f32 v[100:101], v[114:115], v[100:101], v[72:73] op_sel:[1,0,0]
	v_pk_fma_f32 v[98:99], v[114:115], v[98:99], v[70:71] op_sel:[1,0,0]
	v_pk_mul_f32 v[104:105], v[104:105], v[112:113]
	v_pk_mul_f32 v[102:103], v[102:103], v[110:111]
	v_pk_mul_f32 v[104:105], v[100:101], v[104:105]
	v_pk_mul_f32 v[100:101], v[98:99], v[102:103]
	v_add_lshl_u32 v102, v126, v130, 1
	v_cvt_pk_bf16_f32 v98, v106, v107
	v_cvt_pk_bf16_f32 v99, v108, v109
	v_cvt_pk_bf16_f32 v100, v100, v101
	v_cvt_pk_bf16_f32 v101, v104, v105
	buffer_store_dwordx4 v[98:101], v102, s[28:31], 0 offen sc1
	s_nop 1
	v_mov_b32_e32 v98, v172
	s_nop 0
	v_lshl_add_u32 v105, v98, 3, s33
	v_add_u32_e32 v104, s3, v98
	ds_read_b64 v[98:99], v105
	s_waitcnt lgkmcnt(0)
	v_pk_fma_f32 v[84:85], v[88:89], v[98:99], v[84:85] op_sel_hi:[1,0,1]
	v_pk_fma_f32 v[82:83], v[86:87], v[98:99], v[82:83] op_sel_hi:[1,0,1] neg_lo:[1,0,0] neg_hi:[1,0,0]
	v_pk_fma_f32 v[84:85], v[98:99], v[84:85], v[80:81] op_sel:[1,0,0]
	v_pk_fma_f32 v[82:83], v[98:99], v[82:83], v[78:79] op_sel:[1,0,0]
	v_mul_f32_e32 v102, 0xbfb8aa3b, v84
	v_mul_f32_e32 v100, 0xbfb8aa3b, v82
	v_mul_f32_e32 v101, 0xbfb8aa3b, v83
	v_mul_f32_e32 v103, 0xbfb8aa3b, v85
	v_exp_f32_e32 v100, v100
	v_exp_f32_e32 v101, v101
	v_exp_f32_e32 v102, v102
	v_exp_f32_e32 v103, v103
	v_add_f32_e32 v100, 1.0, v100
	v_add_f32_e32 v101, 1.0, v101
	v_add_f32_e32 v102, 1.0, v102
	v_add_f32_e32 v103, 1.0, v103
	v_rcp_f32_e32 v100, v100
	v_rcp_f32_e32 v101, v101
	v_rcp_f32_e32 v102, v102
	v_rcp_f32_e32 v103, v103
	v_pk_fma_f32 v[76:77], v[96:97], v[98:99], v[76:77] op_sel_hi:[1,0,1]
	v_pk_fma_f32 v[74:75], v[94:95], v[98:99], v[74:75] op_sel_hi:[1,0,1] neg_lo:[1,0,0] neg_hi:[1,0,0]
	v_pk_fma_f32 v[56:57], v[64:65], v[98:99], v[56:57] op_sel_hi:[1,0,1]
	v_pk_fma_f32 v[54:55], v[62:63], v[98:99], v[54:55] op_sel_hi:[1,0,1] neg_lo:[1,0,0] neg_hi:[1,0,0]
	v_pk_fma_f32 v[76:77], v[98:99], v[76:77], v[92:93] op_sel:[1,0,0]
	v_pk_fma_f32 v[74:75], v[98:99], v[74:75], v[90:91] op_sel:[1,0,0]
	v_pk_mul_f32 v[84:85], v[84:85], v[102:103]
	v_pk_mul_f32 v[82:83], v[82:83], v[100:101]
	v_pk_fma_f32 v[56:57], v[98:99], v[56:57], v[60:61] op_sel:[1,0,0]
	v_pk_fma_f32 v[54:55], v[98:99], v[54:55], v[58:59] op_sel:[1,0,0]
	v_pk_mul_f32 v[76:77], v[76:77], v[84:85]
	v_pk_mul_f32 v[74:75], v[74:75], v[82:83]
	v_mul_f32_e32 v82, 0xbfb8aa3b, v54
	v_mul_f32_e32 v83, 0xbfb8aa3b, v55
	v_mul_f32_e32 v84, 0xbfb8aa3b, v56
	v_mul_f32_e32 v85, 0xbfb8aa3b, v57
	v_exp_f32_e32 v82, v82
	v_exp_f32_e32 v83, v83
	v_exp_f32_e32 v84, v84
	v_exp_f32_e32 v85, v85
	v_add_f32_e32 v82, 1.0, v82
	v_add_f32_e32 v83, 1.0, v83
	v_add_f32_e32 v84, 1.0, v84
	v_add_f32_e32 v85, 1.0, v85
	v_rcp_f32_e32 v82, v82
	v_rcp_f32_e32 v83, v83
	v_rcp_f32_e32 v84, v84
	v_rcp_f32_e32 v85, v85
	v_pk_fma_f32 v[52:53], v[68:69], v[98:99], v[52:53] op_sel_hi:[1,0,1]
	v_pk_fma_f32 v[50:51], v[66:67], v[98:99], v[50:51] op_sel_hi:[1,0,1] neg_lo:[1,0,0] neg_hi:[1,0,0]
	v_pk_fma_f32 v[52:53], v[98:99], v[52:53], v[72:73] op_sel:[1,0,0]
	v_pk_fma_f32 v[50:51], v[98:99], v[50:51], v[70:71] op_sel:[1,0,0]
	v_pk_mul_f32 v[56:57], v[56:57], v[84:85]
	v_pk_mul_f32 v[54:55], v[54:55], v[82:83]
	v_mul_lo_u32 v82, v104, s27
	v_pk_mul_f32 v[56:57], v[52:53], v[56:57]
	v_pk_mul_f32 v[52:53], v[50:51], v[54:55]
	v_add_lshl_u32 v54, v82, v176, 1
	v_cvt_pk_bf16_f32 v50, v74, v75
	v_cvt_pk_bf16_f32 v51, v76, v77
	v_cvt_pk_bf16_f32 v52, v52, v53
	v_cvt_pk_bf16_f32 v53, v56, v57
	buffer_store_dwordx4 v[50:53], v54, s[28:31], 0 offen sc1
	ds_read_b64 v[50:51], v105 offset:128
	s_waitcnt lgkmcnt(0)
	v_pk_fma_f32 v[48:49], v[88:89], v[50:51], v[48:49] op_sel_hi:[1,0,1]
	v_pk_fma_f32 v[46:47], v[86:87], v[50:51], v[46:47] op_sel_hi:[1,0,1] neg_lo:[1,0,0] neg_hi:[1,0,0]
	v_pk_fma_f32 v[48:49], v[50:51], v[48:49], v[80:81] op_sel:[1,0,0]
	v_pk_fma_f32 v[46:47], v[50:51], v[46:47], v[78:79] op_sel:[1,0,0]
	v_mul_f32_e32 v54, 0xbfb8aa3b, v48
	v_mul_f32_e32 v52, 0xbfb8aa3b, v46
	v_mul_f32_e32 v53, 0xbfb8aa3b, v47
	v_mul_f32_e32 v55, 0xbfb8aa3b, v49
	v_exp_f32_e32 v52, v52
	v_exp_f32_e32 v53, v53
	v_exp_f32_e32 v54, v54
	v_exp_f32_e32 v55, v55
	v_add_f32_e32 v52, 1.0, v52
	v_add_f32_e32 v53, 1.0, v53
	v_add_f32_e32 v54, 1.0, v54
	v_add_f32_e32 v55, 1.0, v55
	v_rcp_f32_e32 v52, v52
	v_rcp_f32_e32 v53, v53
	v_rcp_f32_e32 v54, v54
	v_rcp_f32_e32 v55, v55
	v_pk_fma_f32 v[44:45], v[96:97], v[50:51], v[44:45] op_sel_hi:[1,0,1]
	v_pk_fma_f32 v[42:43], v[94:95], v[50:51], v[42:43] op_sel_hi:[1,0,1] neg_lo:[1,0,0] neg_hi:[1,0,0]
	v_pk_fma_f32 v[40:41], v[64:65], v[50:51], v[40:41] op_sel_hi:[1,0,1]
	v_pk_fma_f32 v[38:39], v[62:63], v[50:51], v[38:39] op_sel_hi:[1,0,1] neg_lo:[1,0,0] neg_hi:[1,0,0]
	v_pk_fma_f32 v[44:45], v[50:51], v[44:45], v[92:93] op_sel:[1,0,0]
	v_pk_fma_f32 v[42:43], v[50:51], v[42:43], v[90:91] op_sel:[1,0,0]
	v_pk_mul_f32 v[48:49], v[48:49], v[54:55]
	v_pk_mul_f32 v[46:47], v[46:47], v[52:53]
	v_pk_fma_f32 v[40:41], v[50:51], v[40:41], v[60:61] op_sel:[1,0,0]
	v_pk_fma_f32 v[38:39], v[50:51], v[38:39], v[58:59] op_sel:[1,0,0]
	v_pk_mul_f32 v[44:45], v[44:45], v[48:49]
	v_pk_mul_f32 v[42:43], v[42:43], v[46:47]
	v_mul_f32_e32 v46, 0xbfb8aa3b, v38
	v_mul_f32_e32 v47, 0xbfb8aa3b, v39
	v_mul_f32_e32 v48, 0xbfb8aa3b, v40
	v_mul_f32_e32 v49, 0xbfb8aa3b, v41
	v_exp_f32_e32 v46, v46
	v_exp_f32_e32 v47, v47
	v_exp_f32_e32 v48, v48
	v_exp_f32_e32 v49, v49
	v_add_f32_e32 v46, 1.0, v46
	v_add_f32_e32 v47, 1.0, v47
	v_add_f32_e32 v48, 1.0, v48
	v_add_f32_e32 v49, 1.0, v49
	v_rcp_f32_e32 v46, v46
	v_rcp_f32_e32 v47, v47
	v_rcp_f32_e32 v48, v48
	v_rcp_f32_e32 v49, v49
	v_pk_fma_f32 v[36:37], v[68:69], v[50:51], v[36:37] op_sel_hi:[1,0,1]
	v_pk_fma_f32 v[34:35], v[66:67], v[50:51], v[34:35] op_sel_hi:[1,0,1] neg_lo:[1,0,0] neg_hi:[1,0,0]
	v_pk_fma_f32 v[36:37], v[50:51], v[36:37], v[72:73] op_sel:[1,0,0]
	v_pk_fma_f32 v[34:35], v[50:51], v[34:35], v[70:71] op_sel:[1,0,0]
	v_pk_mul_f32 v[40:41], v[40:41], v[48:49]
	v_pk_mul_f32 v[38:39], v[38:39], v[46:47]
	v_pk_mul_f32 v[40:41], v[36:37], v[40:41]
	v_pk_mul_f32 v[36:37], v[34:35], v[38:39]
	v_add_lshl_u32 v38, v82, v130, 1
	v_cvt_pk_bf16_f32 v34, v42, v43
	v_cvt_pk_bf16_f32 v35, v44, v45
	v_cvt_pk_bf16_f32 v36, v36, v37
	v_cvt_pk_bf16_f32 v37, v40, v41
	buffer_store_dwordx4 v[34:37], v38, s[28:31], 0 offen sc1
	s_nop 1
	v_mov_b32_e32 v34, v173
	s_nop 0
	v_lshl_add_u32 v41, v34, 3, s33
	v_add_u32_e32 v40, s3, v34
	ds_read_b64 v[34:35], v41
	s_mov_b32 s3, s77
	s_waitcnt lgkmcnt(0)
	v_pk_fma_f32 v[32:33], v[88:89], v[34:35], v[32:33] op_sel_hi:[1,0,1]
	v_pk_fma_f32 v[30:31], v[86:87], v[34:35], v[30:31] op_sel_hi:[1,0,1] neg_lo:[1,0,0] neg_hi:[1,0,0]
	v_pk_fma_f32 v[32:33], v[34:35], v[32:33], v[80:81] op_sel:[1,0,0]
	v_pk_fma_f32 v[30:31], v[34:35], v[30:31], v[78:79] op_sel:[1,0,0]
	v_mul_f32_e32 v38, 0xbfb8aa3b, v32
	v_mul_f32_e32 v36, 0xbfb8aa3b, v30
	v_mul_f32_e32 v37, 0xbfb8aa3b, v31
	v_mul_f32_e32 v39, 0xbfb8aa3b, v33
	v_exp_f32_e32 v36, v36
	v_exp_f32_e32 v37, v37
	v_exp_f32_e32 v38, v38
	v_exp_f32_e32 v39, v39
	v_add_f32_e32 v36, 1.0, v36
	v_add_f32_e32 v37, 1.0, v37
	v_add_f32_e32 v38, 1.0, v38
	v_add_f32_e32 v39, 1.0, v39
	v_rcp_f32_e32 v36, v36
	v_rcp_f32_e32 v37, v37
	v_rcp_f32_e32 v38, v38
	v_rcp_f32_e32 v39, v39
	v_pk_fma_f32 v[28:29], v[96:97], v[34:35], v[28:29] op_sel_hi:[1,0,1]
	v_pk_fma_f32 v[26:27], v[94:95], v[34:35], v[26:27] op_sel_hi:[1,0,1] neg_lo:[1,0,0] neg_hi:[1,0,0]
	v_pk_fma_f32 v[24:25], v[64:65], v[34:35], v[24:25] op_sel_hi:[1,0,1]
	v_pk_fma_f32 v[22:23], v[62:63], v[34:35], v[22:23] op_sel_hi:[1,0,1] neg_lo:[1,0,0] neg_hi:[1,0,0]
	v_pk_fma_f32 v[28:29], v[34:35], v[28:29], v[92:93] op_sel:[1,0,0]
	v_pk_fma_f32 v[26:27], v[34:35], v[26:27], v[90:91] op_sel:[1,0,0]
	v_pk_mul_f32 v[32:33], v[32:33], v[38:39]
	v_pk_mul_f32 v[30:31], v[30:31], v[36:37]
	v_pk_fma_f32 v[24:25], v[34:35], v[24:25], v[60:61] op_sel:[1,0,0]
	v_pk_fma_f32 v[22:23], v[34:35], v[22:23], v[58:59] op_sel:[1,0,0]
	v_pk_mul_f32 v[28:29], v[28:29], v[32:33]
	v_pk_mul_f32 v[26:27], v[26:27], v[30:31]
	v_mul_f32_e32 v30, 0xbfb8aa3b, v22
	v_mul_f32_e32 v31, 0xbfb8aa3b, v23
	v_mul_f32_e32 v32, 0xbfb8aa3b, v24
	v_mul_f32_e32 v33, 0xbfb8aa3b, v25
	v_exp_f32_e32 v30, v30
	v_exp_f32_e32 v31, v31
	v_exp_f32_e32 v32, v32
	v_exp_f32_e32 v33, v33
	v_add_f32_e32 v30, 1.0, v30
	v_add_f32_e32 v31, 1.0, v31
	v_add_f32_e32 v32, 1.0, v32
	v_add_f32_e32 v33, 1.0, v33
	v_rcp_f32_e32 v30, v30
	v_rcp_f32_e32 v31, v31
	v_rcp_f32_e32 v32, v32
	v_rcp_f32_e32 v33, v33
	v_pk_fma_f32 v[20:21], v[68:69], v[34:35], v[20:21] op_sel_hi:[1,0,1]
	v_pk_fma_f32 v[18:19], v[66:67], v[34:35], v[18:19] op_sel_hi:[1,0,1] neg_lo:[1,0,0] neg_hi:[1,0,0]
	v_pk_fma_f32 v[20:21], v[34:35], v[20:21], v[72:73] op_sel:[1,0,0]
	v_pk_fma_f32 v[18:19], v[34:35], v[18:19], v[70:71] op_sel:[1,0,0]
	v_pk_mul_f32 v[24:25], v[24:25], v[32:33]
	v_pk_mul_f32 v[22:23], v[22:23], v[30:31]
	v_mul_lo_u32 v30, v40, s27
	v_pk_mul_f32 v[24:25], v[20:21], v[24:25]
	v_pk_mul_f32 v[20:21], v[18:19], v[22:23]
	v_add_lshl_u32 v22, v30, v176, 1
	v_cvt_pk_bf16_f32 v18, v26, v27
	v_cvt_pk_bf16_f32 v19, v28, v29
	v_cvt_pk_bf16_f32 v20, v20, v21
	v_cvt_pk_bf16_f32 v21, v24, v25
	buffer_store_dwordx4 v[18:21], v22, s[28:31], 0 offen sc1
	ds_read_b64 v[18:19], v41 offset:128
	s_mov_b32 s27, s58
	s_waitcnt lgkmcnt(0)
	v_pk_fma_f32 v[16:17], v[88:89], v[18:19], v[16:17] op_sel_hi:[1,0,1]
	v_pk_fma_f32 v[14:15], v[86:87], v[18:19], v[14:15] op_sel_hi:[1,0,1] neg_lo:[1,0,0] neg_hi:[1,0,0]
	v_pk_fma_f32 v[16:17], v[18:19], v[16:17], v[80:81] op_sel:[1,0,0]
	v_pk_fma_f32 v[14:15], v[18:19], v[14:15], v[78:79] op_sel:[1,0,0]
	v_mul_f32_e32 v22, 0xbfb8aa3b, v16
	v_mul_f32_e32 v20, 0xbfb8aa3b, v14
	v_mul_f32_e32 v21, 0xbfb8aa3b, v15
	v_mul_f32_e32 v23, 0xbfb8aa3b, v17
	v_exp_f32_e32 v20, v20
	v_exp_f32_e32 v21, v21
	v_exp_f32_e32 v22, v22
	v_exp_f32_e32 v23, v23
	v_add_f32_e32 v20, 1.0, v20
	v_add_f32_e32 v21, 1.0, v21
	v_add_f32_e32 v22, 1.0, v22
	v_add_f32_e32 v23, 1.0, v23
	v_rcp_f32_e32 v20, v20
	v_rcp_f32_e32 v21, v21
	v_rcp_f32_e32 v22, v22
	v_rcp_f32_e32 v23, v23
	v_pk_fma_f32 v[12:13], v[96:97], v[18:19], v[12:13] op_sel_hi:[1,0,1]
	v_pk_fma_f32 v[10:11], v[94:95], v[18:19], v[10:11] op_sel_hi:[1,0,1] neg_lo:[1,0,0] neg_hi:[1,0,0]
	v_pk_fma_f32 v[8:9], v[64:65], v[18:19], v[8:9] op_sel_hi:[1,0,1]
	v_pk_fma_f32 v[6:7], v[62:63], v[18:19], v[6:7] op_sel_hi:[1,0,1] neg_lo:[1,0,0] neg_hi:[1,0,0]
	v_pk_fma_f32 v[12:13], v[18:19], v[12:13], v[92:93] op_sel:[1,0,0]
	v_pk_fma_f32 v[10:11], v[18:19], v[10:11], v[90:91] op_sel:[1,0,0]
	v_pk_mul_f32 v[16:17], v[16:17], v[22:23]
	v_pk_mul_f32 v[14:15], v[14:15], v[20:21]
	v_pk_fma_f32 v[8:9], v[18:19], v[8:9], v[60:61] op_sel:[1,0,0]
	v_pk_fma_f32 v[6:7], v[18:19], v[6:7], v[58:59] op_sel:[1,0,0]
	v_pk_mul_f32 v[12:13], v[12:13], v[16:17]
	v_pk_mul_f32 v[10:11], v[10:11], v[14:15]
	v_mul_f32_e32 v14, 0xbfb8aa3b, v6
	v_mul_f32_e32 v15, 0xbfb8aa3b, v7
	v_mul_f32_e32 v16, 0xbfb8aa3b, v8
	v_mul_f32_e32 v17, 0xbfb8aa3b, v9
	v_exp_f32_e32 v14, v14
	v_exp_f32_e32 v15, v15
	v_exp_f32_e32 v16, v16
	v_exp_f32_e32 v17, v17
	v_add_f32_e32 v14, 1.0, v14
	v_add_f32_e32 v15, 1.0, v15
	v_add_f32_e32 v16, 1.0, v16
	v_add_f32_e32 v17, 1.0, v17
	v_rcp_f32_e32 v14, v14
	v_rcp_f32_e32 v15, v15
	v_rcp_f32_e32 v16, v16
	v_rcp_f32_e32 v17, v17
	v_pk_fma_f32 v[4:5], v[68:69], v[18:19], v[4:5] op_sel_hi:[1,0,1]
	v_pk_fma_f32 v[2:3], v[66:67], v[18:19], v[2:3] op_sel_hi:[1,0,1] neg_lo:[1,0,0] neg_hi:[1,0,0]
	v_pk_fma_f32 v[4:5], v[18:19], v[4:5], v[72:73] op_sel:[1,0,0]
	v_pk_fma_f32 v[2:3], v[18:19], v[2:3], v[70:71] op_sel:[1,0,0]
	v_pk_mul_f32 v[8:9], v[8:9], v[16:17]
	v_pk_mul_f32 v[6:7], v[6:7], v[14:15]
	v_pk_mul_f32 v[8:9], v[4:5], v[8:9]
	v_pk_mul_f32 v[4:5], v[2:3], v[6:7]
	v_add_lshl_u32 v6, v30, v130, 1
	v_cvt_pk_bf16_f32 v2, v10, v11
	v_cvt_pk_bf16_f32 v3, v12, v13
	v_cvt_pk_bf16_f32 v4, v4, v5
	v_cvt_pk_bf16_f32 v5, v8, v9
	buffer_store_dwordx4 v[2:5], v6, s[28:31], 0 offen sc1
	s_cbranch_vccz .LBB0_1098
	s_waitcnt vmcnt(0)
	v_readlane_b32 s76, v255, 13
	s_cmpk_gt_u32 s38, 0xff
	v_readlane_b32 s77, v255, 14
	s_cbranch_scc1 .LBB0_1103
	s_barrier

.LBB0_1178:
	s_add_u32 s27, s36, 0x100
	s_addc_u32 s91, s37, 0
	s_add_u32 s36, s42, 0x80
	s_addc_u32 s37, s43, 0
	s_mov_b32 s42, 0
	s_waitcnt lgkmcnt(0)
	s_add_i32 s92, s42, 2
	s_add_u32 s72, s36, 0x80
	s_addc_u32 s43, s37, 0
	s_add_i32 s93, 0, 0x10000
	v_add_u32_e32 v1, s93, v223
	ds_read_b128 v[50:53], v1
	ds_read_b128 v[54:57], v1 offset:1024
	ds_read_b128 v[58:61], v1 offset:2048
	ds_read_b128 v[62:65], v1 offset:3072
	s_cmp_eq_u32 s88, s42
	s_cselect_b32 s42, s66, s72
	s_cselect_b32 s43, s67, s43
	s_cselect_b32 s73, s71, s91
	s_cselect_b32 s72, s70, s27
	v_lshl_add_u64 v[178:179], s[36:37], 0, v[206:207]
	s_add_i32 m0, s79, 0xc000
	ds_read_b128 v[66:69], v230
	ds_read_b128 v[70:73], v230 offset:1024
	ds_read_b128 v[74:77], v230 offset:2048
	ds_read_b128 v[78:81], v230 offset:3072
	ds_read_b128 v[146:149], v230 offset:4096
	ds_read_b128 v[154:157], v230 offset:5120
	ds_read_b128 v[170:173], v230 offset:6144
	ds_read_b128 v[174:177], v230 offset:7168
	global_load_lds_dwordx4 v[178:179], off
	v_lshl_add_u64 v[178:179], s[36:37], 0, v[204:205]
	s_add_i32 m0, s79, 0xe000
	s_nop 0
	global_load_lds_dwordx4 v[178:179], off
	s_waitcnt lgkmcnt(8)
	s_barrier
	s_waitcnt lgkmcnt(0)
	v_mfma_f32_16x16x32_bf16 v[166:169], v[50:53], v[66:69], 0
	v_mfma_f32_16x16x32_bf16 v[162:165], v[58:61], v[66:69], 0
	v_mfma_f32_16x16x32_bf16 v[142:145], v[50:53], v[74:77], 0
	v_mfma_f32_16x16x32_bf16 v[138:141], v[58:61], v[74:77], 0
	v_mfma_f32_16x16x32_bf16 v[126:129], v[50:53], v[146:149], 0
	v_mfma_f32_16x16x32_bf16 v[122:125], v[58:61], v[146:149], 0
	v_mfma_f32_16x16x32_bf16 v[110:113], v[50:53], v[170:173], 0
	v_mfma_f32_16x16x32_bf16 v[106:109], v[58:61], v[170:173], 0
	v_mfma_f32_16x16x32_bf16 v[166:169], v[54:57], v[70:73], v[166:169]
	v_mfma_f32_16x16x32_bf16 v[162:165], v[62:65], v[70:73], v[162:165]
	v_mfma_f32_16x16x32_bf16 v[142:145], v[54:57], v[78:81], v[142:145]
	v_mfma_f32_16x16x32_bf16 v[138:141], v[62:65], v[78:81], v[138:141]
	v_mfma_f32_16x16x32_bf16 v[126:129], v[54:57], v[154:157], v[126:129]
	v_mfma_f32_16x16x32_bf16 v[122:125], v[62:65], v[154:157], v[122:125]
	v_mfma_f32_16x16x32_bf16 v[110:113], v[54:57], v[174:177], v[110:113]
	v_mfma_f32_16x16x32_bf16 v[106:109], v[62:65], v[174:177], v[106:109]
	s_barrier
	s_add_i32 s94, 0, 0x14000
	s_add_i32 s93, s93, s78
	v_add_u32_e32 v1, s94, v223
	v_lshl_add_u64 v[214:215], s[72:73], 0, v[202:203]
	s_mov_b32 m0, s93
	ds_read_b128 v[178:181], v1
	ds_read_b128 v[182:185], v1 offset:1024
	ds_read_b128 v[186:189], v1 offset:2048
	ds_read_b128 v[190:193], v1 offset:3072
	global_load_lds_dwordx4 v[214:215], off
	v_lshl_add_u64 v[236:237], s[72:73], 0, v[200:201]
	s_add_i32 m0, s93, 0x2000
	s_nop 0
	global_load_lds_dwordx4 v[236:237], off
	s_barrier
	s_waitcnt lgkmcnt(0)
	v_mfma_f32_16x16x32_bf16 v[158:161], v[178:181], v[66:69], 0
	v_mfma_f32_16x16x32_bf16 v[66:69], v[186:189], v[66:69], 0
	v_mfma_f32_16x16x32_bf16 v[158:161], v[182:185], v[70:73], v[158:161]
	v_mfma_f32_16x16x32_bf16 v[66:69], v[190:193], v[70:73], v[66:69]
	v_mfma_f32_16x16x32_bf16 v[70:73], v[178:181], v[74:77], 0
	v_mfma_f32_16x16x32_bf16 v[74:77], v[186:189], v[74:77], 0
	v_mfma_f32_16x16x32_bf16 v[114:117], v[186:189], v[146:149], 0
	v_mfma_f32_16x16x32_bf16 v[102:105], v[178:181], v[170:173], 0
	v_mfma_f32_16x16x32_bf16 v[98:101], v[186:189], v[170:173], 0
	v_mfma_f32_16x16x32_bf16 v[70:73], v[182:185], v[78:81], v[70:73]
	v_mfma_f32_16x16x32_bf16 v[74:77], v[190:193], v[78:81], v[74:77]
	v_mfma_f32_16x16x32_bf16 v[78:81], v[178:181], v[146:149], 0
	v_mfma_f32_16x16x32_bf16 v[114:117], v[190:193], v[154:157], v[114:117]
	v_mfma_f32_16x16x32_bf16 v[102:105], v[182:185], v[174:177], v[102:105]
	v_mfma_f32_16x16x32_bf16 v[98:101], v[190:193], v[174:177], v[98:101]
	v_mfma_f32_16x16x32_bf16 v[78:81], v[182:185], v[154:157], v[78:81]
	s_barrier
	s_mov_b32 m0, s79
	v_lshl_add_u64 v[238:239], s[42:43], 0, v[202:203]
	ds_read_b128 v[118:121], v230 offset:16384
	ds_read_b128 v[130:133], v230 offset:17408
	ds_read_b128 v[134:137], v230 offset:18432
	ds_read_b128 v[146:149], v230 offset:19456
	ds_read_b128 v[150:153], v230 offset:20480
	ds_read_b128 v[154:157], v230 offset:21504
	ds_read_b128 v[170:173], v230 offset:22528
	ds_read_b128 v[174:177], v230 offset:23552
	global_load_lds_dwordx4 v[238:239], off
	v_lshl_add_u64 v[240:241], s[42:43], 0, v[200:201]
	s_mov_b32 m0, s80
	s_nop 0
	global_load_lds_dwordx4 v[240:241], off
	s_barrier
	s_waitcnt lgkmcnt(0)
	v_mfma_f32_16x16x32_bf16 v[94:97], v[50:53], v[118:121], 0
	v_mfma_f32_16x16x32_bf16 v[90:93], v[58:61], v[118:121], 0
	v_mfma_f32_16x16x32_bf16 v[46:49], v[50:53], v[134:137], 0
	v_mfma_f32_16x16x32_bf16 v[42:45], v[58:61], v[134:137], 0
	v_mfma_f32_16x16x32_bf16 v[30:33], v[50:53], v[150:153], 0
	v_mfma_f32_16x16x32_bf16 v[26:29], v[58:61], v[150:153], 0
	v_mfma_f32_16x16x32_bf16 v[14:17], v[50:53], v[170:173], 0
	v_mfma_f32_16x16x32_bf16 v[10:13], v[58:61], v[170:173], 0
	v_mfma_f32_16x16x32_bf16 v[94:97], v[54:57], v[130:133], v[94:97]
	v_mfma_f32_16x16x32_bf16 v[90:93], v[62:65], v[130:133], v[90:93]
	v_mfma_f32_16x16x32_bf16 v[46:49], v[54:57], v[146:149], v[46:49]
	v_mfma_f32_16x16x32_bf16 v[42:45], v[62:65], v[146:149], v[42:45]
	v_mfma_f32_16x16x32_bf16 v[30:33], v[54:57], v[154:157], v[30:33]
	v_mfma_f32_16x16x32_bf16 v[26:29], v[62:65], v[154:157], v[26:29]
	v_mfma_f32_16x16x32_bf16 v[14:17], v[54:57], v[174:177], v[14:17]
	v_mfma_f32_16x16x32_bf16 v[10:13], v[62:65], v[174:177], v[10:13]
	s_barrier
	s_add_u32 s72, s72, s4
	s_addc_u32 s73, s73, 0
	s_add_i32 s93, s94, s78
	v_lshl_add_u64 v[242:243], s[72:73], 0, v[202:203]
	s_mov_b32 m0, s93
	v_lshl_add_u64 v[244:245], s[72:73], 0, v[200:201]
	global_load_lds_dwordx4 v[242:243], off
	s_add_i32 m0, s93, 0x2000
	s_nop 0
	global_load_lds_dwordx4 v[244:245], off
	s_waitcnt vmcnt(6)
	s_barrier
	v_mfma_f32_16x16x32_bf16 v[38:41], v[178:181], v[134:137], 0
	v_mfma_f32_16x16x32_bf16 v[34:37], v[186:189], v[134:137], 0
	v_mfma_f32_16x16x32_bf16 v[22:25], v[178:181], v[150:153], 0
	v_mfma_f32_16x16x32_bf16 v[18:21], v[186:189], v[150:153], 0
	v_mfma_f32_16x16x32_bf16 v[6:9], v[178:181], v[170:173], 0
	v_mfma_f32_16x16x32_bf16 v[2:5], v[186:189], v[170:173], 0
	v_mfma_f32_16x16x32_bf16 v[50:53], v[178:181], v[118:121], 0
	v_mfma_f32_16x16x32_bf16 v[54:57], v[186:189], v[118:121], 0
	v_mfma_f32_16x16x32_bf16 v[38:41], v[182:185], v[146:149], v[38:41]
	v_mfma_f32_16x16x32_bf16 v[34:37], v[190:193], v[146:149], v[34:37]
	v_mfma_f32_16x16x32_bf16 v[22:25], v[182:185], v[154:157], v[22:25]
	v_mfma_f32_16x16x32_bf16 v[18:21], v[190:193], v[154:157], v[18:21]
	v_mfma_f32_16x16x32_bf16 v[6:9], v[182:185], v[174:177], v[6:9]
	v_mfma_f32_16x16x32_bf16 v[2:5], v[190:193], v[174:177], v[2:5]
	v_mfma_f32_16x16x32_bf16 v[50:53], v[182:185], v[130:133], v[50:53]
	v_mfma_f32_16x16x32_bf16 v[54:57], v[190:193], v[130:133], v[54:57]
	s_barrier
	s_add_i32 s72, 0, 0x18000
	v_add_u32_e32 v1, s72, v223
	ds_read_b128 v[58:61], v1
	ds_read_b128 v[62:65], v1 offset:1024
	ds_read_b128 v[82:85], v1 offset:2048
	ds_read_b128 v[86:89], v1 offset:3072
	s_add_u32 s42, s42, s4
	s_addc_u32 s43, s43, 0
	s_mov_b32 m0, s81
	v_lshl_add_u64 v[134:135], s[42:43], 0, v[202:203]
	ds_read_b128 v[118:121], v230 offset:32768
	ds_read_b128 v[130:133], v230 offset:33792
	ds_read_b128 v[146:149], v230 offset:34816
	ds_read_b128 v[154:157], v230 offset:35840
	ds_read_b128 v[170:173], v230 offset:36864
	ds_read_b128 v[174:177], v230 offset:37888
	ds_read_b128 v[178:181], v230 offset:38912
	ds_read_b128 v[182:185], v230 offset:39936
	global_load_lds_dwordx4 v[134:135], off
	v_lshl_add_u64 v[134:135], s[42:43], 0, v[200:201]
	s_mov_b32 m0, s82
	s_nop 0
	global_load_lds_dwordx4 v[134:135], off
	s_waitcnt lgkmcnt(8)
	s_barrier
	s_waitcnt lgkmcnt(0)
	v_mfma_f32_16x16x32_bf16 v[134:137], v[58:61], v[118:121], v[166:169]
	v_mfma_f32_16x16x32_bf16 v[166:169], v[62:65], v[130:133], v[134:137]
	v_mfma_f32_16x16x32_bf16 v[134:137], v[82:85], v[118:121], v[162:165]
	v_mfma_f32_16x16x32_bf16 v[162:165], v[86:89], v[130:133], v[134:137]
	v_mfma_f32_16x16x32_bf16 v[134:137], v[58:61], v[146:149], v[142:145]
	v_mfma_f32_16x16x32_bf16 v[142:145], v[62:65], v[154:157], v[134:137]
	v_mfma_f32_16x16x32_bf16 v[134:137], v[82:85], v[146:149], v[138:141]
	v_mfma_f32_16x16x32_bf16 v[126:129], v[58:61], v[170:173], v[126:129]
	v_mfma_f32_16x16x32_bf16 v[122:125], v[82:85], v[170:173], v[122:125]
	v_mfma_f32_16x16x32_bf16 v[110:113], v[58:61], v[178:181], v[110:113]
	v_mfma_f32_16x16x32_bf16 v[106:109], v[82:85], v[178:181], v[106:109]
	v_mfma_f32_16x16x32_bf16 v[138:141], v[86:89], v[154:157], v[134:137]
	v_mfma_f32_16x16x32_bf16 v[126:129], v[62:65], v[174:177], v[126:129]
	v_mfma_f32_16x16x32_bf16 v[122:125], v[86:89], v[174:177], v[122:125]
	v_mfma_f32_16x16x32_bf16 v[110:113], v[62:65], v[182:185], v[110:113]
	v_mfma_f32_16x16x32_bf16 v[106:109], v[86:89], v[182:185], v[106:109]
	s_barrier
	s_add_i32 s42, 0, 0x1c000
	s_add_i32 s43, s72, s78
	v_add_u32_e32 v1, s42, v223
	v_lshl_add_u64 v[134:135], v[214:215], 0, s[22:23]
	s_mov_b32 m0, s43
	ds_read_b128 v[186:189], v1
	ds_read_b128 v[190:193], v1 offset:1024
	ds_read_b128 v[208:211], v1 offset:2048
	ds_read_b128 v[232:235], v1 offset:3072
	global_load_lds_dwordx4 v[134:135], off
	v_lshl_add_u64 v[134:135], v[236:237], 0, s[22:23]
	s_add_i32 m0, s43, 0x2000
	s_nop 0
	global_load_lds_dwordx4 v[134:135], off
	s_barrier
	s_waitcnt lgkmcnt(0)
	v_mfma_f32_16x16x32_bf16 v[66:69], v[208:211], v[118:121], v[66:69]
	v_mfma_f32_16x16x32_bf16 v[134:137], v[186:189], v[118:121], v[158:161]
	v_mfma_f32_16x16x32_bf16 v[150:153], v[232:235], v[130:133], v[66:69]
	v_mfma_f32_16x16x32_bf16 v[66:69], v[186:189], v[146:149], v[70:73]
	v_mfma_f32_16x16x32_bf16 v[158:161], v[190:193], v[130:133], v[134:137]
	v_mfma_f32_16x16x32_bf16 v[134:137], v[190:193], v[154:157], v[66:69]
	v_mfma_f32_16x16x32_bf16 v[66:69], v[208:211], v[146:149], v[74:77]
	v_mfma_f32_16x16x32_bf16 v[130:133], v[232:235], v[154:157], v[66:69]
	v_mfma_f32_16x16x32_bf16 v[66:69], v[186:189], v[170:173], v[78:81]
	v_mfma_f32_16x16x32_bf16 v[118:121], v[190:193], v[174:177], v[66:69]
	v_mfma_f32_16x16x32_bf16 v[66:69], v[208:211], v[170:173], v[114:117]
	v_mfma_f32_16x16x32_bf16 v[114:117], v[232:235], v[174:177], v[66:69]
	v_mfma_f32_16x16x32_bf16 v[66:69], v[186:189], v[178:181], v[102:105]
	v_mfma_f32_16x16x32_bf16 v[102:105], v[190:193], v[182:185], v[66:69]
	v_mfma_f32_16x16x32_bf16 v[66:69], v[208:211], v[178:181], v[98:101]
	v_mfma_f32_16x16x32_bf16 v[98:101], v[232:235], v[182:185], v[66:69]
	s_barrier
	s_mov_b32 m0, s86
	v_lshl_add_u64 v[178:179], v[238:239], 0, s[22:23]
	s_nop 2
	ds_read_b128 v[66:69], v230 offset:49152
	ds_read_b128 v[70:73], v230 offset:50176
	ds_read_b128 v[74:77], v230 offset:51200
	ds_read_b128 v[78:81], v230 offset:52224
	ds_read_b128 v[146:149], v230 offset:53248
	ds_read_b128 v[154:157], v230 offset:54272
	ds_read_b128 v[170:173], v230 offset:55296
	ds_read_b128 v[174:177], v230 offset:56320
	global_load_lds_dwordx4 v[178:179], off
	v_lshl_add_u64 v[178:179], v[240:241], 0, s[22:23]
	s_mov_b32 m0, s87
	s_nop 0
	global_load_lds_dwordx4 v[178:179], off
	s_barrier
	s_waitcnt lgkmcnt(0)
	v_mfma_f32_16x16x32_bf16 v[94:97], v[58:61], v[66:69], v[94:97]
	v_mfma_f32_16x16x32_bf16 v[90:93], v[82:85], v[66:69], v[90:93]
	v_mfma_f32_16x16x32_bf16 v[46:49], v[58:61], v[74:77], v[46:49]
	v_mfma_f32_16x16x32_bf16 v[42:45], v[82:85], v[74:77], v[42:45]
	v_mfma_f32_16x16x32_bf16 v[30:33], v[58:61], v[146:149], v[30:33]
	v_mfma_f32_16x16x32_bf16 v[26:29], v[82:85], v[146:149], v[26:29]
	v_mfma_f32_16x16x32_bf16 v[14:17], v[58:61], v[170:173], v[14:17]
	v_mfma_f32_16x16x32_bf16 v[10:13], v[82:85], v[170:173], v[10:13]
	v_mfma_f32_16x16x32_bf16 v[94:97], v[62:65], v[70:73], v[94:97]
	v_mfma_f32_16x16x32_bf16 v[90:93], v[86:89], v[70:73], v[90:93]
	v_mfma_f32_16x16x32_bf16 v[46:49], v[62:65], v[78:81], v[46:49]
	v_mfma_f32_16x16x32_bf16 v[42:45], v[86:89], v[78:81], v[42:45]
	v_mfma_f32_16x16x32_bf16 v[30:33], v[62:65], v[154:157], v[30:33]
	v_mfma_f32_16x16x32_bf16 v[26:29], v[86:89], v[154:157], v[26:29]
	v_mfma_f32_16x16x32_bf16 v[14:17], v[62:65], v[174:177], v[14:17]
	v_mfma_f32_16x16x32_bf16 v[10:13], v[86:89], v[174:177], v[10:13]
	s_barrier
	s_add_i32 s42, s42, s78
	v_lshl_add_u64 v[58:59], v[242:243], 0, s[22:23]
	s_mov_b32 m0, s42
	s_nop 0
	global_load_lds_dwordx4 v[58:59], off
	v_lshl_add_u64 v[58:59], v[244:245], 0, s[22:23]
	s_add_i32 m0, s42, 0x2000
	s_nop 0
	global_load_lds_dwordx4 v[58:59], off
	s_add_u32 s27, s27, 0x100
	s_addc_u32 s91, s91, 0
	s_add_u32 s36, s36, 0x100
	s_addc_u32 s37, s37, 0
	s_cmp_ge_u32 s92, s84
	s_mov_b32 s42, s92
	s_waitcnt vmcnt(6)
	s_barrier
	v_mfma_f32_16x16x32_bf16 v[50:53], v[186:189], v[66:69], v[50:53]
	v_mfma_f32_16x16x32_bf16 v[86:89], v[190:193], v[70:73], v[50:53]
	v_mfma_f32_16x16x32_bf16 v[50:53], v[208:211], v[66:69], v[54:57]
	v_mfma_f32_16x16x32_bf16 v[38:41], v[186:189], v[74:77], v[38:41]
	v_mfma_f32_16x16x32_bf16 v[34:37], v[208:211], v[74:77], v[34:37]
	v_mfma_f32_16x16x32_bf16 v[22:25], v[186:189], v[146:149], v[22:25]
	v_mfma_f32_16x16x32_bf16 v[18:21], v[208:211], v[146:149], v[18:21]
	v_mfma_f32_16x16x32_bf16 v[6:9], v[186:189], v[170:173], v[6:9]
	v_mfma_f32_16x16x32_bf16 v[2:5], v[208:211], v[170:173], v[2:5]
	v_mfma_f32_16x16x32_bf16 v[82:85], v[232:235], v[70:73], v[50:53]
	v_mfma_f32_16x16x32_bf16 v[38:41], v[190:193], v[78:81], v[38:41]
	v_mfma_f32_16x16x32_bf16 v[34:37], v[232:235], v[78:81], v[34:37]
	v_mfma_f32_16x16x32_bf16 v[22:25], v[190:193], v[154:157], v[22:25]
	v_mfma_f32_16x16x32_bf16 v[18:21], v[232:235], v[154:157], v[18:21]
	v_mfma_f32_16x16x32_bf16 v[6:9], v[190:193], v[174:177], v[6:9]
	v_mfma_f32_16x16x32_bf16 v[2:5], v[232:235], v[174:177], v[2:5]
	s_barrier
.LBB0_1179:
	s_add_i32 s92, s42, 2
	s_add_u32 s72, s36, 0x80
	s_addc_u32 s43, s37, 0
	s_add_i32 s93, 0, 0x10000
	v_add_u32_e32 v1, s93, v223
	ds_read_b128 v[50:53], v1
	ds_read_b128 v[54:57], v1 offset:1024
	ds_read_b128 v[58:61], v1 offset:2048
	ds_read_b128 v[62:65], v1 offset:3072
	s_cmp_eq_u32 s88, s42
	s_cselect_b32 s42, s66, s72
	s_cselect_b32 s43, s67, s43
	s_cselect_b32 s73, s71, s91
	s_cselect_b32 s72, s70, s27
	v_lshl_add_u64 v[178:179], s[36:37], 0, v[206:207]
	s_add_i32 m0, s79, 0xc000
	ds_read_b128 v[66:69], v230
	ds_read_b128 v[70:73], v230 offset:1024
	ds_read_b128 v[74:77], v230 offset:2048
	ds_read_b128 v[78:81], v230 offset:3072
	ds_read_b128 v[146:149], v230 offset:4096
	ds_read_b128 v[154:157], v230 offset:5120
	ds_read_b128 v[170:173], v230 offset:6144
	ds_read_b128 v[174:177], v230 offset:7168
	global_load_lds_dwordx4 v[178:179], off
	v_lshl_add_u64 v[178:179], s[36:37], 0, v[204:205]
	s_add_i32 m0, s79, 0xe000
	s_nop 0
	global_load_lds_dwordx4 v[178:179], off
	s_waitcnt lgkmcnt(8)
	s_barrier
	s_waitcnt lgkmcnt(0)
	v_mfma_f32_16x16x32_bf16 v[166:169], v[50:53], v[66:69], v[166:169]
	v_mfma_f32_16x16x32_bf16 v[162:165], v[58:61], v[66:69], v[162:165]
	v_mfma_f32_16x16x32_bf16 v[142:145], v[50:53], v[74:77], v[142:145]
	v_mfma_f32_16x16x32_bf16 v[138:141], v[58:61], v[74:77], v[138:141]
	v_mfma_f32_16x16x32_bf16 v[126:129], v[50:53], v[146:149], v[126:129]
	v_mfma_f32_16x16x32_bf16 v[122:125], v[58:61], v[146:149], v[122:125]
	v_mfma_f32_16x16x32_bf16 v[110:113], v[50:53], v[170:173], v[110:113]
	v_mfma_f32_16x16x32_bf16 v[106:109], v[58:61], v[170:173], v[106:109]
	v_mfma_f32_16x16x32_bf16 v[166:169], v[54:57], v[70:73], v[166:169]
	v_mfma_f32_16x16x32_bf16 v[162:165], v[62:65], v[70:73], v[162:165]
	v_mfma_f32_16x16x32_bf16 v[142:145], v[54:57], v[78:81], v[142:145]
	v_mfma_f32_16x16x32_bf16 v[138:141], v[62:65], v[78:81], v[138:141]
	v_mfma_f32_16x16x32_bf16 v[126:129], v[54:57], v[154:157], v[126:129]
	v_mfma_f32_16x16x32_bf16 v[122:125], v[62:65], v[154:157], v[122:125]
	v_mfma_f32_16x16x32_bf16 v[110:113], v[54:57], v[174:177], v[110:113]
	v_mfma_f32_16x16x32_bf16 v[106:109], v[62:65], v[174:177], v[106:109]
	s_barrier
	s_add_i32 s94, 0, 0x14000
	s_add_i32 s93, s93, s78
	v_add_u32_e32 v1, s94, v223
	v_lshl_add_u64 v[214:215], s[72:73], 0, v[202:203]
	s_mov_b32 m0, s93
	ds_read_b128 v[178:181], v1
	ds_read_b128 v[182:185], v1 offset:1024
	ds_read_b128 v[186:189], v1 offset:2048
	ds_read_b128 v[190:193], v1 offset:3072
	global_load_lds_dwordx4 v[214:215], off
	v_lshl_add_u64 v[236:237], s[72:73], 0, v[200:201]
	s_add_i32 m0, s93, 0x2000
	s_nop 0
	global_load_lds_dwordx4 v[236:237], off
	s_barrier
	s_waitcnt lgkmcnt(0)
	v_mfma_f32_16x16x32_bf16 v[158:161], v[178:181], v[66:69], v[158:161]
	v_mfma_f32_16x16x32_bf16 v[66:69], v[186:189], v[66:69], v[150:153]
	v_mfma_f32_16x16x32_bf16 v[158:161], v[182:185], v[70:73], v[158:161]
	v_mfma_f32_16x16x32_bf16 v[66:69], v[190:193], v[70:73], v[66:69]
	v_mfma_f32_16x16x32_bf16 v[70:73], v[178:181], v[74:77], v[134:137]
	v_mfma_f32_16x16x32_bf16 v[74:77], v[186:189], v[74:77], v[130:133]
	v_mfma_f32_16x16x32_bf16 v[114:117], v[186:189], v[146:149], v[114:117]
	v_mfma_f32_16x16x32_bf16 v[102:105], v[178:181], v[170:173], v[102:105]
	v_mfma_f32_16x16x32_bf16 v[98:101], v[186:189], v[170:173], v[98:101]
	v_mfma_f32_16x16x32_bf16 v[70:73], v[182:185], v[78:81], v[70:73]
	v_mfma_f32_16x16x32_bf16 v[74:77], v[190:193], v[78:81], v[74:77]
	v_mfma_f32_16x16x32_bf16 v[78:81], v[178:181], v[146:149], v[118:121]
	v_mfma_f32_16x16x32_bf16 v[114:117], v[190:193], v[154:157], v[114:117]
	v_mfma_f32_16x16x32_bf16 v[102:105], v[182:185], v[174:177], v[102:105]
	v_mfma_f32_16x16x32_bf16 v[98:101], v[190:193], v[174:177], v[98:101]
	v_mfma_f32_16x16x32_bf16 v[78:81], v[182:185], v[154:157], v[78:81]
	s_barrier
	s_mov_b32 m0, s79
	v_lshl_add_u64 v[238:239], s[42:43], 0, v[202:203]
	ds_read_b128 v[118:121], v230 offset:16384
	ds_read_b128 v[130:133], v230 offset:17408
	ds_read_b128 v[134:137], v230 offset:18432
	ds_read_b128 v[146:149], v230 offset:19456
	ds_read_b128 v[150:153], v230 offset:20480
	ds_read_b128 v[154:157], v230 offset:21504
	ds_read_b128 v[170:173], v230 offset:22528
	ds_read_b128 v[174:177], v230 offset:23552
	global_load_lds_dwordx4 v[238:239], off
	v_lshl_add_u64 v[240:241], s[42:43], 0, v[200:201]
	s_mov_b32 m0, s80
	s_nop 0
	global_load_lds_dwordx4 v[240:241], off
	s_barrier
	s_waitcnt lgkmcnt(0)
	v_mfma_f32_16x16x32_bf16 v[94:97], v[50:53], v[118:121], v[94:97]
	v_mfma_f32_16x16x32_bf16 v[90:93], v[58:61], v[118:121], v[90:93]
	v_mfma_f32_16x16x32_bf16 v[46:49], v[50:53], v[134:137], v[46:49]
	v_mfma_f32_16x16x32_bf16 v[42:45], v[58:61], v[134:137], v[42:45]
	v_mfma_f32_16x16x32_bf16 v[30:33], v[50:53], v[150:153], v[30:33]
	v_mfma_f32_16x16x32_bf16 v[26:29], v[58:61], v[150:153], v[26:29]
	v_mfma_f32_16x16x32_bf16 v[14:17], v[50:53], v[170:173], v[14:17]
	v_mfma_f32_16x16x32_bf16 v[10:13], v[58:61], v[170:173], v[10:13]
	v_mfma_f32_16x16x32_bf16 v[94:97], v[54:57], v[130:133], v[94:97]
	v_mfma_f32_16x16x32_bf16 v[90:93], v[62:65], v[130:133], v[90:93]
	v_mfma_f32_16x16x32_bf16 v[46:49], v[54:57], v[146:149], v[46:49]
	v_mfma_f32_16x16x32_bf16 v[42:45], v[62:65], v[146:149], v[42:45]
	v_mfma_f32_16x16x32_bf16 v[30:33], v[54:57], v[154:157], v[30:33]
	v_mfma_f32_16x16x32_bf16 v[26:29], v[62:65], v[154:157], v[26:29]
	v_mfma_f32_16x16x32_bf16 v[14:17], v[54:57], v[174:177], v[14:17]
	v_mfma_f32_16x16x32_bf16 v[10:13], v[62:65], v[174:177], v[10:13]
	s_barrier
	s_add_u32 s72, s72, s4
	s_addc_u32 s73, s73, 0
	s_add_i32 s93, s94, s78
	v_lshl_add_u64 v[242:243], s[72:73], 0, v[202:203]
	s_mov_b32 m0, s93
	v_lshl_add_u64 v[244:245], s[72:73], 0, v[200:201]
	global_load_lds_dwordx4 v[242:243], off
	s_add_i32 m0, s93, 0x2000
	s_nop 0
	global_load_lds_dwordx4 v[244:245], off
	s_waitcnt vmcnt(6)
	s_barrier
	v_mfma_f32_16x16x32_bf16 v[38:41], v[178:181], v[134:137], v[38:41]
	v_mfma_f32_16x16x32_bf16 v[34:37], v[186:189], v[134:137], v[34:37]
	v_mfma_f32_16x16x32_bf16 v[22:25], v[178:181], v[150:153], v[22:25]
	v_mfma_f32_16x16x32_bf16 v[18:21], v[186:189], v[150:153], v[18:21]
	v_mfma_f32_16x16x32_bf16 v[6:9], v[178:181], v[170:173], v[6:9]
	v_mfma_f32_16x16x32_bf16 v[2:5], v[186:189], v[170:173], v[2:5]
	v_mfma_f32_16x16x32_bf16 v[50:53], v[178:181], v[118:121], v[86:89]
	v_mfma_f32_16x16x32_bf16 v[54:57], v[186:189], v[118:121], v[82:85]
	v_mfma_f32_16x16x32_bf16 v[38:41], v[182:185], v[146:149], v[38:41]
	v_mfma_f32_16x16x32_bf16 v[34:37], v[190:193], v[146:149], v[34:37]
	v_mfma_f32_16x16x32_bf16 v[22:25], v[182:185], v[154:157], v[22:25]
	v_mfma_f32_16x16x32_bf16 v[18:21], v[190:193], v[154:157], v[18:21]
	v_mfma_f32_16x16x32_bf16 v[6:9], v[182:185], v[174:177], v[6:9]
	v_mfma_f32_16x16x32_bf16 v[2:5], v[190:193], v[174:177], v[2:5]
	v_mfma_f32_16x16x32_bf16 v[50:53], v[182:185], v[130:133], v[50:53]
	v_mfma_f32_16x16x32_bf16 v[54:57], v[190:193], v[130:133], v[54:57]
	s_barrier
	s_add_i32 s72, 0, 0x18000
	v_add_u32_e32 v1, s72, v223
	ds_read_b128 v[58:61], v1
	ds_read_b128 v[62:65], v1 offset:1024
	ds_read_b128 v[82:85], v1 offset:2048
	ds_read_b128 v[86:89], v1 offset:3072
	s_add_u32 s42, s42, s4
	s_addc_u32 s43, s43, 0
	s_mov_b32 m0, s81
	v_lshl_add_u64 v[134:135], s[42:43], 0, v[202:203]
	ds_read_b128 v[118:121], v230 offset:32768
	ds_read_b128 v[130:133], v230 offset:33792
	ds_read_b128 v[146:149], v230 offset:34816
	ds_read_b128 v[154:157], v230 offset:35840
	ds_read_b128 v[170:173], v230 offset:36864
	ds_read_b128 v[174:177], v230 offset:37888
	ds_read_b128 v[178:181], v230 offset:38912
	ds_read_b128 v[182:185], v230 offset:39936
	global_load_lds_dwordx4 v[134:135], off
	v_lshl_add_u64 v[134:135], s[42:43], 0, v[200:201]
	s_mov_b32 m0, s82
	s_nop 0
	global_load_lds_dwordx4 v[134:135], off
	s_waitcnt lgkmcnt(8)
	s_barrier
	s_waitcnt lgkmcnt(0)
	v_mfma_f32_16x16x32_bf16 v[134:137], v[58:61], v[118:121], v[166:169]
	v_mfma_f32_16x16x32_bf16 v[166:169], v[62:65], v[130:133], v[134:137]
	v_mfma_f32_16x16x32_bf16 v[134:137], v[82:85], v[118:121], v[162:165]
	v_mfma_f32_16x16x32_bf16 v[162:165], v[86:89], v[130:133], v[134:137]
	v_mfma_f32_16x16x32_bf16 v[134:137], v[58:61], v[146:149], v[142:145]
	v_mfma_f32_16x16x32_bf16 v[142:145], v[62:65], v[154:157], v[134:137]
	v_mfma_f32_16x16x32_bf16 v[134:137], v[82:85], v[146:149], v[138:141]
	v_mfma_f32_16x16x32_bf16 v[126:129], v[58:61], v[170:173], v[126:129]
	v_mfma_f32_16x16x32_bf16 v[122:125], v[82:85], v[170:173], v[122:125]
	v_mfma_f32_16x16x32_bf16 v[110:113], v[58:61], v[178:181], v[110:113]
	v_mfma_f32_16x16x32_bf16 v[106:109], v[82:85], v[178:181], v[106:109]
	v_mfma_f32_16x16x32_bf16 v[138:141], v[86:89], v[154:157], v[134:137]
	v_mfma_f32_16x16x32_bf16 v[126:129], v[62:65], v[174:177], v[126:129]
	v_mfma_f32_16x16x32_bf16 v[122:125], v[86:89], v[174:177], v[122:125]
	v_mfma_f32_16x16x32_bf16 v[110:113], v[62:65], v[182:185], v[110:113]
	v_mfma_f32_16x16x32_bf16 v[106:109], v[86:89], v[182:185], v[106:109]
	s_barrier
	s_add_i32 s42, 0, 0x1c000
	s_add_i32 s43, s72, s78
	v_add_u32_e32 v1, s42, v223
	v_lshl_add_u64 v[134:135], v[214:215], 0, s[22:23]
	s_mov_b32 m0, s43
	ds_read_b128 v[186:189], v1
	ds_read_b128 v[190:193], v1 offset:1024
	ds_read_b128 v[208:211], v1 offset:2048
	ds_read_b128 v[232:235], v1 offset:3072
	global_load_lds_dwordx4 v[134:135], off
	v_lshl_add_u64 v[134:135], v[236:237], 0, s[22:23]
	s_add_i32 m0, s43, 0x2000
	s_nop 0
	global_load_lds_dwordx4 v[134:135], off
	s_barrier
	s_waitcnt lgkmcnt(0)
	v_mfma_f32_16x16x32_bf16 v[66:69], v[208:211], v[118:121], v[66:69]
	v_mfma_f32_16x16x32_bf16 v[134:137], v[186:189], v[118:121], v[158:161]
	v_mfma_f32_16x16x32_bf16 v[150:153], v[232:235], v[130:133], v[66:69]
	v_mfma_f32_16x16x32_bf16 v[66:69], v[186:189], v[146:149], v[70:73]
	v_mfma_f32_16x16x32_bf16 v[158:161], v[190:193], v[130:133], v[134:137]
	v_mfma_f32_16x16x32_bf16 v[134:137], v[190:193], v[154:157], v[66:69]
	v_mfma_f32_16x16x32_bf16 v[66:69], v[208:211], v[146:149], v[74:77]
	v_mfma_f32_16x16x32_bf16 v[130:133], v[232:235], v[154:157], v[66:69]
	v_mfma_f32_16x16x32_bf16 v[66:69], v[186:189], v[170:173], v[78:81]
	v_mfma_f32_16x16x32_bf16 v[118:121], v[190:193], v[174:177], v[66:69]
	v_mfma_f32_16x16x32_bf16 v[66:69], v[208:211], v[170:173], v[114:117]
	v_mfma_f32_16x16x32_bf16 v[114:117], v[232:235], v[174:177], v[66:69]
	v_mfma_f32_16x16x32_bf16 v[66:69], v[186:189], v[178:181], v[102:105]
	v_mfma_f32_16x16x32_bf16 v[102:105], v[190:193], v[182:185], v[66:69]
	v_mfma_f32_16x16x32_bf16 v[66:69], v[208:211], v[178:181], v[98:101]
	v_mfma_f32_16x16x32_bf16 v[98:101], v[232:235], v[182:185], v[66:69]
	s_barrier
	s_mov_b32 m0, s86
	v_lshl_add_u64 v[178:179], v[238:239], 0, s[22:23]
	s_nop 2
	ds_read_b128 v[66:69], v230 offset:49152
	ds_read_b128 v[70:73], v230 offset:50176
	ds_read_b128 v[74:77], v230 offset:51200
	ds_read_b128 v[78:81], v230 offset:52224
	ds_read_b128 v[146:149], v230 offset:53248
	ds_read_b128 v[154:157], v230 offset:54272
	ds_read_b128 v[170:173], v230 offset:55296
	ds_read_b128 v[174:177], v230 offset:56320
	global_load_lds_dwordx4 v[178:179], off
	v_lshl_add_u64 v[178:179], v[240:241], 0, s[22:23]
	s_mov_b32 m0, s87
	s_nop 0
	global_load_lds_dwordx4 v[178:179], off
	s_barrier
	s_waitcnt lgkmcnt(0)
	v_mfma_f32_16x16x32_bf16 v[94:97], v[58:61], v[66:69], v[94:97]
	v_mfma_f32_16x16x32_bf16 v[90:93], v[82:85], v[66:69], v[90:93]
	v_mfma_f32_16x16x32_bf16 v[46:49], v[58:61], v[74:77], v[46:49]
	v_mfma_f32_16x16x32_bf16 v[42:45], v[82:85], v[74:77], v[42:45]
	v_mfma_f32_16x16x32_bf16 v[30:33], v[58:61], v[146:149], v[30:33]
	v_mfma_f32_16x16x32_bf16 v[26:29], v[82:85], v[146:149], v[26:29]
	v_mfma_f32_16x16x32_bf16 v[14:17], v[58:61], v[170:173], v[14:17]
	v_mfma_f32_16x16x32_bf16 v[10:13], v[82:85], v[170:173], v[10:13]
	v_mfma_f32_16x16x32_bf16 v[94:97], v[62:65], v[70:73], v[94:97]
	v_mfma_f32_16x16x32_bf16 v[90:93], v[86:89], v[70:73], v[90:93]
	v_mfma_f32_16x16x32_bf16 v[46:49], v[62:65], v[78:81], v[46:49]
	v_mfma_f32_16x16x32_bf16 v[42:45], v[86:89], v[78:81], v[42:45]
	v_mfma_f32_16x16x32_bf16 v[30:33], v[62:65], v[154:157], v[30:33]
	v_mfma_f32_16x16x32_bf16 v[26:29], v[86:89], v[154:157], v[26:29]
	v_mfma_f32_16x16x32_bf16 v[14:17], v[62:65], v[174:177], v[14:17]
	v_mfma_f32_16x16x32_bf16 v[10:13], v[86:89], v[174:177], v[10:13]
	s_barrier
	s_add_i32 s42, s42, s78
	v_lshl_add_u64 v[58:59], v[242:243], 0, s[22:23]
	s_mov_b32 m0, s42
	s_nop 0
	global_load_lds_dwordx4 v[58:59], off
	v_lshl_add_u64 v[58:59], v[244:245], 0, s[22:23]
	s_add_i32 m0, s42, 0x2000
	s_nop 0
	global_load_lds_dwordx4 v[58:59], off
	s_add_u32 s27, s27, 0x100
	s_addc_u32 s91, s91, 0
	s_add_u32 s36, s36, 0x100
	s_addc_u32 s37, s37, 0
	s_cmp_ge_u32 s92, s84
	s_mov_b32 s42, s92
	s_waitcnt vmcnt(6)
	s_barrier
	v_mfma_f32_16x16x32_bf16 v[50:53], v[186:189], v[66:69], v[50:53]
	v_mfma_f32_16x16x32_bf16 v[86:89], v[190:193], v[70:73], v[50:53]
	v_mfma_f32_16x16x32_bf16 v[50:53], v[208:211], v[66:69], v[54:57]
	v_mfma_f32_16x16x32_bf16 v[38:41], v[186:189], v[74:77], v[38:41]
	v_mfma_f32_16x16x32_bf16 v[34:37], v[208:211], v[74:77], v[34:37]
	v_mfma_f32_16x16x32_bf16 v[22:25], v[186:189], v[146:149], v[22:25]
	v_mfma_f32_16x16x32_bf16 v[18:21], v[208:211], v[146:149], v[18:21]
	v_mfma_f32_16x16x32_bf16 v[6:9], v[186:189], v[170:173], v[6:9]
	v_mfma_f32_16x16x32_bf16 v[2:5], v[208:211], v[170:173], v[2:5]
	v_mfma_f32_16x16x32_bf16 v[82:85], v[232:235], v[70:73], v[50:53]
	v_mfma_f32_16x16x32_bf16 v[38:41], v[190:193], v[78:81], v[38:41]
	v_mfma_f32_16x16x32_bf16 v[34:37], v[232:235], v[78:81], v[34:37]
	v_mfma_f32_16x16x32_bf16 v[22:25], v[190:193], v[154:157], v[22:25]
	v_mfma_f32_16x16x32_bf16 v[18:21], v[232:235], v[154:157], v[18:21]
	v_mfma_f32_16x16x32_bf16 v[6:9], v[190:193], v[174:177], v[6:9]
	v_mfma_f32_16x16x32_bf16 v[2:5], v[232:235], v[174:177], v[2:5]
	s_barrier
	s_cbranch_scc0 .LBB0_1179
	s_setprio 0
	s_lshl_b32 s3, s3, 8
	s_add_i32 s27, s3, s85
	v_lshl_or_b32 v210, s38, 8, v224
	v_or_b32_e32 v146, s27, v221
	v_ashrrev_i32_e32 v147, 31, v146
	v_ashrrev_i32_e32 v211, 31, v210
	v_lshlrev_b64 v[50:51], 2, v[210:211]
	v_lshl_add_u64 v[208:209], v[210:211], 1, s[48:49]
	v_lshlrev_b64 v[148:149], 11, v[146:147]
	v_lshl_add_u64 v[52:53], s[52:53], 0, v[50:51]
	v_lshl_add_u64 v[54:55], s[54:55], 0, v[50:51]
	v_lshl_add_u64 v[148:149], v[208:209], 0, v[148:149]
	global_load_dwordx4 v[74:77], v[52:53], off
	global_load_dwordx4 v[66:69], v[52:53], off offset:16
	global_load_dwordx4 v[78:81], v[54:55], off
	global_load_dwordx4 v[70:73], v[54:55], off offset:16
	global_load_dwordx4 v[58:61], v[52:53], off offset:512
	s_nop 0
	global_load_dwordx4 v[50:53], v[52:53], off offset:528
	s_nop 0
	global_load_dwordx4 v[62:65], v[54:55], off offset:512
	s_nop 0
	global_load_dwordx4 v[54:57], v[54:55], off offset:528
	global_load_dwordx4 v[190:193], v[148:149], off
	global_load_dwordx4 v[186:189], v[148:149], off offset:256
	v_or_b32_e32 v148, 16, v146
	v_ashrrev_i32_e32 v149, 31, v148
	v_lshlrev_b64 v[148:149], 11, v[148:149]
	v_lshl_add_u64 v[148:149], v[208:209], 0, v[148:149]
	global_load_dwordx4 v[182:185], v[148:149], off
	global_load_dwordx4 v[178:181], v[148:149], off offset:256
	v_or_b32_e32 v148, 32, v146
	v_or_b32_e32 v146, 48, v146
	v_ashrrev_i32_e32 v149, 31, v148
	v_ashrrev_i32_e32 v147, 31, v146
	v_lshlrev_b64 v[148:149], 11, v[148:149]
	v_lshlrev_b64 v[146:147], 11, v[146:147]
	v_mov_b32_e32 v1, v222
	v_lshl_add_u64 v[148:149], v[208:209], 0, v[148:149]
	v_lshl_add_u64 v[146:147], v[208:209], 0, v[146:147]
	global_load_dwordx4 v[174:177], v[148:149], off
	global_load_dwordx4 v[170:173], v[148:149], off offset:256
	global_load_dwordx4 v[154:157], v[146:147], off
	s_nop 0
	global_load_dwordx4 v[146:149], v[146:147], off offset:256
	v_cndmask_b32_e64 v211, 0, 1, s[56:57]
	v_cmp_ne_u32_e64 s[42:43], 1, v211
	s_andn2_b64 vcc, exec, s[56:57]
	v_lshl_add_u32 v231, v1, 3, s33
	s_cbranch_vccnz .LBB0_1182
	ds_read_b64 v[214:215], v231
	s_waitcnt lgkmcnt(0)
	v_mov_b32_e32 v212, v215
	s_branch .LBB0_1183
